# E12 + MFMA issue order changed so the two k-halves of each accumulator issue back to back (dependent accumulate chain, all 8 K-loops); numerics bit-identical
# speedup vs baseline: 1.0229x; 1.0218x over previous
; #define PG8_STAGE(bufoff, gbase, voff) do { _Pragma("unroll") for (int _i = 0; _i < 2; ++_i) \
;         __builtin_amdgcn_global_load_lds((const unsigned*)((const char*)(gbase) + (voff)[_i]), (LAS unsigned*)(lds + (bufoff) + ldsw + _i * 8192), 16, 0, 0); } while (0)
; #define PG8_LDA(dst, b, h) do { _Pragma("unroll") for (int m = 0; m < 4; ++m) _Pragma("unroll") for (int k = 0; k < 2; ++k) dst[m][k] = *(const LAS bf16x8*)(pA + PG8_SA(b, h) + m * 2048 + k * 1024); } while (0)
; #define PG8_LDB(dst, b, h) do { _Pragma("unroll") for (int n = 0; n < 2; ++n) _Pragma("unroll") for (int k = 0; k < 2; ++k) dst[n][k] = *(const LAS bf16x8*)(pB + (PG8_SB(b, h) - 4 * HTB) + n * 2048 + k * 1024); } while (0)
; #define PG8_MMA(ai, bj, At, Bt) do { __builtin_amdgcn_s_setprio(1); _Pragma("unroll") for (int m = 0; m < 4; ++m) _Pragma("unroll") for (int n = 0; n < 2; ++n) _Pragma("unroll") for (int k = 0; k < 2; ++k) \
;         acc[ai][bj][m][n] = __builtin_amdgcn_mfma_f32_16x16x32_bf16(Bt[n][k], At[m][k], acc[ai][bj][m][n], 0, 0, 0); __builtin_amdgcn_s_setprio(0); } while (0)
; #define PG8_WAIT_V(n) asm volatile("s_waitcnt vmcnt(" #n ")" ::: "memory")
; #define PG8_WAIT_L(n) asm volatile("s_waitcnt lgkmcnt(" #n ")" ::: "memory")
; #define PG8_BAR __builtin_amdgcn_s_barrier()
; #define PG8_SCHED __builtin_amdgcn_sched_barrier(0)
; template <class Desc, class Epi, bool ALIGN_EPI>
; __device__ __forceinline__ void gemm_phase(LAS unsigned char* lds, const Desc& D, const Epi& E, int G, int c) {
;     ...
;             const char* a1 = cA + (size_t)(t + 1) * kstep;
;             const char* a2 = last ? nA : cA + (size_t)(t + 2) * kstep; const char* b2 = last ? nB : cB + (size_t)(t + 2) * kstep;
;             const char* a3 = a2 + kstep; const char* b3 = b2 + kstep;
;             PG8_LDB(B0, 0, 0); PG8_LDB(B1, 0, 1); PG8_SCHED; PG8_LDA(At, 0, 0); PG8_STAGE(PG8_SA(1, 1), a1 + hstepA, voffA);
;             PG8_WAIT_V(8); PG8_WAIT_L(0); PG8_BAR; PG8_MMA(0, 0, At, B0); PG8_MMA(0, 1, At, B1); PG8_BAR; PG8_SCHED;
;             PG8_LDA(At, 0, 1); PG8_STAGE(PG8_SB(0, 0), b2, voffB); PG8_STAGE(PG8_SB(0, 1), b2 + hstepB, voffB); PG8_STAGE(PG8_SA(0, 0), a2, voffA);
;             PG8_WAIT_V(8); PG8_WAIT_L(0); PG8_BAR; PG8_MMA(1, 0, At, B0); PG8_MMA(1, 1, At, B1); PG8_BAR; PG8_SCHED;
.LBB0_172:
	s_or_b32 s14, s17, 1
	s_lshl_b64 s[26:27], s[14:15], 7
	s_add_i32 s14, s17, 2
	s_lshl_b64 s[40:41], s[14:15], 7
	s_add_u32 s17, s12, s40
	ds_read_b128 v[134:137], v169
	ds_read_b128 v[138:141], v169 offset:1024
	ds_read_b128 v[142:145], v169 offset:2048
	ds_read_b128 v[146:149], v169 offset:3072
	ds_read_b128 v[160:163], v169 offset:16384
	ds_read_b128 v[164:167], v169 offset:17408
	ds_read_b128 v[174:177], v169 offset:18432
	ds_read_b128 v[178:181], v169 offset:19456
	s_addc_u32 s21, s13, s41
	s_and_b64 s[38:39], s[30:31], exec
	s_cselect_b32 s39, s61, s21
	s_cselect_b32 s38, s60, s17
	s_add_u32 s17, s18, s40
	s_addc_u32 s21, s19, s41
	s_and_b64 s[30:31], s[30:31], exec
	s_cselect_b32 s31, s63, s21
	s_cselect_b32 s30, s62, s17
	s_add_u32 s17, s12, s26
	s_addc_u32 s21, s13, s27
	s_add_u32 s26, s17, 0x100000
	s_addc_u32 s27, s21, 0
	s_mov_b32 m0, s50
	v_lshl_add_u64 v[150:151], s[26:27], 0, v[152:153]
	ds_read_b128 v[182:185], v168
	ds_read_b128 v[186:189], v168 offset:1024
	ds_read_b128 v[190:193], v168 offset:2048
	ds_read_b128 v[194:197], v168 offset:3072
	ds_read_b128 v[198:201], v168 offset:4096
	ds_read_b128 v[202:205], v168 offset:5120
	ds_read_b128 v[206:209], v168 offset:6144
	ds_read_b128 v[210:213], v168 offset:7168
	global_load_lds_dwordx4 v[150:151], off
	v_lshl_add_u64 v[150:151], s[26:27], 0, v[156:157]
	s_mov_b32 m0, s51
	s_nop 0
	global_load_lds_dwordx4 v[150:151], off
	s_waitcnt vmcnt(8)
	s_waitcnt lgkmcnt(0)
	s_barrier
	v_mfma_f32_16x16x32_bf16 v[128:131], v[134:137], v[182:185], v[128:131]
	v_mfma_f32_16x16x32_bf16 v[128:131], v[138:141], v[186:189], v[128:131]
	v_mfma_f32_16x16x32_bf16 v[124:127], v[142:145], v[182:185], v[124:127]
	v_mfma_f32_16x16x32_bf16 v[124:127], v[146:149], v[186:189], v[124:127]
	v_mfma_f32_16x16x32_bf16 v[120:123], v[134:137], v[190:193], v[120:123]
	v_mfma_f32_16x16x32_bf16 v[120:123], v[138:141], v[194:197], v[120:123]
	v_mfma_f32_16x16x32_bf16 v[116:119], v[142:145], v[190:193], v[116:119]
	v_mfma_f32_16x16x32_bf16 v[116:119], v[146:149], v[194:197], v[116:119]
	v_mfma_f32_16x16x32_bf16 v[112:115], v[134:137], v[198:201], v[112:115]
	v_mfma_f32_16x16x32_bf16 v[112:115], v[138:141], v[202:205], v[112:115]
	v_mfma_f32_16x16x32_bf16 v[108:111], v[142:145], v[198:201], v[108:111]
	v_mfma_f32_16x16x32_bf16 v[108:111], v[146:149], v[202:205], v[108:111]
	v_mfma_f32_16x16x32_bf16 v[104:107], v[134:137], v[206:209], v[104:107]
	v_mfma_f32_16x16x32_bf16 v[104:107], v[138:141], v[210:213], v[104:107]
	v_mfma_f32_16x16x32_bf16 v[100:103], v[142:145], v[206:209], v[100:103]
	v_mfma_f32_16x16x32_bf16 v[100:103], v[146:149], v[210:213], v[100:103]
	v_mfma_f32_16x16x32_bf16 v[96:99], v[160:163], v[182:185], v[96:99]
	v_mfma_f32_16x16x32_bf16 v[96:99], v[164:167], v[186:189], v[96:99]
	v_mfma_f32_16x16x32_bf16 v[92:95], v[174:177], v[182:185], v[92:95]
	v_mfma_f32_16x16x32_bf16 v[92:95], v[178:181], v[186:189], v[92:95]
	v_mfma_f32_16x16x32_bf16 v[88:91], v[160:163], v[190:193], v[88:91]
	v_mfma_f32_16x16x32_bf16 v[88:91], v[164:167], v[194:197], v[88:91]
	v_mfma_f32_16x16x32_bf16 v[84:87], v[174:177], v[190:193], v[84:87]
	v_mfma_f32_16x16x32_bf16 v[84:87], v[178:181], v[194:197], v[84:87]
	v_mfma_f32_16x16x32_bf16 v[80:83], v[160:163], v[198:201], v[80:83]
	v_mfma_f32_16x16x32_bf16 v[80:83], v[164:167], v[202:205], v[80:83]
	v_mfma_f32_16x16x32_bf16 v[76:79], v[174:177], v[198:201], v[76:79]
	v_mfma_f32_16x16x32_bf16 v[76:79], v[178:181], v[202:205], v[76:79]
	v_mfma_f32_16x16x32_bf16 v[72:75], v[160:163], v[206:209], v[72:75]
	v_mfma_f32_16x16x32_bf16 v[72:75], v[164:167], v[210:213], v[72:75]
	v_mfma_f32_16x16x32_bf16 v[68:71], v[174:177], v[206:209], v[68:71]
	v_mfma_f32_16x16x32_bf16 v[68:71], v[178:181], v[210:213], v[68:71]
	s_barrier
	s_mov_b32 m0, s84
	v_lshl_add_u64 v[150:151], s[30:31], 0, v[154:155]
	s_add_u32 s26, s30, 0x100000
	ds_read_b128 v[182:185], v168 offset:16384
	ds_read_b128 v[186:189], v168 offset:17408
	ds_read_b128 v[190:193], v168 offset:18432
	ds_read_b128 v[194:197], v168 offset:19456
	ds_read_b128 v[198:201], v168 offset:20480
	ds_read_b128 v[202:205], v168 offset:21504
	ds_read_b128 v[206:209], v168 offset:22528
	ds_read_b128 v[210:213], v168 offset:23552
	global_load_lds_dwordx4 v[150:151], off
	v_lshl_add_u64 v[214:215], s[30:31], 0, v[158:159]
	s_mov_b32 m0, s85
	s_addc_u32 s27, s31, 0
	global_load_lds_dwordx4 v[214:215], off
	v_lshl_add_u64 v[216:217], s[26:27], 0, v[154:155]
	s_mov_b32 m0, s86
	v_lshl_add_u64 v[218:219], s[38:39], 0, v[156:157]
	global_load_lds_dwordx4 v[216:217], off
	v_lshl_add_u64 v[216:217], s[26:27], 0, v[158:159]
	s_mov_b32 m0, s87
	s_nop 0
	global_load_lds_dwordx4 v[216:217], off
	v_lshl_add_u64 v[216:217], s[38:39], 0, v[152:153]
	s_mov_b32 m0, s83
	s_nop 0
	global_load_lds_dwordx4 v[216:217], off
	s_mov_b32 m0, s88
	s_nop 0
	global_load_lds_dwordx4 v[218:219], off
	s_waitcnt vmcnt(8)
	s_waitcnt lgkmcnt(0)
	s_barrier
; #define PG8_STAGE(bufoff, gbase, voff) do { _Pragma("unroll") for (int _i = 0; _i < 2; ++_i) \
;         __builtin_amdgcn_global_load_lds((const unsigned*)((const char*)(gbase) + (voff)[_i]), (LAS unsigned*)(lds + (bufoff) + ldsw + _i * 8192), 16, 0, 0); } while (0)
; #define PG8_LDA(dst, b, h) do { _Pragma("unroll") for (int m = 0; m < 4; ++m) _Pragma("unroll") for (int k = 0; k < 2; ++k) dst[m][k] = *(const LAS bf16x8*)(pA + PG8_SA(b, h) + m * 2048 + k * 1024); } while (0)
; #define PG8_LDB(dst, b, h) do { _Pragma("unroll") for (int n = 0; n < 2; ++n) _Pragma("unroll") for (int k = 0; k < 2; ++k) dst[n][k] = *(const LAS bf16x8*)(pB + (PG8_SB(b, h) - 4 * HTB) + n * 2048 + k * 1024); } while (0)
; #define PG8_MMA(ai, bj, At, Bt) do { __builtin_amdgcn_s_setprio(1); _Pragma("unroll") for (int m = 0; m < 4; ++m) _Pragma("unroll") for (int n = 0; n < 2; ++n) _Pragma("unroll") for (int k = 0; k < 2; ++k) \
;         acc[ai][bj][m][n] = __builtin_amdgcn_mfma_f32_16x16x32_bf16(Bt[n][k], At[m][k], acc[ai][bj][m][n], 0, 0, 0); __builtin_amdgcn_s_setprio(0); } while (0)
; #define PG8_WAIT_V(n) asm volatile("s_waitcnt vmcnt(" #n ")" ::: "memory")
; #define PG8_WAIT_L(n) asm volatile("s_waitcnt lgkmcnt(" #n ")" ::: "memory")
; #define PG8_BAR __builtin_amdgcn_s_barrier()
; #define PG8_SCHED __builtin_amdgcn_sched_barrier(0)
; template <class Desc, class Epi, bool ALIGN_EPI>
; __device__ __forceinline__ void gemm_phase(LAS unsigned char* lds, const Desc& D, const Epi& E, int G, int c) {
;     ...
;             PG8_WAIT_V(8); PG8_WAIT_L(0); PG8_BAR; PG8_MMA(1, 0, At, B0); PG8_MMA(1, 1, At, B1); PG8_BAR; PG8_SCHED;
;             PG8_LDB(B0, 1, 0); PG8_LDB(B1, 1, 1); PG8_SCHED; PG8_LDA(At, 1, 0); PG8_STAGE(PG8_SA(0, 1), a2 + hstepA, voffA);
;             PG8_WAIT_V(8); PG8_WAIT_L(0); PG8_BAR; PG8_MMA(0, 0, At, B0); PG8_MMA(0, 1, At, B1); PG8_BAR; PG8_SCHED;
	v_mfma_f32_16x16x32_bf16 v[64:67], v[134:137], v[182:185], v[64:67]
	v_mfma_f32_16x16x32_bf16 v[64:67], v[138:141], v[186:189], v[64:67]
	v_mfma_f32_16x16x32_bf16 v[52:55], v[142:145], v[182:185], v[52:55]
	v_mfma_f32_16x16x32_bf16 v[52:55], v[146:149], v[186:189], v[52:55]
	v_mfma_f32_16x16x32_bf16 v[32:35], v[134:137], v[190:193], v[32:35]
	v_mfma_f32_16x16x32_bf16 v[32:35], v[138:141], v[194:197], v[32:35]
	v_mfma_f32_16x16x32_bf16 v[20:23], v[142:145], v[190:193], v[20:23]
	v_mfma_f32_16x16x32_bf16 v[20:23], v[146:149], v[194:197], v[20:23]
	v_mfma_f32_16x16x32_bf16 v[16:19], v[134:137], v[198:201], v[16:19]
	v_mfma_f32_16x16x32_bf16 v[16:19], v[138:141], v[202:205], v[16:19]
	v_mfma_f32_16x16x32_bf16 v[12:15], v[142:145], v[198:201], v[12:15]
	v_mfma_f32_16x16x32_bf16 v[12:15], v[146:149], v[202:205], v[12:15]
	v_mfma_f32_16x16x32_bf16 v[8:11], v[134:137], v[206:209], v[8:11]
	v_mfma_f32_16x16x32_bf16 v[8:11], v[138:141], v[210:213], v[8:11]
	v_mfma_f32_16x16x32_bf16 v[4:7], v[142:145], v[206:209], v[4:7]
	v_mfma_f32_16x16x32_bf16 v[4:7], v[146:149], v[210:213], v[4:7]
	v_mfma_f32_16x16x32_bf16 v[60:63], v[160:163], v[182:185], v[60:63]
	v_mfma_f32_16x16x32_bf16 v[60:63], v[164:167], v[186:189], v[60:63]
	v_mfma_f32_16x16x32_bf16 v[56:59], v[174:177], v[182:185], v[56:59]
	v_mfma_f32_16x16x32_bf16 v[56:59], v[178:181], v[186:189], v[56:59]
	v_mfma_f32_16x16x32_bf16 v[48:51], v[160:163], v[190:193], v[48:51]
	v_mfma_f32_16x16x32_bf16 v[48:51], v[164:167], v[194:197], v[48:51]
	v_mfma_f32_16x16x32_bf16 v[44:47], v[174:177], v[190:193], v[44:47]
	v_mfma_f32_16x16x32_bf16 v[44:47], v[178:181], v[194:197], v[44:47]
	v_mfma_f32_16x16x32_bf16 v[40:43], v[160:163], v[198:201], v[40:43]
	v_mfma_f32_16x16x32_bf16 v[40:43], v[164:167], v[202:205], v[40:43]
	v_mfma_f32_16x16x32_bf16 v[36:39], v[174:177], v[198:201], v[36:39]
	v_mfma_f32_16x16x32_bf16 v[36:39], v[178:181], v[202:205], v[36:39]
	v_mfma_f32_16x16x32_bf16 v[28:31], v[160:163], v[206:209], v[28:31]
	v_mfma_f32_16x16x32_bf16 v[28:31], v[164:167], v[210:213], v[28:31]
	v_mfma_f32_16x16x32_bf16 v[24:27], v[174:177], v[206:209], v[24:27]
	v_mfma_f32_16x16x32_bf16 v[24:27], v[178:181], v[210:213], v[24:27]
	s_barrier
	ds_read_b128 v[134:137], v169 offset:32768
	ds_read_b128 v[138:141], v169 offset:33792
	ds_read_b128 v[142:145], v169 offset:34816
	ds_read_b128 v[146:149], v169 offset:35840
	ds_read_b128 v[160:163], v169 offset:49152
	ds_read_b128 v[164:167], v169 offset:50176
	ds_read_b128 v[174:177], v169 offset:51200
	ds_read_b128 v[178:181], v169 offset:52224
	s_add_u32 s26, s38, 0x100000
	s_addc_u32 s27, s39, 0
	s_mov_b32 m0, s89
	v_lshl_add_u64 v[220:221], s[26:27], 0, v[152:153]
	ds_read_b128 v[182:185], v168 offset:32768
	ds_read_b128 v[186:189], v168 offset:33792
	ds_read_b128 v[190:193], v168 offset:34816
	ds_read_b128 v[194:197], v168 offset:35840
	ds_read_b128 v[198:201], v168 offset:36864
	ds_read_b128 v[202:205], v168 offset:37888
	ds_read_b128 v[206:209], v168 offset:38912
	ds_read_b128 v[210:213], v168 offset:39936
	global_load_lds_dwordx4 v[220:221], off
	v_lshl_add_u64 v[220:221], s[26:27], 0, v[156:157]
	s_mov_b32 m0, s90
	s_nop 0
	global_load_lds_dwordx4 v[220:221], off
	s_waitcnt vmcnt(8)
	s_waitcnt lgkmcnt(0)
	s_barrier
	v_mfma_f32_16x16x32_bf16 v[128:131], v[134:137], v[182:185], v[128:131]
	v_mfma_f32_16x16x32_bf16 v[128:131], v[138:141], v[186:189], v[128:131]
	v_mfma_f32_16x16x32_bf16 v[124:127], v[142:145], v[182:185], v[124:127]
	v_mfma_f32_16x16x32_bf16 v[124:127], v[146:149], v[186:189], v[124:127]
	v_mfma_f32_16x16x32_bf16 v[120:123], v[134:137], v[190:193], v[120:123]
	v_mfma_f32_16x16x32_bf16 v[120:123], v[138:141], v[194:197], v[120:123]
	v_mfma_f32_16x16x32_bf16 v[116:119], v[142:145], v[190:193], v[116:119]
	v_mfma_f32_16x16x32_bf16 v[116:119], v[146:149], v[194:197], v[116:119]
	v_mfma_f32_16x16x32_bf16 v[112:115], v[134:137], v[198:201], v[112:115]
	v_mfma_f32_16x16x32_bf16 v[112:115], v[138:141], v[202:205], v[112:115]
	v_mfma_f32_16x16x32_bf16 v[108:111], v[142:145], v[198:201], v[108:111]
	v_mfma_f32_16x16x32_bf16 v[108:111], v[146:149], v[202:205], v[108:111]
	v_mfma_f32_16x16x32_bf16 v[104:107], v[134:137], v[206:209], v[104:107]
	v_mfma_f32_16x16x32_bf16 v[104:107], v[138:141], v[210:213], v[104:107]
	v_mfma_f32_16x16x32_bf16 v[100:103], v[142:145], v[206:209], v[100:103]
	v_mfma_f32_16x16x32_bf16 v[100:103], v[146:149], v[210:213], v[100:103]
	v_mfma_f32_16x16x32_bf16 v[96:99], v[160:163], v[182:185], v[96:99]
	v_mfma_f32_16x16x32_bf16 v[96:99], v[164:167], v[186:189], v[96:99]
	v_mfma_f32_16x16x32_bf16 v[92:95], v[174:177], v[182:185], v[92:95]
	v_mfma_f32_16x16x32_bf16 v[92:95], v[178:181], v[186:189], v[92:95]
	v_mfma_f32_16x16x32_bf16 v[88:91], v[160:163], v[190:193], v[88:91]
	v_mfma_f32_16x16x32_bf16 v[88:91], v[164:167], v[194:197], v[88:91]
	v_mfma_f32_16x16x32_bf16 v[84:87], v[174:177], v[190:193], v[84:87]
	v_mfma_f32_16x16x32_bf16 v[84:87], v[178:181], v[194:197], v[84:87]
	v_mfma_f32_16x16x32_bf16 v[80:83], v[160:163], v[198:201], v[80:83]
	v_mfma_f32_16x16x32_bf16 v[80:83], v[164:167], v[202:205], v[80:83]
	v_mfma_f32_16x16x32_bf16 v[76:79], v[174:177], v[198:201], v[76:79]
	v_mfma_f32_16x16x32_bf16 v[76:79], v[178:181], v[202:205], v[76:79]
	v_mfma_f32_16x16x32_bf16 v[72:75], v[160:163], v[206:209], v[72:75]
	v_mfma_f32_16x16x32_bf16 v[72:75], v[164:167], v[210:213], v[72:75]
	v_mfma_f32_16x16x32_bf16 v[68:71], v[174:177], v[206:209], v[68:71]
	v_mfma_f32_16x16x32_bf16 v[68:71], v[178:181], v[210:213], v[68:71]
	s_barrier
; #define PG8_STAGE(bufoff, gbase, voff) do { _Pragma("unroll") for (int _i = 0; _i < 2; ++_i) \
;         __builtin_amdgcn_global_load_lds((const unsigned*)((const char*)(gbase) + (voff)[_i]), (LAS unsigned*)(lds + (bufoff) + ldsw + _i * 8192), 16, 0, 0); } while (0)
; #define PG8_LDA(dst, b, h) do { _Pragma("unroll") for (int m = 0; m < 4; ++m) _Pragma("unroll") for (int k = 0; k < 2; ++k) dst[m][k] = *(const LAS bf16x8*)(pA + PG8_SA(b, h) + m * 2048 + k * 1024); } while (0)
; #define PG8_MMA(ai, bj, At, Bt) do { __builtin_amdgcn_s_setprio(1); _Pragma("unroll") for (int m = 0; m < 4; ++m) _Pragma("unroll") for (int n = 0; n < 2; ++n) _Pragma("unroll") for (int k = 0; k < 2; ++k) \
;         acc[ai][bj][m][n] = __builtin_amdgcn_mfma_f32_16x16x32_bf16(Bt[n][k], At[m][k], acc[ai][bj][m][n], 0, 0, 0); __builtin_amdgcn_s_setprio(0); } while (0)
; #define PG8_WAIT_V(n) asm volatile("s_waitcnt vmcnt(" #n ")" ::: "memory")
; #define PG8_WAIT_L(n) asm volatile("s_waitcnt lgkmcnt(" #n ")" ::: "memory")
; #define PG8_BAR __builtin_amdgcn_s_barrier()
; #define PG8_SCHED __builtin_amdgcn_sched_barrier(0)
; template <class Desc, class Epi, bool ALIGN_EPI>
; __device__ __forceinline__ void gemm_phase(LAS unsigned char* lds, const Desc& D, const Epi& E, int G, int c) {
;     ...
;             PG8_LDA(At, 1, 1); PG8_STAGE(PG8_SB(1, 0), b3, voffB); PG8_STAGE(PG8_SB(1, 1), b3 + hstepB, voffB); PG8_STAGE(PG8_SA(1, 0), a3, voffA);
;             PG8_WAIT_V(8); PG8_WAIT_L(0); PG8_BAR; PG8_MMA(1, 0, At, B0); PG8_MMA(1, 1, At, B1); PG8_BAR; PG8_SCHED;
;         }
	s_mov_b32 m0, s92
	v_lshl_add_u64 v[150:151], v[150:151], 0, s[76:77]
	s_add_u32 s26, s30, 0x100080
	ds_read_b128 v[182:185], v168 offset:49152
	ds_read_b128 v[186:189], v168 offset:50176
	ds_read_b128 v[190:193], v168 offset:51200
	ds_read_b128 v[194:197], v168 offset:52224
	ds_read_b128 v[198:201], v168 offset:53248
	ds_read_b128 v[202:205], v168 offset:54272
	ds_read_b128 v[206:209], v168 offset:55296
	ds_read_b128 v[210:213], v168 offset:56320
	global_load_lds_dwordx4 v[150:151], off
	v_lshl_add_u64 v[150:151], v[214:215], 0, s[76:77]
	s_mov_b32 m0, s93
	s_addc_u32 s27, s31, 0
	global_load_lds_dwordx4 v[150:151], off
	v_lshl_add_u64 v[150:151], s[26:27], 0, v[154:155]
	s_mov_b32 m0, s97
	s_nop 0
	global_load_lds_dwordx4 v[150:151], off
	v_lshl_add_u64 v[150:151], s[26:27], 0, v[158:159]
	s_mov_b32 m0, s82
	s_nop 0
	global_load_lds_dwordx4 v[150:151], off
	v_lshl_add_u64 v[150:151], v[216:217], 0, s[76:77]
	s_mov_b32 m0, s94
	s_nop 0
	global_load_lds_dwordx4 v[150:151], off
	v_lshl_add_u64 v[150:151], v[218:219], 0, s[76:77]
	s_mov_b32 m0, s95
	s_nop 0
	global_load_lds_dwordx4 v[150:151], off
	s_waitcnt vmcnt(8)
	s_waitcnt lgkmcnt(0)
	s_barrier
	v_mfma_f32_16x16x32_bf16 v[64:67], v[134:137], v[182:185], v[64:67]
	v_mfma_f32_16x16x32_bf16 v[64:67], v[138:141], v[186:189], v[64:67]
	v_mfma_f32_16x16x32_bf16 v[52:55], v[142:145], v[182:185], v[52:55]
	v_mfma_f32_16x16x32_bf16 v[52:55], v[146:149], v[186:189], v[52:55]
	v_mfma_f32_16x16x32_bf16 v[32:35], v[134:137], v[190:193], v[32:35]
	v_mfma_f32_16x16x32_bf16 v[32:35], v[138:141], v[194:197], v[32:35]
	v_mfma_f32_16x16x32_bf16 v[20:23], v[142:145], v[190:193], v[20:23]
	v_mfma_f32_16x16x32_bf16 v[20:23], v[146:149], v[194:197], v[20:23]
	v_mfma_f32_16x16x32_bf16 v[16:19], v[134:137], v[198:201], v[16:19]
	v_mfma_f32_16x16x32_bf16 v[16:19], v[138:141], v[202:205], v[16:19]
	v_mfma_f32_16x16x32_bf16 v[12:15], v[142:145], v[198:201], v[12:15]
	v_mfma_f32_16x16x32_bf16 v[12:15], v[146:149], v[202:205], v[12:15]
	v_mfma_f32_16x16x32_bf16 v[8:11], v[134:137], v[206:209], v[8:11]
	v_mfma_f32_16x16x32_bf16 v[8:11], v[138:141], v[210:213], v[8:11]
	v_mfma_f32_16x16x32_bf16 v[4:7], v[142:145], v[206:209], v[4:7]
	v_mfma_f32_16x16x32_bf16 v[4:7], v[146:149], v[210:213], v[4:7]
	v_mfma_f32_16x16x32_bf16 v[60:63], v[160:163], v[182:185], v[60:63]
	v_mfma_f32_16x16x32_bf16 v[60:63], v[164:167], v[186:189], v[60:63]
	v_mfma_f32_16x16x32_bf16 v[56:59], v[174:177], v[182:185], v[56:59]
	v_mfma_f32_16x16x32_bf16 v[56:59], v[178:181], v[186:189], v[56:59]
	v_mfma_f32_16x16x32_bf16 v[48:51], v[160:163], v[190:193], v[48:51]
	v_mfma_f32_16x16x32_bf16 v[48:51], v[164:167], v[194:197], v[48:51]
	v_mfma_f32_16x16x32_bf16 v[44:47], v[174:177], v[190:193], v[44:47]
	v_mfma_f32_16x16x32_bf16 v[44:47], v[178:181], v[194:197], v[44:47]
	v_mfma_f32_16x16x32_bf16 v[40:43], v[160:163], v[198:201], v[40:43]
	v_mfma_f32_16x16x32_bf16 v[40:43], v[164:167], v[202:205], v[40:43]
	v_mfma_f32_16x16x32_bf16 v[36:39], v[174:177], v[198:201], v[36:39]
	v_mfma_f32_16x16x32_bf16 v[36:39], v[178:181], v[202:205], v[36:39]
	v_mfma_f32_16x16x32_bf16 v[28:31], v[160:163], v[206:209], v[28:31]
	v_mfma_f32_16x16x32_bf16 v[28:31], v[164:167], v[210:213], v[28:31]
	v_mfma_f32_16x16x32_bf16 v[24:27], v[174:177], v[206:209], v[24:27]
	v_mfma_f32_16x16x32_bf16 v[24:27], v[178:181], v[210:213], v[24:27]
	s_barrier
	s_cmp_ge_u32 s14, s3
	s_mov_b32 s17, s14
	s_cbranch_scc1 .LBB0_183

;     __device__ __forceinline__ int nt(const Unit& u) const { return (u.pn >> 1) < 2 ? 22 : 20; }
; #define PG8_STAGE(bufoff, gbase, voff) do { _Pragma("unroll") for (int _i = 0; _i < 2; ++_i) \
;         __builtin_amdgcn_global_load_lds((const unsigned*)((const char*)(gbase) + (voff)[_i]), (LAS unsigned*)(lds + (bufoff) + ldsw + _i * 8192), 16, 0, 0); } while (0)
; #define PG8_LDA(dst, b, h) do { _Pragma("unroll") for (int m = 0; m < 4; ++m) _Pragma("unroll") for (int k = 0; k < 2; ++k) dst[m][k] = *(const LAS bf16x8*)(pA + PG8_SA(b, h) + m * 2048 + k * 1024); } while (0)
; #define PG8_LDB(dst, b, h) do { _Pragma("unroll") for (int n = 0; n < 2; ++n) _Pragma("unroll") for (int k = 0; k < 2; ++k) dst[n][k] = *(const LAS bf16x8*)(pB + (PG8_SB(b, h) - 4 * HTB) + n * 2048 + k * 1024); } while (0)
; #define PG8_MMA(ai, bj, At, Bt) do { __builtin_amdgcn_s_setprio(1); _Pragma("unroll") for (int m = 0; m < 4; ++m) _Pragma("unroll") for (int n = 0; n < 2; ++n) _Pragma("unroll") for (int k = 0; k < 2; ++k) \
;         acc[ai][bj][m][n] = __builtin_amdgcn_mfma_f32_16x16x32_bf16(Bt[n][k], At[m][k], acc[ai][bj][m][n], 0, 0, 0); __builtin_amdgcn_s_setprio(0); } while (0)
; #define PG8_WAIT_V(n) asm volatile("s_waitcnt vmcnt(" #n ")" ::: "memory")
; #define PG8_BAR __builtin_amdgcn_s_barrier()
; template <class Desc, class Epi, bool ALIGN_EPI>
; __device__ __forceinline__ void gemm_phase(LAS unsigned char* lds, const Desc& D, const Epi& E, int G, int c) {
;     ...
;         for (int t = 0; t < nt; t += 2) {
;             const bool last = (t == nt - 2);
;             if (last && has_next) PG8_AWAIT(nxt);
;             const char* a1 = cA + (size_t)(t + 1) * kstep;
;             const char* a2 = last ? nA : cA + (size_t)(t + 2) * kstep; const char* b2 = last ? nB : cB + (size_t)(t + 2) * kstep;
;             const char* a3 = a2 + kstep; const char* b3 = b2 + kstep;
;             PG8_LDB(B0, 0, 0); PG8_LDB(B1, 0, 1); PG8_SCHED; PG8_LDA(At, 0, 0); PG8_STAGE(PG8_SA(1, 1), a1 + hstepA, voffA);
;             PG8_WAIT_V(8); PG8_WAIT_L(0); PG8_BAR; PG8_MMA(0, 0, At, B0); PG8_MMA(0, 1, At, B1); PG8_BAR; PG8_SCHED;
;             PG8_LDA(At, 0, 1); PG8_STAGE(PG8_SB(0, 0), b2, voffB); PG8_STAGE(PG8_SB(0, 1), b2 + hstepB, voffB); PG8_STAGE(PG8_SA(0, 0), a2, voffA);
;             PG8_WAIT_V(8); PG8_WAIT_L(0); PG8_BAR; PG8_MMA(1, 0, At, B0); PG8_MMA(1, 1, At, B1); PG8_BAR; PG8_SCHED;
.LBB0_603:
	ds_read_b128 v[144:147], v149
	ds_read_b128 v[152:155], v149 offset:1024
	ds_read_b128 v[156:159], v149 offset:2048
	ds_read_b128 v[160:163], v149 offset:3072
	ds_read_b128 v[164:167], v149 offset:16384
	ds_read_b128 v[168:171], v149 offset:17408
	ds_read_b128 v[172:175], v149 offset:18432
	ds_read_b128 v[176:179], v149 offset:19456
	s_add_u32 s16, s12, 0xfff80080
	s_addc_u32 s17, s13, -1
	s_cmp_eq_u32 s46, 4
	s_cselect_b32 s19, s9, s17
	s_cselect_b32 s18, s8, s16
	s_cselect_b32 s17, s11, s45
	s_cselect_b32 s16, s10, s7
	v_lshl_add_u64 v[212:213], s[12:13], 0, v[140:141]
	s_add_i32 m0, s20, 0xc000
	ds_read_b128 v[180:183], v148
	ds_read_b128 v[184:187], v148 offset:1024
	ds_read_b128 v[188:191], v148 offset:2048
	ds_read_b128 v[192:195], v148 offset:3072
	ds_read_b128 v[196:199], v148 offset:4096
	ds_read_b128 v[200:203], v148 offset:5120
	ds_read_b128 v[204:207], v148 offset:6144
	ds_read_b128 v[208:211], v148 offset:7168
	global_load_lds_dwordx4 v[212:213], off
	v_lshl_add_u64 v[212:213], s[12:13], 0, v[142:143]
	s_add_i32 m0, s20, 0xe000
	s_nop 0
	global_load_lds_dwordx4 v[212:213], off
	s_waitcnt vmcnt(8)
	s_waitcnt lgkmcnt(0)
	s_barrier
	v_mfma_f32_16x16x32_bf16 v[128:131], v[144:147], v[180:183], v[128:131]
	v_mfma_f32_16x16x32_bf16 v[128:131], v[152:155], v[184:187], v[128:131]
	v_mfma_f32_16x16x32_bf16 v[124:127], v[156:159], v[180:183], v[124:127]
	v_mfma_f32_16x16x32_bf16 v[124:127], v[160:163], v[184:187], v[124:127]
	v_mfma_f32_16x16x32_bf16 v[116:119], v[144:147], v[188:191], v[116:119]
	v_mfma_f32_16x16x32_bf16 v[116:119], v[152:155], v[192:195], v[116:119]
	v_mfma_f32_16x16x32_bf16 v[108:111], v[156:159], v[188:191], v[108:111]
	v_mfma_f32_16x16x32_bf16 v[108:111], v[160:163], v[192:195], v[108:111]
	v_mfma_f32_16x16x32_bf16 v[100:103], v[144:147], v[196:199], v[100:103]
	v_mfma_f32_16x16x32_bf16 v[100:103], v[152:155], v[200:203], v[100:103]
	v_mfma_f32_16x16x32_bf16 v[92:95], v[156:159], v[196:199], v[92:95]
	v_mfma_f32_16x16x32_bf16 v[92:95], v[160:163], v[200:203], v[92:95]
	v_mfma_f32_16x16x32_bf16 v[84:87], v[144:147], v[204:207], v[84:87]
	v_mfma_f32_16x16x32_bf16 v[84:87], v[152:155], v[208:211], v[84:87]
	v_mfma_f32_16x16x32_bf16 v[76:79], v[156:159], v[204:207], v[76:79]
	v_mfma_f32_16x16x32_bf16 v[76:79], v[160:163], v[208:211], v[76:79]
	v_mfma_f32_16x16x32_bf16 v[120:123], v[164:167], v[180:183], v[120:123]
	v_mfma_f32_16x16x32_bf16 v[120:123], v[168:171], v[184:187], v[120:123]
	v_mfma_f32_16x16x32_bf16 v[112:115], v[172:175], v[180:183], v[112:115]
	v_mfma_f32_16x16x32_bf16 v[112:115], v[176:179], v[184:187], v[112:115]
	v_mfma_f32_16x16x32_bf16 v[104:107], v[164:167], v[188:191], v[104:107]
	v_mfma_f32_16x16x32_bf16 v[104:107], v[168:171], v[192:195], v[104:107]
	v_mfma_f32_16x16x32_bf16 v[96:99], v[172:175], v[188:191], v[96:99]
	v_mfma_f32_16x16x32_bf16 v[96:99], v[176:179], v[192:195], v[96:99]
	v_mfma_f32_16x16x32_bf16 v[88:91], v[164:167], v[196:199], v[88:91]
	v_mfma_f32_16x16x32_bf16 v[88:91], v[168:171], v[200:203], v[88:91]
	v_mfma_f32_16x16x32_bf16 v[80:83], v[172:175], v[196:199], v[80:83]
	v_mfma_f32_16x16x32_bf16 v[80:83], v[176:179], v[200:203], v[80:83]
	v_mfma_f32_16x16x32_bf16 v[72:75], v[164:167], v[204:207], v[72:75]
	v_mfma_f32_16x16x32_bf16 v[72:75], v[168:171], v[208:211], v[72:75]
	v_mfma_f32_16x16x32_bf16 v[68:71], v[172:175], v[204:207], v[68:71]
	v_mfma_f32_16x16x32_bf16 v[68:71], v[176:179], v[208:211], v[68:71]
	s_barrier
	s_mov_b32 m0, s21
	v_lshl_add_u64 v[212:213], s[16:17], 0, v[136:137]
	s_add_u32 s48, s16, 0x20000
	ds_read_b128 v[180:183], v148 offset:16384
	ds_read_b128 v[184:187], v148 offset:17408
	ds_read_b128 v[188:191], v148 offset:18432
	ds_read_b128 v[192:195], v148 offset:19456
	ds_read_b128 v[196:199], v148 offset:20480
	ds_read_b128 v[200:203], v148 offset:21504
	ds_read_b128 v[204:207], v148 offset:22528
	ds_read_b128 v[208:211], v148 offset:23552
	global_load_lds_dwordx4 v[212:213], off
	v_lshl_add_u64 v[214:215], s[16:17], 0, v[132:133]
	s_mov_b32 m0, s23
	s_addc_u32 s49, s17, 0
	global_load_lds_dwordx4 v[214:215], off
	v_lshl_add_u64 v[216:217], s[48:49], 0, v[136:137]
	s_mov_b32 m0, s24
	v_lshl_add_u64 v[218:219], s[18:19], 0, v[134:135]
	global_load_lds_dwordx4 v[216:217], off
	v_lshl_add_u64 v[216:217], s[48:49], 0, v[132:133]
	s_mov_b32 m0, s25
	s_nop 0
	global_load_lds_dwordx4 v[216:217], off
	v_lshl_add_u64 v[216:217], s[18:19], 0, v[138:139]
	s_mov_b32 m0, s20
	s_nop 0
	global_load_lds_dwordx4 v[216:217], off
	s_mov_b32 m0, s26
	s_nop 0
	global_load_lds_dwordx4 v[218:219], off
	s_waitcnt vmcnt(8)
	s_waitcnt lgkmcnt(0)
	s_barrier
; #define PG8_STAGE(bufoff, gbase, voff) do { _Pragma("unroll") for (int _i = 0; _i < 2; ++_i) \
;         __builtin_amdgcn_global_load_lds((const unsigned*)((const char*)(gbase) + (voff)[_i]), (LAS unsigned*)(lds + (bufoff) + ldsw + _i * 8192), 16, 0, 0); } while (0)
; #define PG8_LDA(dst, b, h) do { _Pragma("unroll") for (int m = 0; m < 4; ++m) _Pragma("unroll") for (int k = 0; k < 2; ++k) dst[m][k] = *(const LAS bf16x8*)(pA + PG8_SA(b, h) + m * 2048 + k * 1024); } while (0)
; #define PG8_LDB(dst, b, h) do { _Pragma("unroll") for (int n = 0; n < 2; ++n) _Pragma("unroll") for (int k = 0; k < 2; ++k) dst[n][k] = *(const LAS bf16x8*)(pB + (PG8_SB(b, h) - 4 * HTB) + n * 2048 + k * 1024); } while (0)
; #define PG8_MMA(ai, bj, At, Bt) do { __builtin_amdgcn_s_setprio(1); _Pragma("unroll") for (int m = 0; m < 4; ++m) _Pragma("unroll") for (int n = 0; n < 2; ++n) _Pragma("unroll") for (int k = 0; k < 2; ++k) \
;         acc[ai][bj][m][n] = __builtin_amdgcn_mfma_f32_16x16x32_bf16(Bt[n][k], At[m][k], acc[ai][bj][m][n], 0, 0, 0); __builtin_amdgcn_s_setprio(0); } while (0)
; #define PG8_WAIT_V(n) asm volatile("s_waitcnt vmcnt(" #n ")" ::: "memory")
; #define PG8_WAIT_L(n) asm volatile("s_waitcnt lgkmcnt(" #n ")" ::: "memory")
; #define PG8_BAR __builtin_amdgcn_s_barrier()
; #define PG8_SCHED __builtin_amdgcn_sched_barrier(0)
; template <class Desc, class Epi, bool ALIGN_EPI>
; __device__ __forceinline__ void gemm_phase(LAS unsigned char* lds, const Desc& D, const Epi& E, int G, int c) {
;     ...
;             PG8_WAIT_V(8); PG8_WAIT_L(0); PG8_BAR; PG8_MMA(1, 0, At, B0); PG8_MMA(1, 1, At, B1); PG8_BAR; PG8_SCHED;
;             PG8_LDB(B0, 1, 0); PG8_LDB(B1, 1, 1); PG8_SCHED; PG8_LDA(At, 1, 0); PG8_STAGE(PG8_SA(0, 1), a2 + hstepA, voffA);
;             PG8_WAIT_V(8); PG8_WAIT_L(0); PG8_BAR; PG8_MMA(0, 0, At, B0); PG8_MMA(0, 1, At, B1); PG8_BAR; PG8_SCHED;
	v_mfma_f32_16x16x32_bf16 v[64:67], v[144:147], v[180:183], v[64:67]
	v_mfma_f32_16x16x32_bf16 v[64:67], v[152:155], v[184:187], v[64:67]
	v_mfma_f32_16x16x32_bf16 v[60:63], v[156:159], v[180:183], v[60:63]
	v_mfma_f32_16x16x32_bf16 v[60:63], v[160:163], v[184:187], v[60:63]
	v_mfma_f32_16x16x32_bf16 v[52:55], v[144:147], v[188:191], v[52:55]
	v_mfma_f32_16x16x32_bf16 v[52:55], v[152:155], v[192:195], v[52:55]
	v_mfma_f32_16x16x32_bf16 v[44:47], v[156:159], v[188:191], v[44:47]
	v_mfma_f32_16x16x32_bf16 v[44:47], v[160:163], v[192:195], v[44:47]
	v_mfma_f32_16x16x32_bf16 v[36:39], v[144:147], v[196:199], v[36:39]
	v_mfma_f32_16x16x32_bf16 v[36:39], v[152:155], v[200:203], v[36:39]
	v_mfma_f32_16x16x32_bf16 v[28:31], v[156:159], v[196:199], v[28:31]
	v_mfma_f32_16x16x32_bf16 v[28:31], v[160:163], v[200:203], v[28:31]
	v_mfma_f32_16x16x32_bf16 v[20:23], v[144:147], v[204:207], v[20:23]
	v_mfma_f32_16x16x32_bf16 v[20:23], v[152:155], v[208:211], v[20:23]
	v_mfma_f32_16x16x32_bf16 v[12:15], v[156:159], v[204:207], v[12:15]
	v_mfma_f32_16x16x32_bf16 v[12:15], v[160:163], v[208:211], v[12:15]
	v_mfma_f32_16x16x32_bf16 v[56:59], v[164:167], v[180:183], v[56:59]
	v_mfma_f32_16x16x32_bf16 v[56:59], v[168:171], v[184:187], v[56:59]
	v_mfma_f32_16x16x32_bf16 v[48:51], v[172:175], v[180:183], v[48:51]
	v_mfma_f32_16x16x32_bf16 v[48:51], v[176:179], v[184:187], v[48:51]
	v_mfma_f32_16x16x32_bf16 v[40:43], v[164:167], v[188:191], v[40:43]
	v_mfma_f32_16x16x32_bf16 v[40:43], v[168:171], v[192:195], v[40:43]
	v_mfma_f32_16x16x32_bf16 v[32:35], v[172:175], v[188:191], v[32:35]
	v_mfma_f32_16x16x32_bf16 v[32:35], v[176:179], v[192:195], v[32:35]
	v_mfma_f32_16x16x32_bf16 v[24:27], v[164:167], v[196:199], v[24:27]
	v_mfma_f32_16x16x32_bf16 v[24:27], v[168:171], v[200:203], v[24:27]
	v_mfma_f32_16x16x32_bf16 v[16:19], v[172:175], v[196:199], v[16:19]
	v_mfma_f32_16x16x32_bf16 v[16:19], v[176:179], v[200:203], v[16:19]
	v_mfma_f32_16x16x32_bf16 v[8:11], v[164:167], v[204:207], v[8:11]
	v_mfma_f32_16x16x32_bf16 v[8:11], v[168:171], v[208:211], v[8:11]
	v_mfma_f32_16x16x32_bf16 v[4:7], v[172:175], v[204:207], v[4:7]
	v_mfma_f32_16x16x32_bf16 v[4:7], v[176:179], v[208:211], v[4:7]
	s_barrier
	ds_read_b128 v[144:147], v149 offset:32768
	ds_read_b128 v[152:155], v149 offset:33792
	ds_read_b128 v[156:159], v149 offset:34816
	ds_read_b128 v[160:163], v149 offset:35840
	ds_read_b128 v[164:167], v149 offset:49152
	ds_read_b128 v[168:171], v149 offset:50176
	ds_read_b128 v[172:175], v149 offset:51200
	ds_read_b128 v[176:179], v149 offset:52224
	s_add_u32 s18, s18, 0x80000
	s_addc_u32 s19, s19, 0
	s_mov_b32 m0, s27
	v_lshl_add_u64 v[220:221], s[18:19], 0, v[138:139]
	ds_read_b128 v[180:183], v148 offset:32768
	ds_read_b128 v[184:187], v148 offset:33792
	ds_read_b128 v[188:191], v148 offset:34816
	ds_read_b128 v[192:195], v148 offset:35840
	ds_read_b128 v[196:199], v148 offset:36864
	ds_read_b128 v[200:203], v148 offset:37888
	ds_read_b128 v[204:207], v148 offset:38912
	ds_read_b128 v[208:211], v148 offset:39936
	global_load_lds_dwordx4 v[220:221], off
	v_lshl_add_u64 v[220:221], s[18:19], 0, v[134:135]
	s_mov_b32 m0, s30
	s_nop 0
	global_load_lds_dwordx4 v[220:221], off
	s_waitcnt vmcnt(8)
	s_waitcnt lgkmcnt(0)
	s_barrier
	v_mfma_f32_16x16x32_bf16 v[128:131], v[144:147], v[180:183], v[128:131]
	v_mfma_f32_16x16x32_bf16 v[128:131], v[152:155], v[184:187], v[128:131]
	v_mfma_f32_16x16x32_bf16 v[124:127], v[156:159], v[180:183], v[124:127]
	v_mfma_f32_16x16x32_bf16 v[124:127], v[160:163], v[184:187], v[124:127]
	v_mfma_f32_16x16x32_bf16 v[116:119], v[144:147], v[188:191], v[116:119]
	v_mfma_f32_16x16x32_bf16 v[116:119], v[152:155], v[192:195], v[116:119]
	v_mfma_f32_16x16x32_bf16 v[108:111], v[156:159], v[188:191], v[108:111]
	v_mfma_f32_16x16x32_bf16 v[108:111], v[160:163], v[192:195], v[108:111]
	v_mfma_f32_16x16x32_bf16 v[100:103], v[144:147], v[196:199], v[100:103]
	v_mfma_f32_16x16x32_bf16 v[100:103], v[152:155], v[200:203], v[100:103]
	v_mfma_f32_16x16x32_bf16 v[92:95], v[156:159], v[196:199], v[92:95]
	v_mfma_f32_16x16x32_bf16 v[92:95], v[160:163], v[200:203], v[92:95]
	v_mfma_f32_16x16x32_bf16 v[84:87], v[144:147], v[204:207], v[84:87]
	v_mfma_f32_16x16x32_bf16 v[84:87], v[152:155], v[208:211], v[84:87]
	v_mfma_f32_16x16x32_bf16 v[76:79], v[156:159], v[204:207], v[76:79]
	v_mfma_f32_16x16x32_bf16 v[76:79], v[160:163], v[208:211], v[76:79]
	v_mfma_f32_16x16x32_bf16 v[120:123], v[164:167], v[180:183], v[120:123]
	v_mfma_f32_16x16x32_bf16 v[120:123], v[168:171], v[184:187], v[120:123]
	v_mfma_f32_16x16x32_bf16 v[112:115], v[172:175], v[180:183], v[112:115]
	v_mfma_f32_16x16x32_bf16 v[112:115], v[176:179], v[184:187], v[112:115]
	v_mfma_f32_16x16x32_bf16 v[104:107], v[164:167], v[188:191], v[104:107]
	v_mfma_f32_16x16x32_bf16 v[104:107], v[168:171], v[192:195], v[104:107]
	v_mfma_f32_16x16x32_bf16 v[96:99], v[172:175], v[188:191], v[96:99]
	v_mfma_f32_16x16x32_bf16 v[96:99], v[176:179], v[192:195], v[96:99]
	v_mfma_f32_16x16x32_bf16 v[88:91], v[164:167], v[196:199], v[88:91]
	v_mfma_f32_16x16x32_bf16 v[88:91], v[168:171], v[200:203], v[88:91]
	v_mfma_f32_16x16x32_bf16 v[80:83], v[172:175], v[196:199], v[80:83]
	v_mfma_f32_16x16x32_bf16 v[80:83], v[176:179], v[200:203], v[80:83]
	v_mfma_f32_16x16x32_bf16 v[72:75], v[164:167], v[204:207], v[72:75]
	v_mfma_f32_16x16x32_bf16 v[72:75], v[168:171], v[208:211], v[72:75]
	v_mfma_f32_16x16x32_bf16 v[68:71], v[172:175], v[204:207], v[68:71]
	v_mfma_f32_16x16x32_bf16 v[68:71], v[176:179], v[208:211], v[68:71]
	s_barrier
; #define PG8_STAGE(bufoff, gbase, voff) do { _Pragma("unroll") for (int _i = 0; _i < 2; ++_i) \
;         __builtin_amdgcn_global_load_lds((const unsigned*)((const char*)(gbase) + (voff)[_i]), (LAS unsigned*)(lds + (bufoff) + ldsw + _i * 8192), 16, 0, 0); } while (0)
; #define PG8_LDA(dst, b, h) do { _Pragma("unroll") for (int m = 0; m < 4; ++m) _Pragma("unroll") for (int k = 0; k < 2; ++k) dst[m][k] = *(const LAS bf16x8*)(pA + PG8_SA(b, h) + m * 2048 + k * 1024); } while (0)
; #define PG8_MMA(ai, bj, At, Bt) do { __builtin_amdgcn_s_setprio(1); _Pragma("unroll") for (int m = 0; m < 4; ++m) _Pragma("unroll") for (int n = 0; n < 2; ++n) _Pragma("unroll") for (int k = 0; k < 2; ++k) \
;         acc[ai][bj][m][n] = __builtin_amdgcn_mfma_f32_16x16x32_bf16(Bt[n][k], At[m][k], acc[ai][bj][m][n], 0, 0, 0); __builtin_amdgcn_s_setprio(0); } while (0)
; #define PG8_WAIT_V(n) asm volatile("s_waitcnt vmcnt(" #n ")" ::: "memory")
; #define PG8_WAIT_L(n) asm volatile("s_waitcnt lgkmcnt(" #n ")" ::: "memory")
; #define PG8_BAR __builtin_amdgcn_s_barrier()
; #define PG8_SCHED __builtin_amdgcn_sched_barrier(0)
; template <class Desc, class Epi, bool ALIGN_EPI>
; __device__ __forceinline__ void gemm_phase(LAS unsigned char* lds, const Desc& D, const Epi& E, int G, int c) {
;     ...
;             PG8_LDA(At, 1, 1); PG8_STAGE(PG8_SB(1, 0), b3, voffB); PG8_STAGE(PG8_SB(1, 1), b3 + hstepB, voffB); PG8_STAGE(PG8_SA(1, 0), a3, voffA);
;             PG8_WAIT_V(8); PG8_WAIT_L(0); PG8_BAR; PG8_MMA(1, 0, At, B0); PG8_MMA(1, 1, At, B1); PG8_BAR; PG8_SCHED;
;         }
	s_mov_b32 m0, s31
	v_lshl_add_u64 v[212:213], v[212:213], 0, s[76:77]
	s_add_u32 s16, s16, 0x20080
	ds_read_b128 v[180:183], v148 offset:49152
	ds_read_b128 v[184:187], v148 offset:50176
	ds_read_b128 v[188:191], v148 offset:51200
	ds_read_b128 v[192:195], v148 offset:52224
	ds_read_b128 v[196:199], v148 offset:53248
	ds_read_b128 v[200:203], v148 offset:54272
	ds_read_b128 v[204:207], v148 offset:55296
	ds_read_b128 v[208:211], v148 offset:56320
	global_load_lds_dwordx4 v[212:213], off
	v_lshl_add_u64 v[212:213], v[214:215], 0, s[76:77]
	s_mov_b32 m0, s33
	s_addc_u32 s17, s17, 0
	global_load_lds_dwordx4 v[212:213], off
	v_lshl_add_u64 v[212:213], s[16:17], 0, v[136:137]
	s_mov_b32 m0, s38
	s_nop 0
	global_load_lds_dwordx4 v[212:213], off
	v_lshl_add_u64 v[212:213], s[16:17], 0, v[132:133]
	s_mov_b32 m0, s39
	s_nop 0
	global_load_lds_dwordx4 v[212:213], off
	v_lshl_add_u64 v[212:213], v[216:217], 0, s[76:77]
	s_mov_b32 m0, s34
	s_nop 0
	global_load_lds_dwordx4 v[212:213], off
	v_lshl_add_u64 v[212:213], v[218:219], 0, s[76:77]
	s_mov_b32 m0, s35
	s_nop 0
	global_load_lds_dwordx4 v[212:213], off
	s_waitcnt vmcnt(8)
	s_waitcnt lgkmcnt(0)
	s_barrier
	v_mfma_f32_16x16x32_bf16 v[64:67], v[144:147], v[180:183], v[64:67]
	v_mfma_f32_16x16x32_bf16 v[64:67], v[152:155], v[184:187], v[64:67]
	v_mfma_f32_16x16x32_bf16 v[60:63], v[156:159], v[180:183], v[60:63]
	v_mfma_f32_16x16x32_bf16 v[60:63], v[160:163], v[184:187], v[60:63]
	v_mfma_f32_16x16x32_bf16 v[52:55], v[144:147], v[188:191], v[52:55]
	v_mfma_f32_16x16x32_bf16 v[52:55], v[152:155], v[192:195], v[52:55]
	v_mfma_f32_16x16x32_bf16 v[44:47], v[156:159], v[188:191], v[44:47]
	v_mfma_f32_16x16x32_bf16 v[44:47], v[160:163], v[192:195], v[44:47]
	v_mfma_f32_16x16x32_bf16 v[36:39], v[144:147], v[196:199], v[36:39]
	v_mfma_f32_16x16x32_bf16 v[36:39], v[152:155], v[200:203], v[36:39]
	v_mfma_f32_16x16x32_bf16 v[28:31], v[156:159], v[196:199], v[28:31]
	v_mfma_f32_16x16x32_bf16 v[28:31], v[160:163], v[200:203], v[28:31]
	v_mfma_f32_16x16x32_bf16 v[20:23], v[144:147], v[204:207], v[20:23]
	v_mfma_f32_16x16x32_bf16 v[20:23], v[152:155], v[208:211], v[20:23]
	v_mfma_f32_16x16x32_bf16 v[12:15], v[156:159], v[204:207], v[12:15]
	v_mfma_f32_16x16x32_bf16 v[12:15], v[160:163], v[208:211], v[12:15]
	v_mfma_f32_16x16x32_bf16 v[56:59], v[164:167], v[180:183], v[56:59]
	v_mfma_f32_16x16x32_bf16 v[56:59], v[168:171], v[184:187], v[56:59]
	v_mfma_f32_16x16x32_bf16 v[48:51], v[172:175], v[180:183], v[48:51]
	v_mfma_f32_16x16x32_bf16 v[48:51], v[176:179], v[184:187], v[48:51]
	v_mfma_f32_16x16x32_bf16 v[40:43], v[164:167], v[188:191], v[40:43]
	v_mfma_f32_16x16x32_bf16 v[40:43], v[168:171], v[192:195], v[40:43]
	v_mfma_f32_16x16x32_bf16 v[32:35], v[172:175], v[188:191], v[32:35]
	v_mfma_f32_16x16x32_bf16 v[32:35], v[176:179], v[192:195], v[32:35]
	v_mfma_f32_16x16x32_bf16 v[24:27], v[164:167], v[196:199], v[24:27]
	v_mfma_f32_16x16x32_bf16 v[24:27], v[168:171], v[200:203], v[24:27]
	v_mfma_f32_16x16x32_bf16 v[16:19], v[172:175], v[196:199], v[16:19]
	v_mfma_f32_16x16x32_bf16 v[16:19], v[176:179], v[200:203], v[16:19]
	v_mfma_f32_16x16x32_bf16 v[8:11], v[164:167], v[204:207], v[8:11]
	v_mfma_f32_16x16x32_bf16 v[8:11], v[168:171], v[208:211], v[8:11]
	v_mfma_f32_16x16x32_bf16 v[4:7], v[172:175], v[204:207], v[4:7]
	v_mfma_f32_16x16x32_bf16 v[4:7], v[176:179], v[208:211], v[4:7]
	s_barrier
	s_add_i32 s46, s46, 2
	s_add_u32 s12, s12, 0x100
	s_addc_u32 s13, s13, 0
	s_add_u32 s7, s7, 0x100
	s_addc_u32 s45, s45, 0
	s_cmp_gt_u32 s46, 5
	s_cbranch_scc0 .LBB0_603
	v_readlane_b32 s46, v255, 36
	s_and_b64 vcc, exec, s[4:5]
	v_readlane_b32 s47, v255, 37
	s_cbranch_vccz .LBB0_606
	s_barrier

;     __device__ __forceinline__ int nt(const Unit& u) const { return (u.pn >> 1) < 2 ? 22 : 20; }
; #define PG8_STAGE(bufoff, gbase, voff) do { _Pragma("unroll") for (int _i = 0; _i < 2; ++_i) \
;         __builtin_amdgcn_global_load_lds((const unsigned*)((const char*)(gbase) + (voff)[_i]), (LAS unsigned*)(lds + (bufoff) + ldsw + _i * 8192), 16, 0, 0); } while (0)
; #define PG8_LDA(dst, b, h) do { _Pragma("unroll") for (int m = 0; m < 4; ++m) _Pragma("unroll") for (int k = 0; k < 2; ++k) dst[m][k] = *(const LAS bf16x8*)(pA + PG8_SA(b, h) + m * 2048 + k * 1024); } while (0)
; #define PG8_LDB(dst, b, h) do { _Pragma("unroll") for (int n = 0; n < 2; ++n) _Pragma("unroll") for (int k = 0; k < 2; ++k) dst[n][k] = *(const LAS bf16x8*)(pB + (PG8_SB(b, h) - 4 * HTB) + n * 2048 + k * 1024); } while (0)
; #define PG8_MMA(ai, bj, At, Bt) do { __builtin_amdgcn_s_setprio(1); _Pragma("unroll") for (int m = 0; m < 4; ++m) _Pragma("unroll") for (int n = 0; n < 2; ++n) _Pragma("unroll") for (int k = 0; k < 2; ++k) \
;         acc[ai][bj][m][n] = __builtin_amdgcn_mfma_f32_16x16x32_bf16(Bt[n][k], At[m][k], acc[ai][bj][m][n], 0, 0, 0); __builtin_amdgcn_s_setprio(0); } while (0)
; #define PG8_WAIT_V(n) asm volatile("s_waitcnt vmcnt(" #n ")" ::: "memory")
; #define PG8_BAR __builtin_amdgcn_s_barrier()
; template <class Desc, class Epi, bool ALIGN_EPI>
; __device__ __forceinline__ void gemm_phase(LAS unsigned char* lds, const Desc& D, const Epi& E, int G, int c) {
;     ...
;         for (int t = 0; t < nt; t += 2) {
;             const bool last = (t == nt - 2);
;             if (last && has_next) PG8_AWAIT(nxt);
;             const char* a1 = cA + (size_t)(t + 1) * kstep;
;             const char* a2 = last ? nA : cA + (size_t)(t + 2) * kstep; const char* b2 = last ? nB : cB + (size_t)(t + 2) * kstep;
;             const char* a3 = a2 + kstep; const char* b3 = b2 + kstep;
;             PG8_LDB(B0, 0, 0); PG8_LDB(B1, 0, 1); PG8_SCHED; PG8_LDA(At, 0, 0); PG8_STAGE(PG8_SA(1, 1), a1 + hstepA, voffA);
;             PG8_WAIT_V(8); PG8_WAIT_L(0); PG8_BAR; PG8_MMA(0, 0, At, B0); PG8_MMA(0, 1, At, B1); PG8_BAR; PG8_SCHED;
;             PG8_LDA(At, 0, 1); PG8_STAGE(PG8_SB(0, 0), b2, voffB); PG8_STAGE(PG8_SB(0, 1), b2 + hstepB, voffB); PG8_STAGE(PG8_SA(0, 0), a2, voffA);
;             PG8_WAIT_V(8); PG8_WAIT_L(0); PG8_BAR; PG8_MMA(1, 0, At, B0); PG8_MMA(1, 1, At, B1); PG8_BAR; PG8_SCHED;
.LBB0_1164:
	s_waitcnt lgkmcnt(0)
	ds_read_b128 v[132:135], v229
	ds_read_b128 v[136:139], v229 offset:1024
	ds_read_b128 v[140:143], v229 offset:2048
	ds_read_b128 v[144:147], v229 offset:3072
	ds_read_b128 v[148:151], v229 offset:16384
	ds_read_b128 v[152:155], v229 offset:17408
	ds_read_b128 v[156:159], v229 offset:18432
	ds_read_b128 v[160:163], v229 offset:19456
	s_add_i32 s20, s14, 2
	s_add_u32 s16, s12, 0xfff00080
	s_addc_u32 s17, s13, -1
	s_cmp_eq_u32 s1, s14
	s_cselect_b32 s19, s39, s17
	s_cselect_b32 s18, s38, s16
	s_cselect_b32 s17, s41, s11
	s_cselect_b32 s16, s40, s3
	v_lshl_add_u64 v[208:209], s[12:13], 0, v[204:205]
	s_add_i32 m0, s35, 0xc000
	ds_read_b128 v[164:167], v228
	ds_read_b128 v[168:171], v228 offset:1024
	ds_read_b128 v[172:175], v228 offset:2048
	ds_read_b128 v[176:179], v228 offset:3072
	ds_read_b128 v[180:183], v228 offset:4096
	ds_read_b128 v[184:187], v228 offset:5120
	ds_read_b128 v[188:191], v228 offset:6144
	ds_read_b128 v[192:195], v228 offset:7168
	global_load_lds_dwordx4 v[208:209], off
	v_lshl_add_u64 v[208:209], s[12:13], 0, v[206:207]
	s_add_i32 m0, s35, 0xe000
	s_nop 0
	global_load_lds_dwordx4 v[208:209], off
	s_waitcnt vmcnt(8)
	s_waitcnt lgkmcnt(0)
	s_barrier
	v_mfma_f32_16x16x32_bf16 v[128:131], v[132:135], v[164:167], v[128:131]
	v_mfma_f32_16x16x32_bf16 v[128:131], v[136:139], v[168:171], v[128:131]
	v_mfma_f32_16x16x32_bf16 v[124:127], v[140:143], v[164:167], v[124:127]
	v_mfma_f32_16x16x32_bf16 v[124:127], v[144:147], v[168:171], v[124:127]
	v_mfma_f32_16x16x32_bf16 v[120:123], v[132:135], v[172:175], v[120:123]
	v_mfma_f32_16x16x32_bf16 v[120:123], v[136:139], v[176:179], v[120:123]
	v_mfma_f32_16x16x32_bf16 v[116:119], v[140:143], v[172:175], v[116:119]
	v_mfma_f32_16x16x32_bf16 v[116:119], v[144:147], v[176:179], v[116:119]
	v_mfma_f32_16x16x32_bf16 v[112:115], v[132:135], v[180:183], v[112:115]
	v_mfma_f32_16x16x32_bf16 v[112:115], v[136:139], v[184:187], v[112:115]
	v_mfma_f32_16x16x32_bf16 v[108:111], v[140:143], v[180:183], v[108:111]
	v_mfma_f32_16x16x32_bf16 v[108:111], v[144:147], v[184:187], v[108:111]
	v_mfma_f32_16x16x32_bf16 v[104:107], v[132:135], v[188:191], v[104:107]
	v_mfma_f32_16x16x32_bf16 v[104:107], v[136:139], v[192:195], v[104:107]
	v_mfma_f32_16x16x32_bf16 v[100:103], v[140:143], v[188:191], v[100:103]
	v_mfma_f32_16x16x32_bf16 v[100:103], v[144:147], v[192:195], v[100:103]
	v_mfma_f32_16x16x32_bf16 v[96:99], v[148:151], v[164:167], v[96:99]
	v_mfma_f32_16x16x32_bf16 v[96:99], v[152:155], v[168:171], v[96:99]
	v_mfma_f32_16x16x32_bf16 v[92:95], v[156:159], v[164:167], v[92:95]
	v_mfma_f32_16x16x32_bf16 v[92:95], v[160:163], v[168:171], v[92:95]
	v_mfma_f32_16x16x32_bf16 v[88:91], v[148:151], v[172:175], v[88:91]
	v_mfma_f32_16x16x32_bf16 v[88:91], v[152:155], v[176:179], v[88:91]
	v_mfma_f32_16x16x32_bf16 v[80:83], v[156:159], v[172:175], v[80:83]
	v_mfma_f32_16x16x32_bf16 v[80:83], v[160:163], v[176:179], v[80:83]
	v_mfma_f32_16x16x32_bf16 v[64:67], v[148:151], v[180:183], v[64:67]
	v_mfma_f32_16x16x32_bf16 v[64:67], v[152:155], v[184:187], v[64:67]
	v_mfma_f32_16x16x32_bf16 v[52:55], v[156:159], v[180:183], v[52:55]
	v_mfma_f32_16x16x32_bf16 v[52:55], v[160:163], v[184:187], v[52:55]
	v_mfma_f32_16x16x32_bf16 v[32:35], v[148:151], v[188:191], v[32:35]
	v_mfma_f32_16x16x32_bf16 v[32:35], v[152:155], v[192:195], v[32:35]
	v_mfma_f32_16x16x32_bf16 v[20:23], v[156:159], v[188:191], v[20:23]
	v_mfma_f32_16x16x32_bf16 v[20:23], v[160:163], v[192:195], v[20:23]
	s_barrier
	s_mov_b32 m0, s44
	v_lshl_add_u64 v[208:209], s[16:17], 0, v[198:199]
	s_add_u32 s62, s16, 0x100000
	ds_read_b128 v[164:167], v228 offset:16384
	ds_read_b128 v[168:171], v228 offset:17408
	ds_read_b128 v[172:175], v228 offset:18432
	ds_read_b128 v[176:179], v228 offset:19456
	ds_read_b128 v[180:183], v228 offset:20480
	ds_read_b128 v[184:187], v228 offset:21504
	ds_read_b128 v[188:191], v228 offset:22528
	ds_read_b128 v[192:195], v228 offset:23552
	global_load_lds_dwordx4 v[208:209], off
	v_lshl_add_u64 v[210:211], s[16:17], 0, v[202:203]
	s_mov_b32 m0, s45
	s_addc_u32 s63, s17, 0
	global_load_lds_dwordx4 v[210:211], off
	v_lshl_add_u64 v[212:213], s[62:63], 0, v[198:199]
	s_mov_b32 m0, s46
	v_lshl_add_u64 v[214:215], s[18:19], 0, v[200:201]
	global_load_lds_dwordx4 v[212:213], off
	v_lshl_add_u64 v[212:213], s[62:63], 0, v[202:203]
	s_mov_b32 m0, s47
	s_nop 0
	global_load_lds_dwordx4 v[212:213], off
	v_lshl_add_u64 v[212:213], s[18:19], 0, v[196:197]
	s_mov_b32 m0, s35
	s_nop 0
	global_load_lds_dwordx4 v[212:213], off
	s_mov_b32 m0, s48
	s_nop 0
	global_load_lds_dwordx4 v[214:215], off
	s_waitcnt vmcnt(8)
	s_waitcnt lgkmcnt(0)
	s_barrier
; #define PG8_STAGE(bufoff, gbase, voff) do { _Pragma("unroll") for (int _i = 0; _i < 2; ++_i) \
;         __builtin_amdgcn_global_load_lds((const unsigned*)((const char*)(gbase) + (voff)[_i]), (LAS unsigned*)(lds + (bufoff) + ldsw + _i * 8192), 16, 0, 0); } while (0)
; #define PG8_LDA(dst, b, h) do { _Pragma("unroll") for (int m = 0; m < 4; ++m) _Pragma("unroll") for (int k = 0; k < 2; ++k) dst[m][k] = *(const LAS bf16x8*)(pA + PG8_SA(b, h) + m * 2048 + k * 1024); } while (0)
; #define PG8_LDB(dst, b, h) do { _Pragma("unroll") for (int n = 0; n < 2; ++n) _Pragma("unroll") for (int k = 0; k < 2; ++k) dst[n][k] = *(const LAS bf16x8*)(pB + (PG8_SB(b, h) - 4 * HTB) + n * 2048 + k * 1024); } while (0)
; #define PG8_MMA(ai, bj, At, Bt) do { __builtin_amdgcn_s_setprio(1); _Pragma("unroll") for (int m = 0; m < 4; ++m) _Pragma("unroll") for (int n = 0; n < 2; ++n) _Pragma("unroll") for (int k = 0; k < 2; ++k) \
;         acc[ai][bj][m][n] = __builtin_amdgcn_mfma_f32_16x16x32_bf16(Bt[n][k], At[m][k], acc[ai][bj][m][n], 0, 0, 0); __builtin_amdgcn_s_setprio(0); } while (0)
; #define PG8_WAIT_V(n) asm volatile("s_waitcnt vmcnt(" #n ")" ::: "memory")
; #define PG8_WAIT_L(n) asm volatile("s_waitcnt lgkmcnt(" #n ")" ::: "memory")
; #define PG8_BAR __builtin_amdgcn_s_barrier()
; #define PG8_SCHED __builtin_amdgcn_sched_barrier(0)
; template <class Desc, class Epi, bool ALIGN_EPI>
; __device__ __forceinline__ void gemm_phase(LAS unsigned char* lds, const Desc& D, const Epi& E, int G, int c) {
;     ...
;             PG8_WAIT_V(8); PG8_WAIT_L(0); PG8_BAR; PG8_MMA(1, 0, At, B0); PG8_MMA(1, 1, At, B1); PG8_BAR; PG8_SCHED;
;             PG8_LDB(B0, 1, 0); PG8_LDB(B1, 1, 1); PG8_SCHED; PG8_LDA(At, 1, 0); PG8_STAGE(PG8_SA(0, 1), a2 + hstepA, voffA);
;             PG8_WAIT_V(8); PG8_WAIT_L(0); PG8_BAR; PG8_MMA(0, 0, At, B0); PG8_MMA(0, 1, At, B1); PG8_BAR; PG8_SCHED;
	v_mfma_f32_16x16x32_bf16 v[84:87], v[132:135], v[164:167], v[84:87]
	v_mfma_f32_16x16x32_bf16 v[84:87], v[136:139], v[168:171], v[84:87]
	v_mfma_f32_16x16x32_bf16 v[76:79], v[140:143], v[164:167], v[76:79]
	v_mfma_f32_16x16x32_bf16 v[76:79], v[144:147], v[168:171], v[76:79]
	v_mfma_f32_16x16x32_bf16 v[72:75], v[132:135], v[172:175], v[72:75]
	v_mfma_f32_16x16x32_bf16 v[72:75], v[136:139], v[176:179], v[72:75]
	v_mfma_f32_16x16x32_bf16 v[68:71], v[140:143], v[172:175], v[68:71]
	v_mfma_f32_16x16x32_bf16 v[68:71], v[144:147], v[176:179], v[68:71]
	v_mfma_f32_16x16x32_bf16 v[60:63], v[132:135], v[180:183], v[60:63]
	v_mfma_f32_16x16x32_bf16 v[60:63], v[136:139], v[184:187], v[60:63]
	v_mfma_f32_16x16x32_bf16 v[56:59], v[140:143], v[180:183], v[56:59]
	v_mfma_f32_16x16x32_bf16 v[56:59], v[144:147], v[184:187], v[56:59]
	v_mfma_f32_16x16x32_bf16 v[48:51], v[132:135], v[188:191], v[48:51]
	v_mfma_f32_16x16x32_bf16 v[48:51], v[136:139], v[192:195], v[48:51]
	v_mfma_f32_16x16x32_bf16 v[44:47], v[140:143], v[188:191], v[44:47]
	v_mfma_f32_16x16x32_bf16 v[44:47], v[144:147], v[192:195], v[44:47]
	v_mfma_f32_16x16x32_bf16 v[40:43], v[148:151], v[164:167], v[40:43]
	v_mfma_f32_16x16x32_bf16 v[40:43], v[152:155], v[168:171], v[40:43]
	v_mfma_f32_16x16x32_bf16 v[36:39], v[156:159], v[164:167], v[36:39]
	v_mfma_f32_16x16x32_bf16 v[36:39], v[160:163], v[168:171], v[36:39]
	v_mfma_f32_16x16x32_bf16 v[28:31], v[148:151], v[172:175], v[28:31]
	v_mfma_f32_16x16x32_bf16 v[28:31], v[152:155], v[176:179], v[28:31]
	v_mfma_f32_16x16x32_bf16 v[24:27], v[156:159], v[172:175], v[24:27]
	v_mfma_f32_16x16x32_bf16 v[24:27], v[160:163], v[176:179], v[24:27]
	v_mfma_f32_16x16x32_bf16 v[16:19], v[148:151], v[180:183], v[16:19]
	v_mfma_f32_16x16x32_bf16 v[16:19], v[152:155], v[184:187], v[16:19]
	v_mfma_f32_16x16x32_bf16 v[12:15], v[156:159], v[180:183], v[12:15]
	v_mfma_f32_16x16x32_bf16 v[12:15], v[160:163], v[184:187], v[12:15]
	v_mfma_f32_16x16x32_bf16 v[8:11], v[148:151], v[188:191], v[8:11]
	v_mfma_f32_16x16x32_bf16 v[8:11], v[152:155], v[192:195], v[8:11]
	v_mfma_f32_16x16x32_bf16 v[4:7], v[156:159], v[188:191], v[4:7]
	v_mfma_f32_16x16x32_bf16 v[4:7], v[160:163], v[192:195], v[4:7]
	s_barrier
	ds_read_b128 v[132:135], v229 offset:32768
	ds_read_b128 v[136:139], v229 offset:33792
	ds_read_b128 v[140:143], v229 offset:34816
	ds_read_b128 v[144:147], v229 offset:35840
	ds_read_b128 v[148:151], v229 offset:49152
	ds_read_b128 v[152:155], v229 offset:50176
	ds_read_b128 v[156:159], v229 offset:51200
	ds_read_b128 v[160:163], v229 offset:52224
	s_add_u32 s18, s18, 0x100000
	s_addc_u32 s19, s19, 0
	s_mov_b32 m0, s49
	v_lshl_add_u64 v[216:217], s[18:19], 0, v[196:197]
	ds_read_b128 v[164:167], v228 offset:32768
	ds_read_b128 v[168:171], v228 offset:33792
	ds_read_b128 v[172:175], v228 offset:34816
	ds_read_b128 v[176:179], v228 offset:35840
	ds_read_b128 v[180:183], v228 offset:36864
	ds_read_b128 v[184:187], v228 offset:37888
	ds_read_b128 v[188:191], v228 offset:38912
	ds_read_b128 v[192:195], v228 offset:39936
	global_load_lds_dwordx4 v[216:217], off
	v_lshl_add_u64 v[216:217], s[18:19], 0, v[200:201]
	s_mov_b32 m0, s50
	s_nop 0
	global_load_lds_dwordx4 v[216:217], off
	s_waitcnt vmcnt(8)
	s_waitcnt lgkmcnt(0)
	s_barrier
	v_mfma_f32_16x16x32_bf16 v[128:131], v[132:135], v[164:167], v[128:131]
	v_mfma_f32_16x16x32_bf16 v[128:131], v[136:139], v[168:171], v[128:131]
	v_mfma_f32_16x16x32_bf16 v[124:127], v[140:143], v[164:167], v[124:127]
	v_mfma_f32_16x16x32_bf16 v[124:127], v[144:147], v[168:171], v[124:127]
	v_mfma_f32_16x16x32_bf16 v[120:123], v[132:135], v[172:175], v[120:123]
	v_mfma_f32_16x16x32_bf16 v[120:123], v[136:139], v[176:179], v[120:123]
	v_mfma_f32_16x16x32_bf16 v[116:119], v[140:143], v[172:175], v[116:119]
	v_mfma_f32_16x16x32_bf16 v[116:119], v[144:147], v[176:179], v[116:119]
	v_mfma_f32_16x16x32_bf16 v[112:115], v[132:135], v[180:183], v[112:115]
	v_mfma_f32_16x16x32_bf16 v[112:115], v[136:139], v[184:187], v[112:115]
	v_mfma_f32_16x16x32_bf16 v[108:111], v[140:143], v[180:183], v[108:111]
	v_mfma_f32_16x16x32_bf16 v[108:111], v[144:147], v[184:187], v[108:111]
	v_mfma_f32_16x16x32_bf16 v[104:107], v[132:135], v[188:191], v[104:107]
	v_mfma_f32_16x16x32_bf16 v[104:107], v[136:139], v[192:195], v[104:107]
	v_mfma_f32_16x16x32_bf16 v[100:103], v[140:143], v[188:191], v[100:103]
	v_mfma_f32_16x16x32_bf16 v[100:103], v[144:147], v[192:195], v[100:103]
	v_mfma_f32_16x16x32_bf16 v[96:99], v[148:151], v[164:167], v[96:99]
	v_mfma_f32_16x16x32_bf16 v[96:99], v[152:155], v[168:171], v[96:99]
	v_mfma_f32_16x16x32_bf16 v[92:95], v[156:159], v[164:167], v[92:95]
	v_mfma_f32_16x16x32_bf16 v[92:95], v[160:163], v[168:171], v[92:95]
	v_mfma_f32_16x16x32_bf16 v[88:91], v[148:151], v[172:175], v[88:91]
	v_mfma_f32_16x16x32_bf16 v[88:91], v[152:155], v[176:179], v[88:91]
	v_mfma_f32_16x16x32_bf16 v[80:83], v[156:159], v[172:175], v[80:83]
	v_mfma_f32_16x16x32_bf16 v[80:83], v[160:163], v[176:179], v[80:83]
	v_mfma_f32_16x16x32_bf16 v[64:67], v[148:151], v[180:183], v[64:67]
	v_mfma_f32_16x16x32_bf16 v[64:67], v[152:155], v[184:187], v[64:67]
	v_mfma_f32_16x16x32_bf16 v[52:55], v[156:159], v[180:183], v[52:55]
	v_mfma_f32_16x16x32_bf16 v[52:55], v[160:163], v[184:187], v[52:55]
	v_mfma_f32_16x16x32_bf16 v[32:35], v[148:151], v[188:191], v[32:35]
	v_mfma_f32_16x16x32_bf16 v[32:35], v[152:155], v[192:195], v[32:35]
	v_mfma_f32_16x16x32_bf16 v[20:23], v[156:159], v[188:191], v[20:23]
	v_mfma_f32_16x16x32_bf16 v[20:23], v[160:163], v[192:195], v[20:23]
	s_barrier
; #define PG8_STAGE(bufoff, gbase, voff) do { _Pragma("unroll") for (int _i = 0; _i < 2; ++_i) \
;         __builtin_amdgcn_global_load_lds((const unsigned*)((const char*)(gbase) + (voff)[_i]), (LAS unsigned*)(lds + (bufoff) + ldsw + _i * 8192), 16, 0, 0); } while (0)
; #define PG8_LDA(dst, b, h) do { _Pragma("unroll") for (int m = 0; m < 4; ++m) _Pragma("unroll") for (int k = 0; k < 2; ++k) dst[m][k] = *(const LAS bf16x8*)(pA + PG8_SA(b, h) + m * 2048 + k * 1024); } while (0)
; #define PG8_MMA(ai, bj, At, Bt) do { __builtin_amdgcn_s_setprio(1); _Pragma("unroll") for (int m = 0; m < 4; ++m) _Pragma("unroll") for (int n = 0; n < 2; ++n) _Pragma("unroll") for (int k = 0; k < 2; ++k) \
;         acc[ai][bj][m][n] = __builtin_amdgcn_mfma_f32_16x16x32_bf16(Bt[n][k], At[m][k], acc[ai][bj][m][n], 0, 0, 0); __builtin_amdgcn_s_setprio(0); } while (0)
; #define PG8_WAIT_V(n) asm volatile("s_waitcnt vmcnt(" #n ")" ::: "memory")
; #define PG8_WAIT_L(n) asm volatile("s_waitcnt lgkmcnt(" #n ")" ::: "memory")
; #define PG8_BAR __builtin_amdgcn_s_barrier()
; #define PG8_SCHED __builtin_amdgcn_sched_barrier(0)
; template <class Desc, class Epi, bool ALIGN_EPI>
; __device__ __forceinline__ void gemm_phase(LAS unsigned char* lds, const Desc& D, const Epi& E, int G, int c) {
;     ...
;             PG8_LDA(At, 1, 1); PG8_STAGE(PG8_SB(1, 0), b3, voffB); PG8_STAGE(PG8_SB(1, 1), b3 + hstepB, voffB); PG8_STAGE(PG8_SA(1, 0), a3, voffA);
;             PG8_WAIT_V(8); PG8_WAIT_L(0); PG8_BAR; PG8_MMA(1, 0, At, B0); PG8_MMA(1, 1, At, B1); PG8_BAR; PG8_SCHED;
;         }
;         if constexpr (ALIGN_EPI) { if (wr == 0) PG8_BAR; }
	s_mov_b32 m0, s52
	v_lshl_add_u64 v[208:209], v[208:209], 0, s[76:77]
	s_add_u32 s16, s16, 0x100080
	ds_read_b128 v[164:167], v228 offset:49152
	ds_read_b128 v[168:171], v228 offset:50176
	ds_read_b128 v[172:175], v228 offset:51200
	ds_read_b128 v[176:179], v228 offset:52224
	ds_read_b128 v[180:183], v228 offset:53248
	ds_read_b128 v[184:187], v228 offset:54272
	ds_read_b128 v[188:191], v228 offset:55296
	ds_read_b128 v[192:195], v228 offset:56320
	global_load_lds_dwordx4 v[208:209], off
	v_lshl_add_u64 v[208:209], v[210:211], 0, s[76:77]
	s_mov_b32 m0, s53
	s_addc_u32 s17, s17, 0
	global_load_lds_dwordx4 v[208:209], off
	v_lshl_add_u64 v[208:209], s[16:17], 0, v[198:199]
	s_mov_b32 m0, s56
	s_nop 0
	global_load_lds_dwordx4 v[208:209], off
	v_lshl_add_u64 v[208:209], s[16:17], 0, v[202:203]
	s_mov_b32 m0, s57
	s_nop 0
	global_load_lds_dwordx4 v[208:209], off
	v_lshl_add_u64 v[208:209], v[212:213], 0, s[76:77]
	s_mov_b32 m0, s54
	s_nop 0
	global_load_lds_dwordx4 v[208:209], off
	v_lshl_add_u64 v[208:209], v[214:215], 0, s[76:77]
	s_mov_b32 m0, s55
	s_nop 0
	global_load_lds_dwordx4 v[208:209], off
	s_waitcnt vmcnt(8)
	s_waitcnt lgkmcnt(0)
	s_barrier
	v_mfma_f32_16x16x32_bf16 v[84:87], v[132:135], v[164:167], v[84:87]
	v_mfma_f32_16x16x32_bf16 v[84:87], v[136:139], v[168:171], v[84:87]
	v_mfma_f32_16x16x32_bf16 v[76:79], v[140:143], v[164:167], v[76:79]
	v_mfma_f32_16x16x32_bf16 v[76:79], v[144:147], v[168:171], v[76:79]
	v_mfma_f32_16x16x32_bf16 v[72:75], v[132:135], v[172:175], v[72:75]
	v_mfma_f32_16x16x32_bf16 v[72:75], v[136:139], v[176:179], v[72:75]
	v_mfma_f32_16x16x32_bf16 v[68:71], v[140:143], v[172:175], v[68:71]
	v_mfma_f32_16x16x32_bf16 v[68:71], v[144:147], v[176:179], v[68:71]
	v_mfma_f32_16x16x32_bf16 v[60:63], v[132:135], v[180:183], v[60:63]
	v_mfma_f32_16x16x32_bf16 v[60:63], v[136:139], v[184:187], v[60:63]
	v_mfma_f32_16x16x32_bf16 v[56:59], v[140:143], v[180:183], v[56:59]
	v_mfma_f32_16x16x32_bf16 v[56:59], v[144:147], v[184:187], v[56:59]
	v_mfma_f32_16x16x32_bf16 v[48:51], v[132:135], v[188:191], v[48:51]
	v_mfma_f32_16x16x32_bf16 v[48:51], v[136:139], v[192:195], v[48:51]
	v_mfma_f32_16x16x32_bf16 v[44:47], v[140:143], v[188:191], v[44:47]
	v_mfma_f32_16x16x32_bf16 v[44:47], v[144:147], v[192:195], v[44:47]
	v_mfma_f32_16x16x32_bf16 v[40:43], v[148:151], v[164:167], v[40:43]
	v_mfma_f32_16x16x32_bf16 v[40:43], v[152:155], v[168:171], v[40:43]
	v_mfma_f32_16x16x32_bf16 v[36:39], v[156:159], v[164:167], v[36:39]
	v_mfma_f32_16x16x32_bf16 v[36:39], v[160:163], v[168:171], v[36:39]
	v_mfma_f32_16x16x32_bf16 v[28:31], v[148:151], v[172:175], v[28:31]
	v_mfma_f32_16x16x32_bf16 v[28:31], v[152:155], v[176:179], v[28:31]
	v_mfma_f32_16x16x32_bf16 v[24:27], v[156:159], v[172:175], v[24:27]
	v_mfma_f32_16x16x32_bf16 v[24:27], v[160:163], v[176:179], v[24:27]
	v_mfma_f32_16x16x32_bf16 v[16:19], v[148:151], v[180:183], v[16:19]
	v_mfma_f32_16x16x32_bf16 v[16:19], v[152:155], v[184:187], v[16:19]
	v_mfma_f32_16x16x32_bf16 v[12:15], v[156:159], v[180:183], v[12:15]
	v_mfma_f32_16x16x32_bf16 v[12:15], v[160:163], v[184:187], v[12:15]
	v_mfma_f32_16x16x32_bf16 v[8:11], v[148:151], v[188:191], v[8:11]
	v_mfma_f32_16x16x32_bf16 v[8:11], v[152:155], v[192:195], v[8:11]
	v_mfma_f32_16x16x32_bf16 v[4:7], v[156:159], v[188:191], v[4:7]
	v_mfma_f32_16x16x32_bf16 v[4:7], v[160:163], v[192:195], v[4:7]
	s_barrier
	s_add_u32 s12, s12, 0x100
	s_addc_u32 s13, s13, 0
	s_add_u32 s3, s3, 0x100
	s_addc_u32 s11, s11, 0
	s_cmp_ge_u32 s20, s2
	s_mov_b32 s14, s20
	s_cbranch_scc0 .LBB0_1164
	s_and_b64 vcc, exec, s[8:9]
	s_cbranch_vccz .LBB0_1167
	s_barrier

;     __device__ __forceinline__ int nt(const Unit& u) const { return (u.pn >> 1) < 2 ? 22 : 20; }
; #define PG8_STAGE(bufoff, gbase, voff) do { _Pragma("unroll") for (int _i = 0; _i < 2; ++_i) \
;         __builtin_amdgcn_global_load_lds((const unsigned*)((const char*)(gbase) + (voff)[_i]), (LAS unsigned*)(lds + (bufoff) + ldsw + _i * 8192), 16, 0, 0); } while (0)
; #define PG8_LDA(dst, b, h) do { _Pragma("unroll") for (int m = 0; m < 4; ++m) _Pragma("unroll") for (int k = 0; k < 2; ++k) dst[m][k] = *(const LAS bf16x8*)(pA + PG8_SA(b, h) + m * 2048 + k * 1024); } while (0)
; #define PG8_LDB(dst, b, h) do { _Pragma("unroll") for (int n = 0; n < 2; ++n) _Pragma("unroll") for (int k = 0; k < 2; ++k) dst[n][k] = *(const LAS bf16x8*)(pB + (PG8_SB(b, h) - 4 * HTB) + n * 2048 + k * 1024); } while (0)
; #define PG8_MMA(ai, bj, At, Bt) do { __builtin_amdgcn_s_setprio(1); _Pragma("unroll") for (int m = 0; m < 4; ++m) _Pragma("unroll") for (int n = 0; n < 2; ++n) _Pragma("unroll") for (int k = 0; k < 2; ++k) \
;         acc[ai][bj][m][n] = __builtin_amdgcn_mfma_f32_16x16x32_bf16(Bt[n][k], At[m][k], acc[ai][bj][m][n], 0, 0, 0); __builtin_amdgcn_s_setprio(0); } while (0)
; #define PG8_WAIT_V(n) asm volatile("s_waitcnt vmcnt(" #n ")" ::: "memory")
; #define PG8_BAR __builtin_amdgcn_s_barrier()
; template <class Desc, class Epi, bool ALIGN_EPI>
; __device__ __forceinline__ void gemm_phase(LAS unsigned char* lds, const Desc& D, const Epi& E, int G, int c) {
;     ...
;         for (int t = 0; t < nt; t += 2) {
;             const bool last = (t == nt - 2);
;             if (last && has_next) PG8_AWAIT(nxt);
;             const char* a1 = cA + (size_t)(t + 1) * kstep;
;             const char* a2 = last ? nA : cA + (size_t)(t + 2) * kstep; const char* b2 = last ? nB : cB + (size_t)(t + 2) * kstep;
;             const char* a3 = a2 + kstep; const char* b3 = b2 + kstep;
;             PG8_LDB(B0, 0, 0); PG8_LDB(B1, 0, 1); PG8_SCHED; PG8_LDA(At, 0, 0); PG8_STAGE(PG8_SA(1, 1), a1 + hstepA, voffA);
;             PG8_WAIT_V(8); PG8_WAIT_L(0); PG8_BAR; PG8_MMA(0, 0, At, B0); PG8_MMA(0, 1, At, B1); PG8_BAR; PG8_SCHED;
;             PG8_LDA(At, 0, 1); PG8_STAGE(PG8_SB(0, 0), b2, voffB); PG8_STAGE(PG8_SB(0, 1), b2 + hstepB, voffB); PG8_STAGE(PG8_SA(0, 0), a2, voffA);
;             PG8_WAIT_V(8); PG8_WAIT_L(0); PG8_BAR; PG8_MMA(1, 0, At, B0); PG8_MMA(1, 1, At, B1); PG8_BAR; PG8_SCHED;
.LBB0_1324:
	ds_read_b128 v[144:147], v149
	ds_read_b128 v[152:155], v149 offset:1024
	ds_read_b128 v[156:159], v149 offset:2048
	ds_read_b128 v[160:163], v149 offset:3072
	ds_read_b128 v[164:167], v149 offset:16384
	ds_read_b128 v[168:171], v149 offset:17408
	ds_read_b128 v[172:175], v149 offset:18432
	ds_read_b128 v[176:179], v149 offset:19456
	s_add_i32 s50, s18, 2
	s_add_u32 s19, s16, 0xfff00080
	s_addc_u32 s20, s17, -1
	s_cmp_eq_u32 s9, s18
	s_cselect_b32 s18, s12, s48
	s_cselect_b32 s21, s11, s20
	s_cselect_b32 s20, s10, s19
	s_cselect_b32 s19, s13, s49
	v_lshl_add_u64 v[212:213], s[16:17], 0, v[140:141]
	s_add_i32 m0, s24, 0xc000
	ds_read_b128 v[180:183], v148
	ds_read_b128 v[184:187], v148 offset:1024
	ds_read_b128 v[188:191], v148 offset:2048
	ds_read_b128 v[192:195], v148 offset:3072
	ds_read_b128 v[196:199], v148 offset:4096
	ds_read_b128 v[200:203], v148 offset:5120
	ds_read_b128 v[204:207], v148 offset:6144
	ds_read_b128 v[208:211], v148 offset:7168
	global_load_lds_dwordx4 v[212:213], off
	v_lshl_add_u64 v[212:213], s[16:17], 0, v[142:143]
	s_add_i32 m0, s24, 0xe000
	s_nop 0
	global_load_lds_dwordx4 v[212:213], off
	s_waitcnt vmcnt(8)
	s_waitcnt lgkmcnt(0)
	s_barrier
	v_mfma_f32_16x16x32_bf16 v[128:131], v[144:147], v[180:183], v[128:131]
	v_mfma_f32_16x16x32_bf16 v[128:131], v[152:155], v[184:187], v[128:131]
	v_mfma_f32_16x16x32_bf16 v[124:127], v[156:159], v[180:183], v[124:127]
	v_mfma_f32_16x16x32_bf16 v[124:127], v[160:163], v[184:187], v[124:127]
	v_mfma_f32_16x16x32_bf16 v[120:123], v[144:147], v[188:191], v[120:123]
	v_mfma_f32_16x16x32_bf16 v[120:123], v[152:155], v[192:195], v[120:123]
	v_mfma_f32_16x16x32_bf16 v[112:115], v[156:159], v[188:191], v[112:115]
	v_mfma_f32_16x16x32_bf16 v[112:115], v[160:163], v[192:195], v[112:115]
	v_mfma_f32_16x16x32_bf16 v[104:107], v[144:147], v[196:199], v[104:107]
	v_mfma_f32_16x16x32_bf16 v[104:107], v[152:155], v[200:203], v[104:107]
	v_mfma_f32_16x16x32_bf16 v[96:99], v[156:159], v[196:199], v[96:99]
	v_mfma_f32_16x16x32_bf16 v[96:99], v[160:163], v[200:203], v[96:99]
	v_mfma_f32_16x16x32_bf16 v[88:91], v[144:147], v[204:207], v[88:91]
	v_mfma_f32_16x16x32_bf16 v[88:91], v[152:155], v[208:211], v[88:91]
	v_mfma_f32_16x16x32_bf16 v[80:83], v[156:159], v[204:207], v[80:83]
	v_mfma_f32_16x16x32_bf16 v[80:83], v[160:163], v[208:211], v[80:83]
	v_mfma_f32_16x16x32_bf16 v[116:119], v[164:167], v[180:183], v[116:119]
	v_mfma_f32_16x16x32_bf16 v[116:119], v[168:171], v[184:187], v[116:119]
	v_mfma_f32_16x16x32_bf16 v[108:111], v[172:175], v[180:183], v[108:111]
	v_mfma_f32_16x16x32_bf16 v[108:111], v[176:179], v[184:187], v[108:111]
	v_mfma_f32_16x16x32_bf16 v[100:103], v[164:167], v[188:191], v[100:103]
	v_mfma_f32_16x16x32_bf16 v[100:103], v[168:171], v[192:195], v[100:103]
	v_mfma_f32_16x16x32_bf16 v[92:95], v[172:175], v[188:191], v[92:95]
	v_mfma_f32_16x16x32_bf16 v[92:95], v[176:179], v[192:195], v[92:95]
	v_mfma_f32_16x16x32_bf16 v[84:87], v[164:167], v[196:199], v[84:87]
	v_mfma_f32_16x16x32_bf16 v[84:87], v[168:171], v[200:203], v[84:87]
	v_mfma_f32_16x16x32_bf16 v[76:79], v[172:175], v[196:199], v[76:79]
	v_mfma_f32_16x16x32_bf16 v[76:79], v[176:179], v[200:203], v[76:79]
	v_mfma_f32_16x16x32_bf16 v[72:75], v[164:167], v[204:207], v[72:75]
	v_mfma_f32_16x16x32_bf16 v[72:75], v[168:171], v[208:211], v[72:75]
	v_mfma_f32_16x16x32_bf16 v[68:71], v[172:175], v[204:207], v[68:71]
	v_mfma_f32_16x16x32_bf16 v[68:71], v[176:179], v[208:211], v[68:71]
	s_barrier
	s_mov_b32 m0, s25
	v_lshl_add_u64 v[212:213], s[18:19], 0, v[136:137]
	s_add_u32 s52, s18, 0x100000
	ds_read_b128 v[180:183], v148 offset:16384
	ds_read_b128 v[184:187], v148 offset:17408
	ds_read_b128 v[188:191], v148 offset:18432
	ds_read_b128 v[192:195], v148 offset:19456
	ds_read_b128 v[196:199], v148 offset:20480
	ds_read_b128 v[200:203], v148 offset:21504
	ds_read_b128 v[204:207], v148 offset:22528
	ds_read_b128 v[208:211], v148 offset:23552
	global_load_lds_dwordx4 v[212:213], off
	v_lshl_add_u64 v[214:215], s[18:19], 0, v[132:133]
	s_mov_b32 m0, s26
	s_addc_u32 s53, s19, 0
	global_load_lds_dwordx4 v[214:215], off
	v_lshl_add_u64 v[216:217], s[52:53], 0, v[136:137]
	s_mov_b32 m0, s27
	v_lshl_add_u64 v[218:219], s[20:21], 0, v[134:135]
	global_load_lds_dwordx4 v[216:217], off
	v_lshl_add_u64 v[216:217], s[52:53], 0, v[132:133]
	s_mov_b32 m0, s30
	s_nop 0
	global_load_lds_dwordx4 v[216:217], off
	v_lshl_add_u64 v[216:217], s[20:21], 0, v[138:139]
	s_mov_b32 m0, s24
	s_nop 0
	global_load_lds_dwordx4 v[216:217], off
	s_mov_b32 m0, s31
	s_nop 0
	global_load_lds_dwordx4 v[218:219], off
	s_waitcnt vmcnt(8)
	s_waitcnt lgkmcnt(0)
	s_barrier
; #define PG8_STAGE(bufoff, gbase, voff) do { _Pragma("unroll") for (int _i = 0; _i < 2; ++_i) \
;         __builtin_amdgcn_global_load_lds((const unsigned*)((const char*)(gbase) + (voff)[_i]), (LAS unsigned*)(lds + (bufoff) + ldsw + _i * 8192), 16, 0, 0); } while (0)
; #define PG8_LDA(dst, b, h) do { _Pragma("unroll") for (int m = 0; m < 4; ++m) _Pragma("unroll") for (int k = 0; k < 2; ++k) dst[m][k] = *(const LAS bf16x8*)(pA + PG8_SA(b, h) + m * 2048 + k * 1024); } while (0)
; #define PG8_LDB(dst, b, h) do { _Pragma("unroll") for (int n = 0; n < 2; ++n) _Pragma("unroll") for (int k = 0; k < 2; ++k) dst[n][k] = *(const LAS bf16x8*)(pB + (PG8_SB(b, h) - 4 * HTB) + n * 2048 + k * 1024); } while (0)
; #define PG8_MMA(ai, bj, At, Bt) do { __builtin_amdgcn_s_setprio(1); _Pragma("unroll") for (int m = 0; m < 4; ++m) _Pragma("unroll") for (int n = 0; n < 2; ++n) _Pragma("unroll") for (int k = 0; k < 2; ++k) \
;         acc[ai][bj][m][n] = __builtin_amdgcn_mfma_f32_16x16x32_bf16(Bt[n][k], At[m][k], acc[ai][bj][m][n], 0, 0, 0); __builtin_amdgcn_s_setprio(0); } while (0)
; #define PG8_WAIT_V(n) asm volatile("s_waitcnt vmcnt(" #n ")" ::: "memory")
; #define PG8_WAIT_L(n) asm volatile("s_waitcnt lgkmcnt(" #n ")" ::: "memory")
; #define PG8_BAR __builtin_amdgcn_s_barrier()
; #define PG8_SCHED __builtin_amdgcn_sched_barrier(0)
; template <class Desc, class Epi, bool ALIGN_EPI>
; __device__ __forceinline__ void gemm_phase(LAS unsigned char* lds, const Desc& D, const Epi& E, int G, int c) {
;     ...
;             PG8_WAIT_V(8); PG8_WAIT_L(0); PG8_BAR; PG8_MMA(1, 0, At, B0); PG8_MMA(1, 1, At, B1); PG8_BAR; PG8_SCHED;
;             PG8_LDB(B0, 1, 0); PG8_LDB(B1, 1, 1); PG8_SCHED; PG8_LDA(At, 1, 0); PG8_STAGE(PG8_SA(0, 1), a2 + hstepA, voffA);
;             PG8_WAIT_V(8); PG8_WAIT_L(0); PG8_BAR; PG8_MMA(0, 0, At, B0); PG8_MMA(0, 1, At, B1); PG8_BAR; PG8_SCHED;
	v_mfma_f32_16x16x32_bf16 v[64:67], v[144:147], v[180:183], v[64:67]
	v_mfma_f32_16x16x32_bf16 v[64:67], v[152:155], v[184:187], v[64:67]
	v_mfma_f32_16x16x32_bf16 v[60:63], v[156:159], v[180:183], v[60:63]
	v_mfma_f32_16x16x32_bf16 v[60:63], v[160:163], v[184:187], v[60:63]
	v_mfma_f32_16x16x32_bf16 v[56:59], v[144:147], v[188:191], v[56:59]
	v_mfma_f32_16x16x32_bf16 v[56:59], v[152:155], v[192:195], v[56:59]
	v_mfma_f32_16x16x32_bf16 v[48:51], v[156:159], v[188:191], v[48:51]
	v_mfma_f32_16x16x32_bf16 v[48:51], v[160:163], v[192:195], v[48:51]
	v_mfma_f32_16x16x32_bf16 v[40:43], v[144:147], v[196:199], v[40:43]
	v_mfma_f32_16x16x32_bf16 v[40:43], v[152:155], v[200:203], v[40:43]
	v_mfma_f32_16x16x32_bf16 v[32:35], v[156:159], v[196:199], v[32:35]
	v_mfma_f32_16x16x32_bf16 v[32:35], v[160:163], v[200:203], v[32:35]
	v_mfma_f32_16x16x32_bf16 v[24:27], v[144:147], v[204:207], v[24:27]
	v_mfma_f32_16x16x32_bf16 v[24:27], v[152:155], v[208:211], v[24:27]
	v_mfma_f32_16x16x32_bf16 v[16:19], v[156:159], v[204:207], v[16:19]
	v_mfma_f32_16x16x32_bf16 v[16:19], v[160:163], v[208:211], v[16:19]
	v_mfma_f32_16x16x32_bf16 v[52:55], v[164:167], v[180:183], v[52:55]
	v_mfma_f32_16x16x32_bf16 v[52:55], v[168:171], v[184:187], v[52:55]
	v_mfma_f32_16x16x32_bf16 v[44:47], v[172:175], v[180:183], v[44:47]
	v_mfma_f32_16x16x32_bf16 v[44:47], v[176:179], v[184:187], v[44:47]
	v_mfma_f32_16x16x32_bf16 v[36:39], v[164:167], v[188:191], v[36:39]
	v_mfma_f32_16x16x32_bf16 v[36:39], v[168:171], v[192:195], v[36:39]
	v_mfma_f32_16x16x32_bf16 v[28:31], v[172:175], v[188:191], v[28:31]
	v_mfma_f32_16x16x32_bf16 v[28:31], v[176:179], v[192:195], v[28:31]
	v_mfma_f32_16x16x32_bf16 v[20:23], v[164:167], v[196:199], v[20:23]
	v_mfma_f32_16x16x32_bf16 v[20:23], v[168:171], v[200:203], v[20:23]
	v_mfma_f32_16x16x32_bf16 v[12:15], v[172:175], v[196:199], v[12:15]
	v_mfma_f32_16x16x32_bf16 v[12:15], v[176:179], v[200:203], v[12:15]
	v_mfma_f32_16x16x32_bf16 v[8:11], v[164:167], v[204:207], v[8:11]
	v_mfma_f32_16x16x32_bf16 v[8:11], v[168:171], v[208:211], v[8:11]
	v_mfma_f32_16x16x32_bf16 v[4:7], v[172:175], v[204:207], v[4:7]
	v_mfma_f32_16x16x32_bf16 v[4:7], v[176:179], v[208:211], v[4:7]
	s_barrier
	ds_read_b128 v[144:147], v149 offset:32768
	ds_read_b128 v[152:155], v149 offset:33792
	ds_read_b128 v[156:159], v149 offset:34816
	ds_read_b128 v[160:163], v149 offset:35840
	ds_read_b128 v[164:167], v149 offset:49152
	ds_read_b128 v[168:171], v149 offset:50176
	ds_read_b128 v[172:175], v149 offset:51200
	ds_read_b128 v[176:179], v149 offset:52224
	s_add_u32 s20, s20, 0x100000
	s_addc_u32 s21, s21, 0
	s_mov_b32 m0, s33
	v_lshl_add_u64 v[220:221], s[20:21], 0, v[138:139]
	ds_read_b128 v[180:183], v148 offset:32768
	ds_read_b128 v[184:187], v148 offset:33792
	ds_read_b128 v[188:191], v148 offset:34816
	ds_read_b128 v[192:195], v148 offset:35840
	ds_read_b128 v[196:199], v148 offset:36864
	ds_read_b128 v[200:203], v148 offset:37888
	ds_read_b128 v[204:207], v148 offset:38912
	ds_read_b128 v[208:211], v148 offset:39936
	global_load_lds_dwordx4 v[220:221], off
	v_lshl_add_u64 v[220:221], s[20:21], 0, v[134:135]
	s_mov_b32 m0, s34
	s_nop 0
	global_load_lds_dwordx4 v[220:221], off
	s_waitcnt vmcnt(8)
	s_waitcnt lgkmcnt(0)
	s_barrier
	v_mfma_f32_16x16x32_bf16 v[128:131], v[144:147], v[180:183], v[128:131]
	v_mfma_f32_16x16x32_bf16 v[128:131], v[152:155], v[184:187], v[128:131]
	v_mfma_f32_16x16x32_bf16 v[124:127], v[156:159], v[180:183], v[124:127]
	v_mfma_f32_16x16x32_bf16 v[124:127], v[160:163], v[184:187], v[124:127]
	v_mfma_f32_16x16x32_bf16 v[120:123], v[144:147], v[188:191], v[120:123]
	v_mfma_f32_16x16x32_bf16 v[120:123], v[152:155], v[192:195], v[120:123]
	v_mfma_f32_16x16x32_bf16 v[112:115], v[156:159], v[188:191], v[112:115]
	v_mfma_f32_16x16x32_bf16 v[112:115], v[160:163], v[192:195], v[112:115]
	v_mfma_f32_16x16x32_bf16 v[104:107], v[144:147], v[196:199], v[104:107]
	v_mfma_f32_16x16x32_bf16 v[104:107], v[152:155], v[200:203], v[104:107]
	v_mfma_f32_16x16x32_bf16 v[96:99], v[156:159], v[196:199], v[96:99]
	v_mfma_f32_16x16x32_bf16 v[96:99], v[160:163], v[200:203], v[96:99]
	v_mfma_f32_16x16x32_bf16 v[88:91], v[144:147], v[204:207], v[88:91]
	v_mfma_f32_16x16x32_bf16 v[88:91], v[152:155], v[208:211], v[88:91]
	v_mfma_f32_16x16x32_bf16 v[80:83], v[156:159], v[204:207], v[80:83]
	v_mfma_f32_16x16x32_bf16 v[80:83], v[160:163], v[208:211], v[80:83]
	v_mfma_f32_16x16x32_bf16 v[116:119], v[164:167], v[180:183], v[116:119]
	v_mfma_f32_16x16x32_bf16 v[116:119], v[168:171], v[184:187], v[116:119]
	v_mfma_f32_16x16x32_bf16 v[108:111], v[172:175], v[180:183], v[108:111]
	v_mfma_f32_16x16x32_bf16 v[108:111], v[176:179], v[184:187], v[108:111]
	v_mfma_f32_16x16x32_bf16 v[100:103], v[164:167], v[188:191], v[100:103]
	v_mfma_f32_16x16x32_bf16 v[100:103], v[168:171], v[192:195], v[100:103]
	v_mfma_f32_16x16x32_bf16 v[92:95], v[172:175], v[188:191], v[92:95]
	v_mfma_f32_16x16x32_bf16 v[92:95], v[176:179], v[192:195], v[92:95]
	v_mfma_f32_16x16x32_bf16 v[84:87], v[164:167], v[196:199], v[84:87]
	v_mfma_f32_16x16x32_bf16 v[84:87], v[168:171], v[200:203], v[84:87]
	v_mfma_f32_16x16x32_bf16 v[76:79], v[172:175], v[196:199], v[76:79]
	v_mfma_f32_16x16x32_bf16 v[76:79], v[176:179], v[200:203], v[76:79]
	v_mfma_f32_16x16x32_bf16 v[72:75], v[164:167], v[204:207], v[72:75]
	v_mfma_f32_16x16x32_bf16 v[72:75], v[168:171], v[208:211], v[72:75]
	v_mfma_f32_16x16x32_bf16 v[68:71], v[172:175], v[204:207], v[68:71]
	v_mfma_f32_16x16x32_bf16 v[68:71], v[176:179], v[208:211], v[68:71]
	s_barrier
; #define PG8_STAGE(bufoff, gbase, voff) do { _Pragma("unroll") for (int _i = 0; _i < 2; ++_i) \
;         __builtin_amdgcn_global_load_lds((const unsigned*)((const char*)(gbase) + (voff)[_i]), (LAS unsigned*)(lds + (bufoff) + ldsw + _i * 8192), 16, 0, 0); } while (0)
; #define PG8_LDA(dst, b, h) do { _Pragma("unroll") for (int m = 0; m < 4; ++m) _Pragma("unroll") for (int k = 0; k < 2; ++k) dst[m][k] = *(const LAS bf16x8*)(pA + PG8_SA(b, h) + m * 2048 + k * 1024); } while (0)
; #define PG8_MMA(ai, bj, At, Bt) do { __builtin_amdgcn_s_setprio(1); _Pragma("unroll") for (int m = 0; m < 4; ++m) _Pragma("unroll") for (int n = 0; n < 2; ++n) _Pragma("unroll") for (int k = 0; k < 2; ++k) \
;         acc[ai][bj][m][n] = __builtin_amdgcn_mfma_f32_16x16x32_bf16(Bt[n][k], At[m][k], acc[ai][bj][m][n], 0, 0, 0); __builtin_amdgcn_s_setprio(0); } while (0)
; #define PG8_WAIT_V(n) asm volatile("s_waitcnt vmcnt(" #n ")" ::: "memory")
; #define PG8_WAIT_L(n) asm volatile("s_waitcnt lgkmcnt(" #n ")" ::: "memory")
; #define PG8_BAR __builtin_amdgcn_s_barrier()
; #define PG8_SCHED __builtin_amdgcn_sched_barrier(0)
; template <class Desc, class Epi, bool ALIGN_EPI>
; __device__ __forceinline__ void gemm_phase(LAS unsigned char* lds, const Desc& D, const Epi& E, int G, int c) {
;     ...
;             PG8_LDA(At, 1, 1); PG8_STAGE(PG8_SB(1, 0), b3, voffB); PG8_STAGE(PG8_SB(1, 1), b3 + hstepB, voffB); PG8_STAGE(PG8_SA(1, 0), a3, voffA);
;             PG8_WAIT_V(8); PG8_WAIT_L(0); PG8_BAR; PG8_MMA(1, 0, At, B0); PG8_MMA(1, 1, At, B1); PG8_BAR; PG8_SCHED;
;         }
	s_mov_b32 m0, s35
	v_lshl_add_u64 v[212:213], v[212:213], 0, s[76:77]
	s_add_u32 s18, s18, 0x100080
	ds_read_b128 v[180:183], v148 offset:49152
	ds_read_b128 v[184:187], v148 offset:50176
	ds_read_b128 v[188:191], v148 offset:51200
	ds_read_b128 v[192:195], v148 offset:52224
	ds_read_b128 v[196:199], v148 offset:53248
	ds_read_b128 v[200:203], v148 offset:54272
	ds_read_b128 v[204:207], v148 offset:55296
	ds_read_b128 v[208:211], v148 offset:56320
	global_load_lds_dwordx4 v[212:213], off
	v_lshl_add_u64 v[212:213], v[214:215], 0, s[76:77]
	s_mov_b32 m0, s38
	s_addc_u32 s19, s19, 0
	global_load_lds_dwordx4 v[212:213], off
	v_lshl_add_u64 v[212:213], s[18:19], 0, v[136:137]
	s_mov_b32 m0, s41
	s_nop 0
	global_load_lds_dwordx4 v[212:213], off
	v_lshl_add_u64 v[212:213], s[18:19], 0, v[132:133]
	s_mov_b32 m0, s42
	s_nop 0
	global_load_lds_dwordx4 v[212:213], off
	v_lshl_add_u64 v[212:213], v[216:217], 0, s[76:77]
	s_mov_b32 m0, s39
	s_nop 0
	global_load_lds_dwordx4 v[212:213], off
	v_lshl_add_u64 v[212:213], v[218:219], 0, s[76:77]
	s_mov_b32 m0, s40
	s_nop 0
	global_load_lds_dwordx4 v[212:213], off
	s_waitcnt vmcnt(8)
	s_waitcnt lgkmcnt(0)
	s_barrier
	v_mfma_f32_16x16x32_bf16 v[64:67], v[144:147], v[180:183], v[64:67]
	v_mfma_f32_16x16x32_bf16 v[64:67], v[152:155], v[184:187], v[64:67]
	v_mfma_f32_16x16x32_bf16 v[60:63], v[156:159], v[180:183], v[60:63]
	v_mfma_f32_16x16x32_bf16 v[60:63], v[160:163], v[184:187], v[60:63]
	v_mfma_f32_16x16x32_bf16 v[56:59], v[144:147], v[188:191], v[56:59]
	v_mfma_f32_16x16x32_bf16 v[56:59], v[152:155], v[192:195], v[56:59]
	v_mfma_f32_16x16x32_bf16 v[48:51], v[156:159], v[188:191], v[48:51]
	v_mfma_f32_16x16x32_bf16 v[48:51], v[160:163], v[192:195], v[48:51]
	v_mfma_f32_16x16x32_bf16 v[40:43], v[144:147], v[196:199], v[40:43]
	v_mfma_f32_16x16x32_bf16 v[40:43], v[152:155], v[200:203], v[40:43]
	v_mfma_f32_16x16x32_bf16 v[32:35], v[156:159], v[196:199], v[32:35]
	v_mfma_f32_16x16x32_bf16 v[32:35], v[160:163], v[200:203], v[32:35]
	v_mfma_f32_16x16x32_bf16 v[24:27], v[144:147], v[204:207], v[24:27]
	v_mfma_f32_16x16x32_bf16 v[24:27], v[152:155], v[208:211], v[24:27]
	v_mfma_f32_16x16x32_bf16 v[16:19], v[156:159], v[204:207], v[16:19]
	v_mfma_f32_16x16x32_bf16 v[16:19], v[160:163], v[208:211], v[16:19]
	v_mfma_f32_16x16x32_bf16 v[52:55], v[164:167], v[180:183], v[52:55]
	v_mfma_f32_16x16x32_bf16 v[52:55], v[168:171], v[184:187], v[52:55]
	v_mfma_f32_16x16x32_bf16 v[44:47], v[172:175], v[180:183], v[44:47]
	v_mfma_f32_16x16x32_bf16 v[44:47], v[176:179], v[184:187], v[44:47]
	v_mfma_f32_16x16x32_bf16 v[36:39], v[164:167], v[188:191], v[36:39]
	v_mfma_f32_16x16x32_bf16 v[36:39], v[168:171], v[192:195], v[36:39]
	v_mfma_f32_16x16x32_bf16 v[28:31], v[172:175], v[188:191], v[28:31]
	v_mfma_f32_16x16x32_bf16 v[28:31], v[176:179], v[192:195], v[28:31]
	v_mfma_f32_16x16x32_bf16 v[20:23], v[164:167], v[196:199], v[20:23]
	v_mfma_f32_16x16x32_bf16 v[20:23], v[168:171], v[200:203], v[20:23]
	v_mfma_f32_16x16x32_bf16 v[12:15], v[172:175], v[196:199], v[12:15]
	v_mfma_f32_16x16x32_bf16 v[12:15], v[176:179], v[200:203], v[12:15]
	v_mfma_f32_16x16x32_bf16 v[8:11], v[164:167], v[204:207], v[8:11]
	v_mfma_f32_16x16x32_bf16 v[8:11], v[168:171], v[208:211], v[8:11]
	v_mfma_f32_16x16x32_bf16 v[4:7], v[172:175], v[204:207], v[4:7]
	v_mfma_f32_16x16x32_bf16 v[4:7], v[176:179], v[208:211], v[4:7]
	s_barrier
	s_add_u32 s16, s16, 0x100
	s_addc_u32 s17, s17, 0
	s_add_u32 s48, s48, 0x100
	s_addc_u32 s49, s49, 0
	s_cmp_ge_u32 s50, s46
	s_mov_b32 s18, s50
	s_cbranch_scc0 .LBB0_1324
	s_and_b64 vcc, exec, s[6:7]
	s_cbranch_vccz .LBB0_1327
	s_barrier

;     __device__ __forceinline__ int nt(const Unit& u) const { return (u.pn >> 1) < 2 ? 22 : 20; }
; #define PG8_STAGE(bufoff, gbase, voff) do { _Pragma("unroll") for (int _i = 0; _i < 2; ++_i) \
;         __builtin_amdgcn_global_load_lds((const unsigned*)((const char*)(gbase) + (voff)[_i]), (LAS unsigned*)(lds + (bufoff) + ldsw + _i * 8192), 16, 0, 0); } while (0)
; #define PG8_LDA(dst, b, h) do { _Pragma("unroll") for (int m = 0; m < 4; ++m) _Pragma("unroll") for (int k = 0; k < 2; ++k) dst[m][k] = *(const LAS bf16x8*)(pA + PG8_SA(b, h) + m * 2048 + k * 1024); } while (0)
; #define PG8_LDB(dst, b, h) do { _Pragma("unroll") for (int n = 0; n < 2; ++n) _Pragma("unroll") for (int k = 0; k < 2; ++k) dst[n][k] = *(const LAS bf16x8*)(pB + (PG8_SB(b, h) - 4 * HTB) + n * 2048 + k * 1024); } while (0)
; #define PG8_MMA(ai, bj, At, Bt) do { __builtin_amdgcn_s_setprio(1); _Pragma("unroll") for (int m = 0; m < 4; ++m) _Pragma("unroll") for (int n = 0; n < 2; ++n) _Pragma("unroll") for (int k = 0; k < 2; ++k) \
;         acc[ai][bj][m][n] = __builtin_amdgcn_mfma_f32_16x16x32_bf16(Bt[n][k], At[m][k], acc[ai][bj][m][n], 0, 0, 0); __builtin_amdgcn_s_setprio(0); } while (0)
; #define PG8_WAIT_V(n) asm volatile("s_waitcnt vmcnt(" #n ")" ::: "memory")
; #define PG8_BAR __builtin_amdgcn_s_barrier()
; template <class Desc, class Epi, bool ALIGN_EPI>
; __device__ __forceinline__ void gemm_phase(LAS unsigned char* lds, const Desc& D, const Epi& E, int G, int c) {
;     ...
;         for (int t = 0; t < nt; t += 2) {
;             const bool last = (t == nt - 2);
;             if (last && has_next) PG8_AWAIT(nxt);
;             const char* a1 = cA + (size_t)(t + 1) * kstep;
;             const char* a2 = last ? nA : cA + (size_t)(t + 2) * kstep; const char* b2 = last ? nB : cB + (size_t)(t + 2) * kstep;
;             const char* a3 = a2 + kstep; const char* b3 = b2 + kstep;
;             PG8_LDB(B0, 0, 0); PG8_LDB(B1, 0, 1); PG8_SCHED; PG8_LDA(At, 0, 0); PG8_STAGE(PG8_SA(1, 1), a1 + hstepA, voffA);
;             PG8_WAIT_V(8); PG8_WAIT_L(0); PG8_BAR; PG8_MMA(0, 0, At, B0); PG8_MMA(0, 1, At, B1); PG8_BAR; PG8_SCHED;
;             PG8_LDA(At, 0, 1); PG8_STAGE(PG8_SB(0, 0), b2, voffB); PG8_STAGE(PG8_SB(0, 1), b2 + hstepB, voffB); PG8_STAGE(PG8_SA(0, 0), a2, voffA);
;             PG8_WAIT_V(8); PG8_WAIT_L(0); PG8_BAR; PG8_MMA(1, 0, At, B0); PG8_MMA(1, 1, At, B1); PG8_BAR; PG8_SCHED;
.LBB0_1479:
	ds_read_b128 v[116:119], v225
	ds_read_b128 v[128:131], v225 offset:1024
	ds_read_b128 v[132:135], v225 offset:2048
	ds_read_b128 v[136:139], v225 offset:3072
	ds_read_b128 v[140:143], v225 offset:16384
	ds_read_b128 v[144:147], v225 offset:17408
	ds_read_b128 v[148:151], v225 offset:18432
	ds_read_b128 v[152:155], v225 offset:19456
	s_add_u32 s12, s0, 0xfffe0080
	s_addc_u32 s13, s1, -1
	s_cmp_eq_u32 s52, 4
	s_cselect_b32 s17, s37, s13
	s_cselect_b32 s16, s36, s12
	s_cselect_b32 s13, s21, s33
	s_cselect_b32 s12, s24, s27
	v_lshl_add_u64 v[208:209], s[0:1], 0, v[200:201]
	s_add_i32 m0, s31, 0xc000
	ds_read_b128 v[164:167], v224
	ds_read_b128 v[168:171], v224 offset:1024
	ds_read_b128 v[172:175], v224 offset:2048
	ds_read_b128 v[176:179], v224 offset:3072
	ds_read_b128 v[180:183], v224 offset:4096
	ds_read_b128 v[184:187], v224 offset:5120
	ds_read_b128 v[188:191], v224 offset:6144
	ds_read_b128 v[204:207], v224 offset:7168
	global_load_lds_dwordx4 v[208:209], off
	v_lshl_add_u64 v[208:209], s[0:1], 0, v[202:203]
	s_add_i32 m0, s31, 0xe000
	s_nop 0
	global_load_lds_dwordx4 v[208:209], off
	s_waitcnt vmcnt(8)
	s_waitcnt lgkmcnt(0)
	s_barrier
	v_mfma_f32_16x16x32_bf16 v[160:163], v[116:119], v[164:167], v[160:163]
	v_mfma_f32_16x16x32_bf16 v[160:163], v[128:131], v[168:171], v[160:163]
	v_mfma_f32_16x16x32_bf16 v[156:159], v[132:135], v[164:167], v[156:159]
	v_mfma_f32_16x16x32_bf16 v[156:159], v[136:139], v[168:171], v[156:159]
	v_mfma_f32_16x16x32_bf16 v[112:115], v[116:119], v[172:175], v[112:115]
	v_mfma_f32_16x16x32_bf16 v[112:115], v[128:131], v[176:179], v[112:115]
	v_mfma_f32_16x16x32_bf16 v[108:111], v[132:135], v[172:175], v[108:111]
	v_mfma_f32_16x16x32_bf16 v[108:111], v[136:139], v[176:179], v[108:111]
	v_mfma_f32_16x16x32_bf16 v[96:99], v[116:119], v[180:183], v[96:99]
	v_mfma_f32_16x16x32_bf16 v[96:99], v[128:131], v[184:187], v[96:99]
	v_mfma_f32_16x16x32_bf16 v[92:95], v[132:135], v[180:183], v[92:95]
	v_mfma_f32_16x16x32_bf16 v[92:95], v[136:139], v[184:187], v[92:95]
	v_mfma_f32_16x16x32_bf16 v[80:83], v[116:119], v[188:191], v[80:83]
	v_mfma_f32_16x16x32_bf16 v[80:83], v[128:131], v[204:207], v[80:83]
	v_mfma_f32_16x16x32_bf16 v[76:79], v[132:135], v[188:191], v[76:79]
	v_mfma_f32_16x16x32_bf16 v[76:79], v[136:139], v[204:207], v[76:79]
	v_mfma_f32_16x16x32_bf16 v[124:127], v[140:143], v[164:167], v[124:127]
	v_mfma_f32_16x16x32_bf16 v[124:127], v[144:147], v[168:171], v[124:127]
	v_mfma_f32_16x16x32_bf16 v[120:123], v[148:151], v[164:167], v[120:123]
	v_mfma_f32_16x16x32_bf16 v[120:123], v[152:155], v[168:171], v[120:123]
	v_mfma_f32_16x16x32_bf16 v[104:107], v[140:143], v[172:175], v[104:107]
	v_mfma_f32_16x16x32_bf16 v[104:107], v[144:147], v[176:179], v[104:107]
	v_mfma_f32_16x16x32_bf16 v[100:103], v[148:151], v[172:175], v[100:103]
	v_mfma_f32_16x16x32_bf16 v[100:103], v[152:155], v[176:179], v[100:103]
	v_mfma_f32_16x16x32_bf16 v[88:91], v[140:143], v[180:183], v[88:91]
	v_mfma_f32_16x16x32_bf16 v[88:91], v[144:147], v[184:187], v[88:91]
	v_mfma_f32_16x16x32_bf16 v[84:87], v[148:151], v[180:183], v[84:87]
	v_mfma_f32_16x16x32_bf16 v[84:87], v[152:155], v[184:187], v[84:87]
	v_mfma_f32_16x16x32_bf16 v[72:75], v[140:143], v[188:191], v[72:75]
	v_mfma_f32_16x16x32_bf16 v[72:75], v[144:147], v[204:207], v[72:75]
	v_mfma_f32_16x16x32_bf16 v[68:71], v[148:151], v[188:191], v[68:71]
	v_mfma_f32_16x16x32_bf16 v[68:71], v[152:155], v[204:207], v[68:71]
	s_barrier
	s_mov_b32 m0, s34
	v_lshl_add_u64 v[208:209], s[12:13], 0, v[196:197]
	s_add_u32 s54, s12, 0x20000
	ds_read_b128 v[164:167], v224 offset:16384
	ds_read_b128 v[168:171], v224 offset:17408
	ds_read_b128 v[172:175], v224 offset:18432
	ds_read_b128 v[176:179], v224 offset:19456
	ds_read_b128 v[180:183], v224 offset:20480
	ds_read_b128 v[184:187], v224 offset:21504
	ds_read_b128 v[188:191], v224 offset:22528
	ds_read_b128 v[204:207], v224 offset:23552
	global_load_lds_dwordx4 v[208:209], off
	v_lshl_add_u64 v[210:211], s[12:13], 0, v[192:193]
	s_mov_b32 m0, s35
	s_addc_u32 s55, s13, 0
	global_load_lds_dwordx4 v[210:211], off
	v_lshl_add_u64 v[212:213], s[54:55], 0, v[196:197]
	s_mov_b32 m0, s40
	v_lshl_add_u64 v[214:215], s[16:17], 0, v[194:195]
	global_load_lds_dwordx4 v[212:213], off
	v_lshl_add_u64 v[212:213], s[54:55], 0, v[192:193]
	s_mov_b32 m0, s41
	s_nop 0
	global_load_lds_dwordx4 v[212:213], off
	v_lshl_add_u64 v[212:213], s[16:17], 0, v[198:199]
	s_mov_b32 m0, s31
	s_nop 0
	global_load_lds_dwordx4 v[212:213], off
	s_mov_b32 m0, s42
	s_nop 0
	global_load_lds_dwordx4 v[214:215], off
	s_waitcnt vmcnt(8)
	s_waitcnt lgkmcnt(0)
	s_barrier
; #define PG8_STAGE(bufoff, gbase, voff) do { _Pragma("unroll") for (int _i = 0; _i < 2; ++_i) \
;         __builtin_amdgcn_global_load_lds((const unsigned*)((const char*)(gbase) + (voff)[_i]), (LAS unsigned*)(lds + (bufoff) + ldsw + _i * 8192), 16, 0, 0); } while (0)
; #define PG8_LDA(dst, b, h) do { _Pragma("unroll") for (int m = 0; m < 4; ++m) _Pragma("unroll") for (int k = 0; k < 2; ++k) dst[m][k] = *(const LAS bf16x8*)(pA + PG8_SA(b, h) + m * 2048 + k * 1024); } while (0)
; #define PG8_LDB(dst, b, h) do { _Pragma("unroll") for (int n = 0; n < 2; ++n) _Pragma("unroll") for (int k = 0; k < 2; ++k) dst[n][k] = *(const LAS bf16x8*)(pB + (PG8_SB(b, h) - 4 * HTB) + n * 2048 + k * 1024); } while (0)
; #define PG8_MMA(ai, bj, At, Bt) do { __builtin_amdgcn_s_setprio(1); _Pragma("unroll") for (int m = 0; m < 4; ++m) _Pragma("unroll") for (int n = 0; n < 2; ++n) _Pragma("unroll") for (int k = 0; k < 2; ++k) \
;         acc[ai][bj][m][n] = __builtin_amdgcn_mfma_f32_16x16x32_bf16(Bt[n][k], At[m][k], acc[ai][bj][m][n], 0, 0, 0); __builtin_amdgcn_s_setprio(0); } while (0)
; #define PG8_WAIT_V(n) asm volatile("s_waitcnt vmcnt(" #n ")" ::: "memory")
; #define PG8_WAIT_L(n) asm volatile("s_waitcnt lgkmcnt(" #n ")" ::: "memory")
; #define PG8_BAR __builtin_amdgcn_s_barrier()
; #define PG8_SCHED __builtin_amdgcn_sched_barrier(0)
; template <class Desc, class Epi, bool ALIGN_EPI>
; __device__ __forceinline__ void gemm_phase(LAS unsigned char* lds, const Desc& D, const Epi& E, int G, int c) {
;     ...
;             PG8_WAIT_V(8); PG8_WAIT_L(0); PG8_BAR; PG8_MMA(1, 0, At, B0); PG8_MMA(1, 1, At, B1); PG8_BAR; PG8_SCHED;
;             PG8_LDB(B0, 1, 0); PG8_LDB(B1, 1, 1); PG8_SCHED; PG8_LDA(At, 1, 0); PG8_STAGE(PG8_SA(0, 1), a2 + hstepA, voffA);
;             PG8_WAIT_V(8); PG8_WAIT_L(0); PG8_BAR; PG8_MMA(0, 0, At, B0); PG8_MMA(0, 1, At, B1); PG8_BAR; PG8_SCHED;
	v_mfma_f32_16x16x32_bf16 v[64:67], v[116:119], v[164:167], v[64:67]
	v_mfma_f32_16x16x32_bf16 v[64:67], v[128:131], v[168:171], v[64:67]
	v_mfma_f32_16x16x32_bf16 v[60:63], v[132:135], v[164:167], v[60:63]
	v_mfma_f32_16x16x32_bf16 v[60:63], v[136:139], v[168:171], v[60:63]
	v_mfma_f32_16x16x32_bf16 v[48:51], v[116:119], v[172:175], v[48:51]
	v_mfma_f32_16x16x32_bf16 v[48:51], v[128:131], v[176:179], v[48:51]
	v_mfma_f32_16x16x32_bf16 v[44:47], v[132:135], v[172:175], v[44:47]
	v_mfma_f32_16x16x32_bf16 v[44:47], v[136:139], v[176:179], v[44:47]
	v_mfma_f32_16x16x32_bf16 v[32:35], v[116:119], v[180:183], v[32:35]
	v_mfma_f32_16x16x32_bf16 v[32:35], v[128:131], v[184:187], v[32:35]
	v_mfma_f32_16x16x32_bf16 v[28:31], v[132:135], v[180:183], v[28:31]
	v_mfma_f32_16x16x32_bf16 v[28:31], v[136:139], v[184:187], v[28:31]
	v_mfma_f32_16x16x32_bf16 v[16:19], v[116:119], v[188:191], v[16:19]
	v_mfma_f32_16x16x32_bf16 v[16:19], v[128:131], v[204:207], v[16:19]
	v_mfma_f32_16x16x32_bf16 v[12:15], v[132:135], v[188:191], v[12:15]
	v_mfma_f32_16x16x32_bf16 v[12:15], v[136:139], v[204:207], v[12:15]
	v_mfma_f32_16x16x32_bf16 v[56:59], v[140:143], v[164:167], v[56:59]
	v_mfma_f32_16x16x32_bf16 v[56:59], v[144:147], v[168:171], v[56:59]
	v_mfma_f32_16x16x32_bf16 v[52:55], v[148:151], v[164:167], v[52:55]
	v_mfma_f32_16x16x32_bf16 v[52:55], v[152:155], v[168:171], v[52:55]
	v_mfma_f32_16x16x32_bf16 v[40:43], v[140:143], v[172:175], v[40:43]
	v_mfma_f32_16x16x32_bf16 v[40:43], v[144:147], v[176:179], v[40:43]
	v_mfma_f32_16x16x32_bf16 v[36:39], v[148:151], v[172:175], v[36:39]
	v_mfma_f32_16x16x32_bf16 v[36:39], v[152:155], v[176:179], v[36:39]
	v_mfma_f32_16x16x32_bf16 v[24:27], v[140:143], v[180:183], v[24:27]
	v_mfma_f32_16x16x32_bf16 v[24:27], v[144:147], v[184:187], v[24:27]
	v_mfma_f32_16x16x32_bf16 v[20:23], v[148:151], v[180:183], v[20:23]
	v_mfma_f32_16x16x32_bf16 v[20:23], v[152:155], v[184:187], v[20:23]
	v_mfma_f32_16x16x32_bf16 v[8:11], v[140:143], v[188:191], v[8:11]
	v_mfma_f32_16x16x32_bf16 v[8:11], v[144:147], v[204:207], v[8:11]
	v_mfma_f32_16x16x32_bf16 v[4:7], v[148:151], v[188:191], v[4:7]
	v_mfma_f32_16x16x32_bf16 v[4:7], v[152:155], v[204:207], v[4:7]
	s_barrier
	ds_read_b128 v[116:119], v225 offset:32768
	ds_read_b128 v[128:131], v225 offset:33792
	ds_read_b128 v[132:135], v225 offset:34816
	ds_read_b128 v[136:139], v225 offset:35840
	ds_read_b128 v[140:143], v225 offset:49152
	ds_read_b128 v[144:147], v225 offset:50176
	ds_read_b128 v[148:151], v225 offset:51200
	ds_read_b128 v[152:155], v225 offset:52224
	s_add_u32 s16, s16, 0x20000
	s_addc_u32 s17, s17, 0
	s_mov_b32 m0, s43
	v_lshl_add_u64 v[216:217], s[16:17], 0, v[198:199]
	ds_read_b128 v[164:167], v224 offset:32768
	ds_read_b128 v[168:171], v224 offset:33792
	ds_read_b128 v[172:175], v224 offset:34816
	ds_read_b128 v[176:179], v224 offset:35840
	ds_read_b128 v[180:183], v224 offset:36864
	ds_read_b128 v[184:187], v224 offset:37888
	ds_read_b128 v[188:191], v224 offset:38912
	ds_read_b128 v[204:207], v224 offset:39936
	global_load_lds_dwordx4 v[216:217], off
	v_lshl_add_u64 v[216:217], s[16:17], 0, v[194:195]
	s_mov_b32 m0, s44
	s_nop 0
	global_load_lds_dwordx4 v[216:217], off
	s_waitcnt vmcnt(8)
	s_waitcnt lgkmcnt(0)
	s_barrier
	v_mfma_f32_16x16x32_bf16 v[160:163], v[116:119], v[164:167], v[160:163]
	v_mfma_f32_16x16x32_bf16 v[160:163], v[128:131], v[168:171], v[160:163]
	v_mfma_f32_16x16x32_bf16 v[156:159], v[132:135], v[164:167], v[156:159]
	v_mfma_f32_16x16x32_bf16 v[156:159], v[136:139], v[168:171], v[156:159]
	v_mfma_f32_16x16x32_bf16 v[112:115], v[116:119], v[172:175], v[112:115]
	v_mfma_f32_16x16x32_bf16 v[112:115], v[128:131], v[176:179], v[112:115]
	v_mfma_f32_16x16x32_bf16 v[108:111], v[132:135], v[172:175], v[108:111]
	v_mfma_f32_16x16x32_bf16 v[108:111], v[136:139], v[176:179], v[108:111]
	v_mfma_f32_16x16x32_bf16 v[96:99], v[116:119], v[180:183], v[96:99]
	v_mfma_f32_16x16x32_bf16 v[96:99], v[128:131], v[184:187], v[96:99]
	v_mfma_f32_16x16x32_bf16 v[92:95], v[132:135], v[180:183], v[92:95]
	v_mfma_f32_16x16x32_bf16 v[92:95], v[136:139], v[184:187], v[92:95]
	v_mfma_f32_16x16x32_bf16 v[80:83], v[116:119], v[188:191], v[80:83]
	v_mfma_f32_16x16x32_bf16 v[80:83], v[128:131], v[204:207], v[80:83]
	v_mfma_f32_16x16x32_bf16 v[76:79], v[132:135], v[188:191], v[76:79]
	v_mfma_f32_16x16x32_bf16 v[76:79], v[136:139], v[204:207], v[76:79]
	v_mfma_f32_16x16x32_bf16 v[124:127], v[140:143], v[164:167], v[124:127]
	v_mfma_f32_16x16x32_bf16 v[124:127], v[144:147], v[168:171], v[124:127]
	v_mfma_f32_16x16x32_bf16 v[120:123], v[148:151], v[164:167], v[120:123]
	v_mfma_f32_16x16x32_bf16 v[120:123], v[152:155], v[168:171], v[120:123]
	v_mfma_f32_16x16x32_bf16 v[104:107], v[140:143], v[172:175], v[104:107]
	v_mfma_f32_16x16x32_bf16 v[104:107], v[144:147], v[176:179], v[104:107]
	v_mfma_f32_16x16x32_bf16 v[100:103], v[148:151], v[172:175], v[100:103]
	v_mfma_f32_16x16x32_bf16 v[100:103], v[152:155], v[176:179], v[100:103]
	v_mfma_f32_16x16x32_bf16 v[88:91], v[140:143], v[180:183], v[88:91]
	v_mfma_f32_16x16x32_bf16 v[88:91], v[144:147], v[184:187], v[88:91]
	v_mfma_f32_16x16x32_bf16 v[84:87], v[148:151], v[180:183], v[84:87]
	v_mfma_f32_16x16x32_bf16 v[84:87], v[152:155], v[184:187], v[84:87]
	v_mfma_f32_16x16x32_bf16 v[72:75], v[140:143], v[188:191], v[72:75]
	v_mfma_f32_16x16x32_bf16 v[72:75], v[144:147], v[204:207], v[72:75]
	v_mfma_f32_16x16x32_bf16 v[68:71], v[148:151], v[188:191], v[68:71]
	v_mfma_f32_16x16x32_bf16 v[68:71], v[152:155], v[204:207], v[68:71]
	s_barrier
; #define PG8_STAGE(bufoff, gbase, voff) do { _Pragma("unroll") for (int _i = 0; _i < 2; ++_i) \
;         __builtin_amdgcn_global_load_lds((const unsigned*)((const char*)(gbase) + (voff)[_i]), (LAS unsigned*)(lds + (bufoff) + ldsw + _i * 8192), 16, 0, 0); } while (0)
; #define PG8_LDA(dst, b, h) do { _Pragma("unroll") for (int m = 0; m < 4; ++m) _Pragma("unroll") for (int k = 0; k < 2; ++k) dst[m][k] = *(const LAS bf16x8*)(pA + PG8_SA(b, h) + m * 2048 + k * 1024); } while (0)
; #define PG8_MMA(ai, bj, At, Bt) do { __builtin_amdgcn_s_setprio(1); _Pragma("unroll") for (int m = 0; m < 4; ++m) _Pragma("unroll") for (int n = 0; n < 2; ++n) _Pragma("unroll") for (int k = 0; k < 2; ++k) \
;         acc[ai][bj][m][n] = __builtin_amdgcn_mfma_f32_16x16x32_bf16(Bt[n][k], At[m][k], acc[ai][bj][m][n], 0, 0, 0); __builtin_amdgcn_s_setprio(0); } while (0)
; #define PG8_WAIT_V(n) asm volatile("s_waitcnt vmcnt(" #n ")" ::: "memory")
; #define PG8_WAIT_L(n) asm volatile("s_waitcnt lgkmcnt(" #n ")" ::: "memory")
; #define PG8_BAR __builtin_amdgcn_s_barrier()
; #define PG8_SCHED __builtin_amdgcn_sched_barrier(0)
; template <class Desc, class Epi, bool ALIGN_EPI>
; __device__ __forceinline__ void gemm_phase(LAS unsigned char* lds, const Desc& D, const Epi& E, int G, int c) {
;     ...
;             PG8_LDA(At, 1, 1); PG8_STAGE(PG8_SB(1, 0), b3, voffB); PG8_STAGE(PG8_SB(1, 1), b3 + hstepB, voffB); PG8_STAGE(PG8_SA(1, 0), a3, voffA);
;             PG8_WAIT_V(8); PG8_WAIT_L(0); PG8_BAR; PG8_MMA(1, 0, At, B0); PG8_MMA(1, 1, At, B1); PG8_BAR; PG8_SCHED;
;         }
;         if constexpr (ALIGN_EPI) { if (wr == 0) PG8_BAR; }
	s_mov_b32 m0, s45
	v_lshl_add_u64 v[208:209], v[208:209], 0, s[76:77]
	s_add_u32 s12, s12, 0x20080
	ds_read_b128 v[164:167], v224 offset:49152
	ds_read_b128 v[168:171], v224 offset:50176
	ds_read_b128 v[172:175], v224 offset:51200
	ds_read_b128 v[176:179], v224 offset:52224
	ds_read_b128 v[180:183], v224 offset:53248
	ds_read_b128 v[184:187], v224 offset:54272
	ds_read_b128 v[188:191], v224 offset:55296
	ds_read_b128 v[204:207], v224 offset:56320
	global_load_lds_dwordx4 v[208:209], off
	v_lshl_add_u64 v[208:209], v[210:211], 0, s[76:77]
	s_mov_b32 m0, s46
	s_addc_u32 s13, s13, 0
	global_load_lds_dwordx4 v[208:209], off
	v_lshl_add_u64 v[208:209], s[12:13], 0, v[196:197]
	s_mov_b32 m0, s49
	s_nop 0
	global_load_lds_dwordx4 v[208:209], off
	v_lshl_add_u64 v[208:209], s[12:13], 0, v[192:193]
	s_mov_b32 m0, s50
	s_nop 0
	global_load_lds_dwordx4 v[208:209], off
	v_lshl_add_u64 v[208:209], v[212:213], 0, s[76:77]
	s_mov_b32 m0, s47
	s_nop 0
	global_load_lds_dwordx4 v[208:209], off
	v_lshl_add_u64 v[208:209], v[214:215], 0, s[76:77]
	s_mov_b32 m0, s48
	s_nop 0
	global_load_lds_dwordx4 v[208:209], off
	s_waitcnt vmcnt(8)
	s_waitcnt lgkmcnt(0)
	s_barrier
	v_mfma_f32_16x16x32_bf16 v[64:67], v[116:119], v[164:167], v[64:67]
	v_mfma_f32_16x16x32_bf16 v[64:67], v[128:131], v[168:171], v[64:67]
	v_mfma_f32_16x16x32_bf16 v[60:63], v[132:135], v[164:167], v[60:63]
	v_mfma_f32_16x16x32_bf16 v[60:63], v[136:139], v[168:171], v[60:63]
	v_mfma_f32_16x16x32_bf16 v[48:51], v[116:119], v[172:175], v[48:51]
	v_mfma_f32_16x16x32_bf16 v[48:51], v[128:131], v[176:179], v[48:51]
	v_mfma_f32_16x16x32_bf16 v[44:47], v[132:135], v[172:175], v[44:47]
	v_mfma_f32_16x16x32_bf16 v[44:47], v[136:139], v[176:179], v[44:47]
	v_mfma_f32_16x16x32_bf16 v[32:35], v[116:119], v[180:183], v[32:35]
	v_mfma_f32_16x16x32_bf16 v[32:35], v[128:131], v[184:187], v[32:35]
	v_mfma_f32_16x16x32_bf16 v[28:31], v[132:135], v[180:183], v[28:31]
	v_mfma_f32_16x16x32_bf16 v[28:31], v[136:139], v[184:187], v[28:31]
	v_mfma_f32_16x16x32_bf16 v[16:19], v[116:119], v[188:191], v[16:19]
	v_mfma_f32_16x16x32_bf16 v[16:19], v[128:131], v[204:207], v[16:19]
	v_mfma_f32_16x16x32_bf16 v[12:15], v[132:135], v[188:191], v[12:15]
	v_mfma_f32_16x16x32_bf16 v[12:15], v[136:139], v[204:207], v[12:15]
	v_mfma_f32_16x16x32_bf16 v[56:59], v[140:143], v[164:167], v[56:59]
	v_mfma_f32_16x16x32_bf16 v[56:59], v[144:147], v[168:171], v[56:59]
	v_mfma_f32_16x16x32_bf16 v[52:55], v[148:151], v[164:167], v[52:55]
	v_mfma_f32_16x16x32_bf16 v[52:55], v[152:155], v[168:171], v[52:55]
	v_mfma_f32_16x16x32_bf16 v[40:43], v[140:143], v[172:175], v[40:43]
	v_mfma_f32_16x16x32_bf16 v[40:43], v[144:147], v[176:179], v[40:43]
	v_mfma_f32_16x16x32_bf16 v[36:39], v[148:151], v[172:175], v[36:39]
	v_mfma_f32_16x16x32_bf16 v[36:39], v[152:155], v[176:179], v[36:39]
	v_mfma_f32_16x16x32_bf16 v[24:27], v[140:143], v[180:183], v[24:27]
	v_mfma_f32_16x16x32_bf16 v[24:27], v[144:147], v[184:187], v[24:27]
	v_mfma_f32_16x16x32_bf16 v[20:23], v[148:151], v[180:183], v[20:23]
	v_mfma_f32_16x16x32_bf16 v[20:23], v[152:155], v[184:187], v[20:23]
	v_mfma_f32_16x16x32_bf16 v[8:11], v[140:143], v[188:191], v[8:11]
	v_mfma_f32_16x16x32_bf16 v[8:11], v[144:147], v[204:207], v[8:11]
	v_mfma_f32_16x16x32_bf16 v[4:7], v[148:151], v[188:191], v[4:7]
	v_mfma_f32_16x16x32_bf16 v[4:7], v[152:155], v[204:207], v[4:7]
	s_barrier
	s_add_i32 s52, s52, 2
	s_add_u32 s0, s0, 0x100
	s_addc_u32 s1, s1, 0
	s_add_u32 s27, s27, 0x100
	s_addc_u32 s33, s33, 0
	s_cmp_gt_u32 s52, 5
	s_cbranch_scc0 .LBB0_1479
	s_and_b64 vcc, exec, s[8:9]
	s_cbranch_vccz .LBB0_1482
	s_barrier

;     __device__ __forceinline__ int nt(const Unit& u) const { return (u.pn >> 1) < 2 ? 22 : 20; }
; #define PG8_STAGE(bufoff, gbase, voff) do { _Pragma("unroll") for (int _i = 0; _i < 2; ++_i) \
;         __builtin_amdgcn_global_load_lds((const unsigned*)((const char*)(gbase) + (voff)[_i]), (LAS unsigned*)(lds + (bufoff) + ldsw + _i * 8192), 16, 0, 0); } while (0)
; #define PG8_LDA(dst, b, h) do { _Pragma("unroll") for (int m = 0; m < 4; ++m) _Pragma("unroll") for (int k = 0; k < 2; ++k) dst[m][k] = *(const LAS bf16x8*)(pA + PG8_SA(b, h) + m * 2048 + k * 1024); } while (0)
; #define PG8_LDB(dst, b, h) do { _Pragma("unroll") for (int n = 0; n < 2; ++n) _Pragma("unroll") for (int k = 0; k < 2; ++k) dst[n][k] = *(const LAS bf16x8*)(pB + (PG8_SB(b, h) - 4 * HTB) + n * 2048 + k * 1024); } while (0)
; #define PG8_MMA(ai, bj, At, Bt) do { __builtin_amdgcn_s_setprio(1); _Pragma("unroll") for (int m = 0; m < 4; ++m) _Pragma("unroll") for (int n = 0; n < 2; ++n) _Pragma("unroll") for (int k = 0; k < 2; ++k) \
;         acc[ai][bj][m][n] = __builtin_amdgcn_mfma_f32_16x16x32_bf16(Bt[n][k], At[m][k], acc[ai][bj][m][n], 0, 0, 0); __builtin_amdgcn_s_setprio(0); } while (0)
; #define PG8_WAIT_V(n) asm volatile("s_waitcnt vmcnt(" #n ")" ::: "memory")
; #define PG8_BAR __builtin_amdgcn_s_barrier()
; template <class Desc, class Epi, bool ALIGN_EPI>
; __device__ __forceinline__ void gemm_phase(LAS unsigned char* lds, const Desc& D, const Epi& E, int G, int c) {
;     ...
;         for (int t = 0; t < nt; t += 2) {
;             const bool last = (t == nt - 2);
;             if (last && has_next) PG8_AWAIT(nxt);
;             const char* a1 = cA + (size_t)(t + 1) * kstep;
;             const char* a2 = last ? nA : cA + (size_t)(t + 2) * kstep; const char* b2 = last ? nB : cB + (size_t)(t + 2) * kstep;
;             const char* a3 = a2 + kstep; const char* b3 = b2 + kstep;
;             PG8_LDB(B0, 0, 0); PG8_LDB(B1, 0, 1); PG8_SCHED; PG8_LDA(At, 0, 0); PG8_STAGE(PG8_SA(1, 1), a1 + hstepA, voffA);
;             PG8_WAIT_V(8); PG8_WAIT_L(0); PG8_BAR; PG8_MMA(0, 0, At, B0); PG8_MMA(0, 1, At, B1); PG8_BAR; PG8_SCHED;
;             PG8_LDA(At, 0, 1); PG8_STAGE(PG8_SB(0, 0), b2, voffB); PG8_STAGE(PG8_SB(0, 1), b2 + hstepB, voffB); PG8_STAGE(PG8_SA(0, 0), a2, voffA);
;             PG8_WAIT_V(8); PG8_WAIT_L(0); PG8_BAR; PG8_MMA(1, 0, At, B0); PG8_MMA(1, 1, At, B1); PG8_BAR; PG8_SCHED;
.LBB0_1517:
	ds_read_b128 v[116:119], v225
	ds_read_b128 v[128:131], v225 offset:1024
	ds_read_b128 v[132:135], v225 offset:2048
	ds_read_b128 v[136:139], v225 offset:3072
	ds_read_b128 v[140:143], v225 offset:16384
	ds_read_b128 v[144:147], v225 offset:17408
	ds_read_b128 v[148:151], v225 offset:18432
	ds_read_b128 v[152:155], v225 offset:19456
	s_add_u32 s12, s0, 0xfffe0080
	s_addc_u32 s13, s1, -1
	s_cmp_eq_u32 s54, 4
	s_cselect_b32 s17, s37, s13
	s_cselect_b32 s16, s36, s12
	s_cselect_b32 s13, s21, s33
	s_cselect_b32 s12, s24, s27
	v_lshl_add_u64 v[208:209], s[0:1], 0, v[200:201]
	s_add_i32 m0, s31, 0xc000
	ds_read_b128 v[164:167], v224
	ds_read_b128 v[168:171], v224 offset:1024
	ds_read_b128 v[172:175], v224 offset:2048
	ds_read_b128 v[176:179], v224 offset:3072
	ds_read_b128 v[180:183], v224 offset:4096
	ds_read_b128 v[184:187], v224 offset:5120
	ds_read_b128 v[188:191], v224 offset:6144
	ds_read_b128 v[204:207], v224 offset:7168
	global_load_lds_dwordx4 v[208:209], off
	v_lshl_add_u64 v[208:209], s[0:1], 0, v[202:203]
	s_add_i32 m0, s31, 0xe000
	s_nop 0
	global_load_lds_dwordx4 v[208:209], off
	s_waitcnt vmcnt(8)
	s_waitcnt lgkmcnt(0)
	s_barrier
	v_mfma_f32_16x16x32_bf16 v[160:163], v[116:119], v[164:167], v[160:163]
	v_mfma_f32_16x16x32_bf16 v[160:163], v[128:131], v[168:171], v[160:163]
	v_mfma_f32_16x16x32_bf16 v[156:159], v[132:135], v[164:167], v[156:159]
	v_mfma_f32_16x16x32_bf16 v[156:159], v[136:139], v[168:171], v[156:159]
	v_mfma_f32_16x16x32_bf16 v[112:115], v[116:119], v[172:175], v[112:115]
	v_mfma_f32_16x16x32_bf16 v[112:115], v[128:131], v[176:179], v[112:115]
	v_mfma_f32_16x16x32_bf16 v[108:111], v[132:135], v[172:175], v[108:111]
	v_mfma_f32_16x16x32_bf16 v[108:111], v[136:139], v[176:179], v[108:111]
	v_mfma_f32_16x16x32_bf16 v[96:99], v[116:119], v[180:183], v[96:99]
	v_mfma_f32_16x16x32_bf16 v[96:99], v[128:131], v[184:187], v[96:99]
	v_mfma_f32_16x16x32_bf16 v[92:95], v[132:135], v[180:183], v[92:95]
	v_mfma_f32_16x16x32_bf16 v[92:95], v[136:139], v[184:187], v[92:95]
	v_mfma_f32_16x16x32_bf16 v[80:83], v[116:119], v[188:191], v[80:83]
	v_mfma_f32_16x16x32_bf16 v[80:83], v[128:131], v[204:207], v[80:83]
	v_mfma_f32_16x16x32_bf16 v[76:79], v[132:135], v[188:191], v[76:79]
	v_mfma_f32_16x16x32_bf16 v[76:79], v[136:139], v[204:207], v[76:79]
	v_mfma_f32_16x16x32_bf16 v[124:127], v[140:143], v[164:167], v[124:127]
	v_mfma_f32_16x16x32_bf16 v[124:127], v[144:147], v[168:171], v[124:127]
	v_mfma_f32_16x16x32_bf16 v[120:123], v[148:151], v[164:167], v[120:123]
	v_mfma_f32_16x16x32_bf16 v[120:123], v[152:155], v[168:171], v[120:123]
	v_mfma_f32_16x16x32_bf16 v[104:107], v[140:143], v[172:175], v[104:107]
	v_mfma_f32_16x16x32_bf16 v[104:107], v[144:147], v[176:179], v[104:107]
	v_mfma_f32_16x16x32_bf16 v[100:103], v[148:151], v[172:175], v[100:103]
	v_mfma_f32_16x16x32_bf16 v[100:103], v[152:155], v[176:179], v[100:103]
	v_mfma_f32_16x16x32_bf16 v[88:91], v[140:143], v[180:183], v[88:91]
	v_mfma_f32_16x16x32_bf16 v[88:91], v[144:147], v[184:187], v[88:91]
	v_mfma_f32_16x16x32_bf16 v[84:87], v[148:151], v[180:183], v[84:87]
	v_mfma_f32_16x16x32_bf16 v[84:87], v[152:155], v[184:187], v[84:87]
	v_mfma_f32_16x16x32_bf16 v[72:75], v[140:143], v[188:191], v[72:75]
	v_mfma_f32_16x16x32_bf16 v[72:75], v[144:147], v[204:207], v[72:75]
	v_mfma_f32_16x16x32_bf16 v[68:71], v[148:151], v[188:191], v[68:71]
	v_mfma_f32_16x16x32_bf16 v[68:71], v[152:155], v[204:207], v[68:71]
	s_barrier
	s_mov_b32 m0, s34
	v_lshl_add_u64 v[208:209], s[12:13], 0, v[196:197]
	s_add_u32 s56, s12, 0x20000
	ds_read_b128 v[164:167], v224 offset:16384
	ds_read_b128 v[168:171], v224 offset:17408
	ds_read_b128 v[172:175], v224 offset:18432
	ds_read_b128 v[176:179], v224 offset:19456
	ds_read_b128 v[180:183], v224 offset:20480
	ds_read_b128 v[184:187], v224 offset:21504
	ds_read_b128 v[188:191], v224 offset:22528
	ds_read_b128 v[204:207], v224 offset:23552
	global_load_lds_dwordx4 v[208:209], off
	v_lshl_add_u64 v[210:211], s[12:13], 0, v[192:193]
	s_mov_b32 m0, s35
	s_addc_u32 s57, s13, 0
	global_load_lds_dwordx4 v[210:211], off
	v_lshl_add_u64 v[212:213], s[56:57], 0, v[196:197]
	s_mov_b32 m0, s42
	v_lshl_add_u64 v[214:215], s[16:17], 0, v[194:195]
	global_load_lds_dwordx4 v[212:213], off
	v_lshl_add_u64 v[212:213], s[56:57], 0, v[192:193]
	s_mov_b32 m0, s43
	s_nop 0
	global_load_lds_dwordx4 v[212:213], off
	v_lshl_add_u64 v[212:213], s[16:17], 0, v[198:199]
	s_mov_b32 m0, s31
	s_nop 0
	global_load_lds_dwordx4 v[212:213], off
	s_mov_b32 m0, s44
	s_nop 0
	global_load_lds_dwordx4 v[214:215], off
	s_waitcnt vmcnt(8)
	s_waitcnt lgkmcnt(0)
	s_barrier
; #define PG8_STAGE(bufoff, gbase, voff) do { _Pragma("unroll") for (int _i = 0; _i < 2; ++_i) \
;         __builtin_amdgcn_global_load_lds((const unsigned*)((const char*)(gbase) + (voff)[_i]), (LAS unsigned*)(lds + (bufoff) + ldsw + _i * 8192), 16, 0, 0); } while (0)
; #define PG8_LDA(dst, b, h) do { _Pragma("unroll") for (int m = 0; m < 4; ++m) _Pragma("unroll") for (int k = 0; k < 2; ++k) dst[m][k] = *(const LAS bf16x8*)(pA + PG8_SA(b, h) + m * 2048 + k * 1024); } while (0)
; #define PG8_LDB(dst, b, h) do { _Pragma("unroll") for (int n = 0; n < 2; ++n) _Pragma("unroll") for (int k = 0; k < 2; ++k) dst[n][k] = *(const LAS bf16x8*)(pB + (PG8_SB(b, h) - 4 * HTB) + n * 2048 + k * 1024); } while (0)
; #define PG8_MMA(ai, bj, At, Bt) do { __builtin_amdgcn_s_setprio(1); _Pragma("unroll") for (int m = 0; m < 4; ++m) _Pragma("unroll") for (int n = 0; n < 2; ++n) _Pragma("unroll") for (int k = 0; k < 2; ++k) \
;         acc[ai][bj][m][n] = __builtin_amdgcn_mfma_f32_16x16x32_bf16(Bt[n][k], At[m][k], acc[ai][bj][m][n], 0, 0, 0); __builtin_amdgcn_s_setprio(0); } while (0)
; #define PG8_WAIT_V(n) asm volatile("s_waitcnt vmcnt(" #n ")" ::: "memory")
; #define PG8_WAIT_L(n) asm volatile("s_waitcnt lgkmcnt(" #n ")" ::: "memory")
; #define PG8_BAR __builtin_amdgcn_s_barrier()
; #define PG8_SCHED __builtin_amdgcn_sched_barrier(0)
; template <class Desc, class Epi, bool ALIGN_EPI>
; __device__ __forceinline__ void gemm_phase(LAS unsigned char* lds, const Desc& D, const Epi& E, int G, int c) {
;     ...
;             PG8_WAIT_V(8); PG8_WAIT_L(0); PG8_BAR; PG8_MMA(1, 0, At, B0); PG8_MMA(1, 1, At, B1); PG8_BAR; PG8_SCHED;
;             PG8_LDB(B0, 1, 0); PG8_LDB(B1, 1, 1); PG8_SCHED; PG8_LDA(At, 1, 0); PG8_STAGE(PG8_SA(0, 1), a2 + hstepA, voffA);
;             PG8_WAIT_V(8); PG8_WAIT_L(0); PG8_BAR; PG8_MMA(0, 0, At, B0); PG8_MMA(0, 1, At, B1); PG8_BAR; PG8_SCHED;
	v_mfma_f32_16x16x32_bf16 v[64:67], v[116:119], v[164:167], v[64:67]
	v_mfma_f32_16x16x32_bf16 v[64:67], v[128:131], v[168:171], v[64:67]
	v_mfma_f32_16x16x32_bf16 v[60:63], v[132:135], v[164:167], v[60:63]
	v_mfma_f32_16x16x32_bf16 v[60:63], v[136:139], v[168:171], v[60:63]
	v_mfma_f32_16x16x32_bf16 v[48:51], v[116:119], v[172:175], v[48:51]
	v_mfma_f32_16x16x32_bf16 v[48:51], v[128:131], v[176:179], v[48:51]
	v_mfma_f32_16x16x32_bf16 v[44:47], v[132:135], v[172:175], v[44:47]
	v_mfma_f32_16x16x32_bf16 v[44:47], v[136:139], v[176:179], v[44:47]
	v_mfma_f32_16x16x32_bf16 v[32:35], v[116:119], v[180:183], v[32:35]
	v_mfma_f32_16x16x32_bf16 v[32:35], v[128:131], v[184:187], v[32:35]
	v_mfma_f32_16x16x32_bf16 v[28:31], v[132:135], v[180:183], v[28:31]
	v_mfma_f32_16x16x32_bf16 v[28:31], v[136:139], v[184:187], v[28:31]
	v_mfma_f32_16x16x32_bf16 v[16:19], v[116:119], v[188:191], v[16:19]
	v_mfma_f32_16x16x32_bf16 v[16:19], v[128:131], v[204:207], v[16:19]
	v_mfma_f32_16x16x32_bf16 v[12:15], v[132:135], v[188:191], v[12:15]
	v_mfma_f32_16x16x32_bf16 v[12:15], v[136:139], v[204:207], v[12:15]
	v_mfma_f32_16x16x32_bf16 v[56:59], v[140:143], v[164:167], v[56:59]
	v_mfma_f32_16x16x32_bf16 v[56:59], v[144:147], v[168:171], v[56:59]
	v_mfma_f32_16x16x32_bf16 v[52:55], v[148:151], v[164:167], v[52:55]
	v_mfma_f32_16x16x32_bf16 v[52:55], v[152:155], v[168:171], v[52:55]
	v_mfma_f32_16x16x32_bf16 v[40:43], v[140:143], v[172:175], v[40:43]
	v_mfma_f32_16x16x32_bf16 v[40:43], v[144:147], v[176:179], v[40:43]
	v_mfma_f32_16x16x32_bf16 v[36:39], v[148:151], v[172:175], v[36:39]
	v_mfma_f32_16x16x32_bf16 v[36:39], v[152:155], v[176:179], v[36:39]
	v_mfma_f32_16x16x32_bf16 v[24:27], v[140:143], v[180:183], v[24:27]
	v_mfma_f32_16x16x32_bf16 v[24:27], v[144:147], v[184:187], v[24:27]
	v_mfma_f32_16x16x32_bf16 v[20:23], v[148:151], v[180:183], v[20:23]
	v_mfma_f32_16x16x32_bf16 v[20:23], v[152:155], v[184:187], v[20:23]
	v_mfma_f32_16x16x32_bf16 v[8:11], v[140:143], v[188:191], v[8:11]
	v_mfma_f32_16x16x32_bf16 v[8:11], v[144:147], v[204:207], v[8:11]
	v_mfma_f32_16x16x32_bf16 v[4:7], v[148:151], v[188:191], v[4:7]
	v_mfma_f32_16x16x32_bf16 v[4:7], v[152:155], v[204:207], v[4:7]
	s_barrier
	ds_read_b128 v[116:119], v225 offset:32768
	ds_read_b128 v[128:131], v225 offset:33792
	ds_read_b128 v[132:135], v225 offset:34816
	ds_read_b128 v[136:139], v225 offset:35840
	ds_read_b128 v[140:143], v225 offset:49152
	ds_read_b128 v[144:147], v225 offset:50176
	ds_read_b128 v[148:151], v225 offset:51200
	ds_read_b128 v[152:155], v225 offset:52224
	s_add_u32 s16, s16, 0x20000
	s_addc_u32 s17, s17, 0
	s_mov_b32 m0, s45
	v_lshl_add_u64 v[216:217], s[16:17], 0, v[198:199]
	ds_read_b128 v[164:167], v224 offset:32768
	ds_read_b128 v[168:171], v224 offset:33792
	ds_read_b128 v[172:175], v224 offset:34816
	ds_read_b128 v[176:179], v224 offset:35840
	ds_read_b128 v[180:183], v224 offset:36864
	ds_read_b128 v[184:187], v224 offset:37888
	ds_read_b128 v[188:191], v224 offset:38912
	ds_read_b128 v[204:207], v224 offset:39936
	global_load_lds_dwordx4 v[216:217], off
	v_lshl_add_u64 v[216:217], s[16:17], 0, v[194:195]
	s_mov_b32 m0, s46
	s_nop 0
	global_load_lds_dwordx4 v[216:217], off
	s_waitcnt vmcnt(8)
	s_waitcnt lgkmcnt(0)
	s_barrier
	v_mfma_f32_16x16x32_bf16 v[160:163], v[116:119], v[164:167], v[160:163]
	v_mfma_f32_16x16x32_bf16 v[160:163], v[128:131], v[168:171], v[160:163]
	v_mfma_f32_16x16x32_bf16 v[156:159], v[132:135], v[164:167], v[156:159]
	v_mfma_f32_16x16x32_bf16 v[156:159], v[136:139], v[168:171], v[156:159]
	v_mfma_f32_16x16x32_bf16 v[112:115], v[116:119], v[172:175], v[112:115]
	v_mfma_f32_16x16x32_bf16 v[112:115], v[128:131], v[176:179], v[112:115]
	v_mfma_f32_16x16x32_bf16 v[108:111], v[132:135], v[172:175], v[108:111]
	v_mfma_f32_16x16x32_bf16 v[108:111], v[136:139], v[176:179], v[108:111]
	v_mfma_f32_16x16x32_bf16 v[96:99], v[116:119], v[180:183], v[96:99]
	v_mfma_f32_16x16x32_bf16 v[96:99], v[128:131], v[184:187], v[96:99]
	v_mfma_f32_16x16x32_bf16 v[92:95], v[132:135], v[180:183], v[92:95]
	v_mfma_f32_16x16x32_bf16 v[92:95], v[136:139], v[184:187], v[92:95]
	v_mfma_f32_16x16x32_bf16 v[80:83], v[116:119], v[188:191], v[80:83]
	v_mfma_f32_16x16x32_bf16 v[80:83], v[128:131], v[204:207], v[80:83]
	v_mfma_f32_16x16x32_bf16 v[76:79], v[132:135], v[188:191], v[76:79]
	v_mfma_f32_16x16x32_bf16 v[76:79], v[136:139], v[204:207], v[76:79]
	v_mfma_f32_16x16x32_bf16 v[124:127], v[140:143], v[164:167], v[124:127]
	v_mfma_f32_16x16x32_bf16 v[124:127], v[144:147], v[168:171], v[124:127]
	v_mfma_f32_16x16x32_bf16 v[120:123], v[148:151], v[164:167], v[120:123]
	v_mfma_f32_16x16x32_bf16 v[120:123], v[152:155], v[168:171], v[120:123]
	v_mfma_f32_16x16x32_bf16 v[104:107], v[140:143], v[172:175], v[104:107]
	v_mfma_f32_16x16x32_bf16 v[104:107], v[144:147], v[176:179], v[104:107]
	v_mfma_f32_16x16x32_bf16 v[100:103], v[148:151], v[172:175], v[100:103]
	v_mfma_f32_16x16x32_bf16 v[100:103], v[152:155], v[176:179], v[100:103]
	v_mfma_f32_16x16x32_bf16 v[88:91], v[140:143], v[180:183], v[88:91]
	v_mfma_f32_16x16x32_bf16 v[88:91], v[144:147], v[184:187], v[88:91]
	v_mfma_f32_16x16x32_bf16 v[84:87], v[148:151], v[180:183], v[84:87]
	v_mfma_f32_16x16x32_bf16 v[84:87], v[152:155], v[184:187], v[84:87]
	v_mfma_f32_16x16x32_bf16 v[72:75], v[140:143], v[188:191], v[72:75]
	v_mfma_f32_16x16x32_bf16 v[72:75], v[144:147], v[204:207], v[72:75]
	v_mfma_f32_16x16x32_bf16 v[68:71], v[148:151], v[188:191], v[68:71]
	v_mfma_f32_16x16x32_bf16 v[68:71], v[152:155], v[204:207], v[68:71]
	s_barrier
; #define PG8_STAGE(bufoff, gbase, voff) do { _Pragma("unroll") for (int _i = 0; _i < 2; ++_i) \
;         __builtin_amdgcn_global_load_lds((const unsigned*)((const char*)(gbase) + (voff)[_i]), (LAS unsigned*)(lds + (bufoff) + ldsw + _i * 8192), 16, 0, 0); } while (0)
; #define PG8_LDA(dst, b, h) do { _Pragma("unroll") for (int m = 0; m < 4; ++m) _Pragma("unroll") for (int k = 0; k < 2; ++k) dst[m][k] = *(const LAS bf16x8*)(pA + PG8_SA(b, h) + m * 2048 + k * 1024); } while (0)
; #define PG8_MMA(ai, bj, At, Bt) do { __builtin_amdgcn_s_setprio(1); _Pragma("unroll") for (int m = 0; m < 4; ++m) _Pragma("unroll") for (int n = 0; n < 2; ++n) _Pragma("unroll") for (int k = 0; k < 2; ++k) \
;         acc[ai][bj][m][n] = __builtin_amdgcn_mfma_f32_16x16x32_bf16(Bt[n][k], At[m][k], acc[ai][bj][m][n], 0, 0, 0); __builtin_amdgcn_s_setprio(0); } while (0)
; #define PG8_WAIT_V(n) asm volatile("s_waitcnt vmcnt(" #n ")" ::: "memory")
; #define PG8_WAIT_L(n) asm volatile("s_waitcnt lgkmcnt(" #n ")" ::: "memory")
; #define PG8_BAR __builtin_amdgcn_s_barrier()
; #define PG8_SCHED __builtin_amdgcn_sched_barrier(0)
; template <class Desc, class Epi, bool ALIGN_EPI>
; __device__ __forceinline__ void gemm_phase(LAS unsigned char* lds, const Desc& D, const Epi& E, int G, int c) {
;     ...
;             PG8_LDA(At, 1, 1); PG8_STAGE(PG8_SB(1, 0), b3, voffB); PG8_STAGE(PG8_SB(1, 1), b3 + hstepB, voffB); PG8_STAGE(PG8_SA(1, 0), a3, voffA);
;             PG8_WAIT_V(8); PG8_WAIT_L(0); PG8_BAR; PG8_MMA(1, 0, At, B0); PG8_MMA(1, 1, At, B1); PG8_BAR; PG8_SCHED;
;         }
;         if constexpr (ALIGN_EPI) { if (wr == 0) PG8_BAR; }
	s_mov_b32 m0, s47
	v_lshl_add_u64 v[208:209], v[208:209], 0, s[76:77]
	s_add_u32 s12, s12, 0x20080
	ds_read_b128 v[164:167], v224 offset:49152
	ds_read_b128 v[168:171], v224 offset:50176
	ds_read_b128 v[172:175], v224 offset:51200
	ds_read_b128 v[176:179], v224 offset:52224
	ds_read_b128 v[180:183], v224 offset:53248
	ds_read_b128 v[184:187], v224 offset:54272
	ds_read_b128 v[188:191], v224 offset:55296
	ds_read_b128 v[204:207], v224 offset:56320
	global_load_lds_dwordx4 v[208:209], off
	v_lshl_add_u64 v[208:209], v[210:211], 0, s[76:77]
	s_mov_b32 m0, s48
	s_addc_u32 s13, s13, 0
	global_load_lds_dwordx4 v[208:209], off
	v_lshl_add_u64 v[208:209], s[12:13], 0, v[196:197]
	s_mov_b32 m0, s51
	s_nop 0
	global_load_lds_dwordx4 v[208:209], off
	v_lshl_add_u64 v[208:209], s[12:13], 0, v[192:193]
	s_mov_b32 m0, s52
	s_nop 0
	global_load_lds_dwordx4 v[208:209], off
	v_lshl_add_u64 v[208:209], v[212:213], 0, s[76:77]
	s_mov_b32 m0, s49
	s_nop 0
	global_load_lds_dwordx4 v[208:209], off
	v_lshl_add_u64 v[208:209], v[214:215], 0, s[76:77]
	s_mov_b32 m0, s50
	s_nop 0
	global_load_lds_dwordx4 v[208:209], off
	s_waitcnt vmcnt(8)
	s_waitcnt lgkmcnt(0)
	s_barrier
	v_mfma_f32_16x16x32_bf16 v[64:67], v[116:119], v[164:167], v[64:67]
	v_mfma_f32_16x16x32_bf16 v[64:67], v[128:131], v[168:171], v[64:67]
	v_mfma_f32_16x16x32_bf16 v[60:63], v[132:135], v[164:167], v[60:63]
	v_mfma_f32_16x16x32_bf16 v[60:63], v[136:139], v[168:171], v[60:63]
	v_mfma_f32_16x16x32_bf16 v[48:51], v[116:119], v[172:175], v[48:51]
	v_mfma_f32_16x16x32_bf16 v[48:51], v[128:131], v[176:179], v[48:51]
	v_mfma_f32_16x16x32_bf16 v[44:47], v[132:135], v[172:175], v[44:47]
	v_mfma_f32_16x16x32_bf16 v[44:47], v[136:139], v[176:179], v[44:47]
	v_mfma_f32_16x16x32_bf16 v[32:35], v[116:119], v[180:183], v[32:35]
	v_mfma_f32_16x16x32_bf16 v[32:35], v[128:131], v[184:187], v[32:35]
	v_mfma_f32_16x16x32_bf16 v[28:31], v[132:135], v[180:183], v[28:31]
	v_mfma_f32_16x16x32_bf16 v[28:31], v[136:139], v[184:187], v[28:31]
	v_mfma_f32_16x16x32_bf16 v[16:19], v[116:119], v[188:191], v[16:19]
	v_mfma_f32_16x16x32_bf16 v[16:19], v[128:131], v[204:207], v[16:19]
	v_mfma_f32_16x16x32_bf16 v[12:15], v[132:135], v[188:191], v[12:15]
	v_mfma_f32_16x16x32_bf16 v[12:15], v[136:139], v[204:207], v[12:15]
	v_mfma_f32_16x16x32_bf16 v[56:59], v[140:143], v[164:167], v[56:59]
	v_mfma_f32_16x16x32_bf16 v[56:59], v[144:147], v[168:171], v[56:59]
	v_mfma_f32_16x16x32_bf16 v[52:55], v[148:151], v[164:167], v[52:55]
	v_mfma_f32_16x16x32_bf16 v[52:55], v[152:155], v[168:171], v[52:55]
	v_mfma_f32_16x16x32_bf16 v[40:43], v[140:143], v[172:175], v[40:43]
	v_mfma_f32_16x16x32_bf16 v[40:43], v[144:147], v[176:179], v[40:43]
	v_mfma_f32_16x16x32_bf16 v[36:39], v[148:151], v[172:175], v[36:39]
	v_mfma_f32_16x16x32_bf16 v[36:39], v[152:155], v[176:179], v[36:39]
	v_mfma_f32_16x16x32_bf16 v[24:27], v[140:143], v[180:183], v[24:27]
	v_mfma_f32_16x16x32_bf16 v[24:27], v[144:147], v[184:187], v[24:27]
	v_mfma_f32_16x16x32_bf16 v[20:23], v[148:151], v[180:183], v[20:23]
	v_mfma_f32_16x16x32_bf16 v[20:23], v[152:155], v[184:187], v[20:23]
	v_mfma_f32_16x16x32_bf16 v[8:11], v[140:143], v[188:191], v[8:11]
	v_mfma_f32_16x16x32_bf16 v[8:11], v[144:147], v[204:207], v[8:11]
	v_mfma_f32_16x16x32_bf16 v[4:7], v[148:151], v[188:191], v[4:7]
	v_mfma_f32_16x16x32_bf16 v[4:7], v[152:155], v[204:207], v[4:7]
	s_barrier
	s_add_i32 s54, s54, 2
	s_add_u32 s0, s0, 0x100
	s_addc_u32 s1, s1, 0
	s_add_u32 s27, s27, 0x100
	s_addc_u32 s33, s33, 0
	s_cmp_gt_u32 s54, 5
	s_cbranch_scc0 .LBB0_1517
	s_and_b64 vcc, exec, s[10:11]
	s_cbranch_vccz .LBB0_1520
	s_barrier

;     __device__ __forceinline__ int nt(const Unit& u) const { return (u.pn >> 1) < 2 ? 22 : 20; }
; #define PG8_STAGE(bufoff, gbase, voff) do { _Pragma("unroll") for (int _i = 0; _i < 2; ++_i) \
;         __builtin_amdgcn_global_load_lds((const unsigned*)((const char*)(gbase) + (voff)[_i]), (LAS unsigned*)(lds + (bufoff) + ldsw + _i * 8192), 16, 0, 0); } while (0)
; #define PG8_LDA(dst, b, h) do { _Pragma("unroll") for (int m = 0; m < 4; ++m) _Pragma("unroll") for (int k = 0; k < 2; ++k) dst[m][k] = *(const LAS bf16x8*)(pA + PG8_SA(b, h) + m * 2048 + k * 1024); } while (0)
; #define PG8_LDB(dst, b, h) do { _Pragma("unroll") for (int n = 0; n < 2; ++n) _Pragma("unroll") for (int k = 0; k < 2; ++k) dst[n][k] = *(const LAS bf16x8*)(pB + (PG8_SB(b, h) - 4 * HTB) + n * 2048 + k * 1024); } while (0)
; #define PG8_MMA(ai, bj, At, Bt) do { __builtin_amdgcn_s_setprio(1); _Pragma("unroll") for (int m = 0; m < 4; ++m) _Pragma("unroll") for (int n = 0; n < 2; ++n) _Pragma("unroll") for (int k = 0; k < 2; ++k) \
;         acc[ai][bj][m][n] = __builtin_amdgcn_mfma_f32_16x16x32_bf16(Bt[n][k], At[m][k], acc[ai][bj][m][n], 0, 0, 0); __builtin_amdgcn_s_setprio(0); } while (0)
; #define PG8_WAIT_V(n) asm volatile("s_waitcnt vmcnt(" #n ")" ::: "memory")
; #define PG8_BAR __builtin_amdgcn_s_barrier()
; template <class Desc, class Epi, bool ALIGN_EPI>
; __device__ __forceinline__ void gemm_phase(LAS unsigned char* lds, const Desc& D, const Epi& E, int G, int c) {
;     ...
;         for (int t = 0; t < nt; t += 2) {
;             const bool last = (t == nt - 2);
;             if (last && has_next) PG8_AWAIT(nxt);
;             const char* a1 = cA + (size_t)(t + 1) * kstep;
;             const char* a2 = last ? nA : cA + (size_t)(t + 2) * kstep; const char* b2 = last ? nB : cB + (size_t)(t + 2) * kstep;
;             const char* a3 = a2 + kstep; const char* b3 = b2 + kstep;
;             PG8_LDB(B0, 0, 0); PG8_LDB(B1, 0, 1); PG8_SCHED; PG8_LDA(At, 0, 0); PG8_STAGE(PG8_SA(1, 1), a1 + hstepA, voffA);
;             PG8_WAIT_V(8); PG8_WAIT_L(0); PG8_BAR; PG8_MMA(0, 0, At, B0); PG8_MMA(0, 1, At, B1); PG8_BAR; PG8_SCHED;
;             PG8_LDA(At, 0, 1); PG8_STAGE(PG8_SB(0, 0), b2, voffB); PG8_STAGE(PG8_SB(0, 1), b2 + hstepB, voffB); PG8_STAGE(PG8_SA(0, 0), a2, voffA);
;             PG8_WAIT_V(8); PG8_WAIT_L(0); PG8_BAR; PG8_MMA(1, 0, At, B0); PG8_MMA(1, 1, At, B1); PG8_BAR; PG8_SCHED;
.LBB0_1580:
	s_or_b32 s14, s30, 1
	s_add_i32 s30, s30, 2
	s_mov_b32 s31, s15
	s_lshl_b64 s[72:73], s[14:15], 7
	s_lshl_b64 s[74:75], s[30:31], 7
	s_add_u32 s14, s18, s74
	ds_read_b128 v[140:143], v163
	ds_read_b128 v[144:147], v163 offset:1024
	ds_read_b128 v[148:151], v163 offset:2048
	ds_read_b128 v[152:155], v163 offset:3072
	ds_read_b128 v[156:159], v163 offset:16384
	ds_read_b128 v[166:169], v163 offset:17408
	ds_read_b128 v[170:173], v163 offset:18432
	ds_read_b128 v[174:177], v163 offset:19456
	s_addc_u32 s31, s19, s75
	s_and_b64 s[46:47], s[34:35], exec
	s_cselect_b32 s47, s43, s31
	s_cselect_b32 s46, s42, s14
	s_add_u32 s14, s20, s74
	s_addc_u32 s31, s21, s75
	s_and_b64 s[34:35], s[34:35], exec
	s_cselect_b32 s35, s3, s31
	s_cselect_b32 s34, s13, s14
	s_add_u32 s14, s18, s72
	s_addc_u32 s31, s19, s73
	s_add_u32 s72, s14, 0x100000
	s_addc_u32 s73, s31, 0
	s_add_i32 m0, s52, 0xc000
	ds_read_b128 v[178:181], v162
	ds_read_b128 v[182:185], v162 offset:1024
	ds_read_b128 v[186:189], v162 offset:2048
	ds_read_b128 v[190:193], v162 offset:3072
	ds_read_b128 v[194:197], v162 offset:4096
	ds_read_b128 v[198:201], v162 offset:5120
	ds_read_b128 v[202:205], v162 offset:6144
	ds_read_b128 v[206:209], v162 offset:7168
	global_load_lds_dwordx4 v132, s[72:73]
	s_add_i32 m0, s52, 0xe000
	s_nop 0
	global_load_lds_dwordx4 v136, s[72:73]
	s_waitcnt vmcnt(8)
	s_waitcnt lgkmcnt(0)
	s_barrier
	v_mfma_f32_16x16x32_bf16 v[128:131], v[140:143], v[178:181], v[128:131]
	v_mfma_f32_16x16x32_bf16 v[128:131], v[144:147], v[182:185], v[128:131]
	v_mfma_f32_16x16x32_bf16 v[124:127], v[148:151], v[178:181], v[124:127]
	v_mfma_f32_16x16x32_bf16 v[124:127], v[152:155], v[182:185], v[124:127]
	v_mfma_f32_16x16x32_bf16 v[120:123], v[140:143], v[186:189], v[120:123]
	v_mfma_f32_16x16x32_bf16 v[120:123], v[144:147], v[190:193], v[120:123]
	v_mfma_f32_16x16x32_bf16 v[116:119], v[148:151], v[186:189], v[116:119]
	v_mfma_f32_16x16x32_bf16 v[116:119], v[152:155], v[190:193], v[116:119]
	v_mfma_f32_16x16x32_bf16 v[112:115], v[140:143], v[194:197], v[112:115]
	v_mfma_f32_16x16x32_bf16 v[112:115], v[144:147], v[198:201], v[112:115]
	v_mfma_f32_16x16x32_bf16 v[108:111], v[148:151], v[194:197], v[108:111]
	v_mfma_f32_16x16x32_bf16 v[108:111], v[152:155], v[198:201], v[108:111]
	v_mfma_f32_16x16x32_bf16 v[104:107], v[140:143], v[202:205], v[104:107]
	v_mfma_f32_16x16x32_bf16 v[104:107], v[144:147], v[206:209], v[104:107]
	v_mfma_f32_16x16x32_bf16 v[100:103], v[148:151], v[202:205], v[100:103]
	v_mfma_f32_16x16x32_bf16 v[100:103], v[152:155], v[206:209], v[100:103]
	v_mfma_f32_16x16x32_bf16 v[96:99], v[156:159], v[178:181], v[96:99]
	v_mfma_f32_16x16x32_bf16 v[96:99], v[166:169], v[182:185], v[96:99]
	v_mfma_f32_16x16x32_bf16 v[92:95], v[170:173], v[178:181], v[92:95]
	v_mfma_f32_16x16x32_bf16 v[92:95], v[174:177], v[182:185], v[92:95]
	v_mfma_f32_16x16x32_bf16 v[88:91], v[156:159], v[186:189], v[88:91]
	v_mfma_f32_16x16x32_bf16 v[88:91], v[166:169], v[190:193], v[88:91]
	v_mfma_f32_16x16x32_bf16 v[84:87], v[170:173], v[186:189], v[84:87]
	v_mfma_f32_16x16x32_bf16 v[84:87], v[174:177], v[190:193], v[84:87]
	v_mfma_f32_16x16x32_bf16 v[80:83], v[156:159], v[194:197], v[80:83]
	v_mfma_f32_16x16x32_bf16 v[80:83], v[166:169], v[198:201], v[80:83]
	v_mfma_f32_16x16x32_bf16 v[76:79], v[170:173], v[194:197], v[76:79]
	v_mfma_f32_16x16x32_bf16 v[76:79], v[174:177], v[198:201], v[76:79]
	v_mfma_f32_16x16x32_bf16 v[72:75], v[156:159], v[202:205], v[72:75]
	v_mfma_f32_16x16x32_bf16 v[72:75], v[166:169], v[206:209], v[72:75]
	v_mfma_f32_16x16x32_bf16 v[68:71], v[170:173], v[202:205], v[68:71]
	v_mfma_f32_16x16x32_bf16 v[68:71], v[174:177], v[206:209], v[68:71]
	s_barrier
	s_mov_b32 m0, s53
	s_add_u32 s72, s34, 0x100000
	s_addc_u32 s73, s35, 0
	ds_read_b128 v[178:181], v162 offset:16384
	ds_read_b128 v[182:185], v162 offset:17408
	ds_read_b128 v[186:189], v162 offset:18432
	ds_read_b128 v[190:193], v162 offset:19456
	ds_read_b128 v[194:197], v162 offset:20480
	ds_read_b128 v[198:201], v162 offset:21504
	ds_read_b128 v[202:205], v162 offset:22528
	ds_read_b128 v[206:209], v162 offset:23552
	global_load_lds_dwordx4 v134, s[34:35]
	s_mov_b32 m0, s54
	s_nop 0
	global_load_lds_dwordx4 v138, s[34:35]
	s_mov_b32 m0, s55
	s_nop 0
	global_load_lds_dwordx4 v134, s[72:73]
	s_mov_b32 m0, s56
	s_nop 0
	global_load_lds_dwordx4 v138, s[72:73]
	s_mov_b32 m0, s52
	s_nop 0
	global_load_lds_dwordx4 v132, s[46:47]
	s_mov_b32 m0, s57
	s_nop 0
	global_load_lds_dwordx4 v136, s[46:47]
	s_waitcnt vmcnt(8)
	s_waitcnt lgkmcnt(0)
	s_barrier
; #define PG8_STAGE(bufoff, gbase, voff) do { _Pragma("unroll") for (int _i = 0; _i < 2; ++_i) \
;         __builtin_amdgcn_global_load_lds((const unsigned*)((const char*)(gbase) + (voff)[_i]), (LAS unsigned*)(lds + (bufoff) + ldsw + _i * 8192), 16, 0, 0); } while (0)
; #define PG8_LDA(dst, b, h) do { _Pragma("unroll") for (int m = 0; m < 4; ++m) _Pragma("unroll") for (int k = 0; k < 2; ++k) dst[m][k] = *(const LAS bf16x8*)(pA + PG8_SA(b, h) + m * 2048 + k * 1024); } while (0)
; #define PG8_LDB(dst, b, h) do { _Pragma("unroll") for (int n = 0; n < 2; ++n) _Pragma("unroll") for (int k = 0; k < 2; ++k) dst[n][k] = *(const LAS bf16x8*)(pB + (PG8_SB(b, h) - 4 * HTB) + n * 2048 + k * 1024); } while (0)
; #define PG8_MMA(ai, bj, At, Bt) do { __builtin_amdgcn_s_setprio(1); _Pragma("unroll") for (int m = 0; m < 4; ++m) _Pragma("unroll") for (int n = 0; n < 2; ++n) _Pragma("unroll") for (int k = 0; k < 2; ++k) \
;         acc[ai][bj][m][n] = __builtin_amdgcn_mfma_f32_16x16x32_bf16(Bt[n][k], At[m][k], acc[ai][bj][m][n], 0, 0, 0); __builtin_amdgcn_s_setprio(0); } while (0)
; #define PG8_WAIT_V(n) asm volatile("s_waitcnt vmcnt(" #n ")" ::: "memory")
; #define PG8_WAIT_L(n) asm volatile("s_waitcnt lgkmcnt(" #n ")" ::: "memory")
; #define PG8_BAR __builtin_amdgcn_s_barrier()
; #define PG8_SCHED __builtin_amdgcn_sched_barrier(0)
; template <class Desc, class Epi, bool ALIGN_EPI>
; __device__ __forceinline__ void gemm_phase(LAS unsigned char* lds, const Desc& D, const Epi& E, int G, int c) {
;     ...
;             PG8_WAIT_V(8); PG8_WAIT_L(0); PG8_BAR; PG8_MMA(1, 0, At, B0); PG8_MMA(1, 1, At, B1); PG8_BAR; PG8_SCHED;
;             PG8_LDB(B0, 1, 0); PG8_LDB(B1, 1, 1); PG8_SCHED; PG8_LDA(At, 1, 0); PG8_STAGE(PG8_SA(0, 1), a2 + hstepA, voffA);
;             PG8_WAIT_V(8); PG8_WAIT_L(0); PG8_BAR; PG8_MMA(0, 0, At, B0); PG8_MMA(0, 1, At, B1); PG8_BAR; PG8_SCHED;
	v_mfma_f32_16x16x32_bf16 v[64:67], v[140:143], v[178:181], v[64:67]
	v_mfma_f32_16x16x32_bf16 v[64:67], v[144:147], v[182:185], v[64:67]
	v_mfma_f32_16x16x32_bf16 v[52:55], v[148:151], v[178:181], v[52:55]
	v_mfma_f32_16x16x32_bf16 v[52:55], v[152:155], v[182:185], v[52:55]
	v_mfma_f32_16x16x32_bf16 v[32:35], v[140:143], v[186:189], v[32:35]
	v_mfma_f32_16x16x32_bf16 v[32:35], v[144:147], v[190:193], v[32:35]
	v_mfma_f32_16x16x32_bf16 v[20:23], v[148:151], v[186:189], v[20:23]
	v_mfma_f32_16x16x32_bf16 v[20:23], v[152:155], v[190:193], v[20:23]
	v_mfma_f32_16x16x32_bf16 v[16:19], v[140:143], v[194:197], v[16:19]
	v_mfma_f32_16x16x32_bf16 v[16:19], v[144:147], v[198:201], v[16:19]
	v_mfma_f32_16x16x32_bf16 v[12:15], v[148:151], v[194:197], v[12:15]
	v_mfma_f32_16x16x32_bf16 v[12:15], v[152:155], v[198:201], v[12:15]
	v_mfma_f32_16x16x32_bf16 v[8:11], v[140:143], v[202:205], v[8:11]
	v_mfma_f32_16x16x32_bf16 v[8:11], v[144:147], v[206:209], v[8:11]
	v_mfma_f32_16x16x32_bf16 v[4:7], v[148:151], v[202:205], v[4:7]
	v_mfma_f32_16x16x32_bf16 v[4:7], v[152:155], v[206:209], v[4:7]
	v_mfma_f32_16x16x32_bf16 v[60:63], v[156:159], v[178:181], v[60:63]
	v_mfma_f32_16x16x32_bf16 v[60:63], v[166:169], v[182:185], v[60:63]
	v_mfma_f32_16x16x32_bf16 v[56:59], v[170:173], v[178:181], v[56:59]
	v_mfma_f32_16x16x32_bf16 v[56:59], v[174:177], v[182:185], v[56:59]
	v_mfma_f32_16x16x32_bf16 v[48:51], v[156:159], v[186:189], v[48:51]
	v_mfma_f32_16x16x32_bf16 v[48:51], v[166:169], v[190:193], v[48:51]
	v_mfma_f32_16x16x32_bf16 v[44:47], v[170:173], v[186:189], v[44:47]
	v_mfma_f32_16x16x32_bf16 v[44:47], v[174:177], v[190:193], v[44:47]
	v_mfma_f32_16x16x32_bf16 v[40:43], v[156:159], v[194:197], v[40:43]
	v_mfma_f32_16x16x32_bf16 v[40:43], v[166:169], v[198:201], v[40:43]
	v_mfma_f32_16x16x32_bf16 v[36:39], v[170:173], v[194:197], v[36:39]
	v_mfma_f32_16x16x32_bf16 v[36:39], v[174:177], v[198:201], v[36:39]
	v_mfma_f32_16x16x32_bf16 v[28:31], v[156:159], v[202:205], v[28:31]
	v_mfma_f32_16x16x32_bf16 v[28:31], v[166:169], v[206:209], v[28:31]
	v_mfma_f32_16x16x32_bf16 v[24:27], v[170:173], v[202:205], v[24:27]
	v_mfma_f32_16x16x32_bf16 v[24:27], v[174:177], v[206:209], v[24:27]
	s_barrier
	ds_read_b128 v[140:143], v163 offset:32768
	ds_read_b128 v[144:147], v163 offset:33792
	ds_read_b128 v[148:151], v163 offset:34816
	ds_read_b128 v[152:155], v163 offset:35840
	ds_read_b128 v[156:159], v163 offset:49152
	ds_read_b128 v[166:169], v163 offset:50176
	ds_read_b128 v[170:173], v163 offset:51200
	ds_read_b128 v[174:177], v163 offset:52224
	s_add_u32 s46, s46, 0x100000
	s_addc_u32 s47, s47, 0
	s_mov_b32 m0, s58
	ds_read_b128 v[178:181], v162 offset:32768
	ds_read_b128 v[182:185], v162 offset:33792
	ds_read_b128 v[186:189], v162 offset:34816
	ds_read_b128 v[190:193], v162 offset:35840
	ds_read_b128 v[194:197], v162 offset:36864
	ds_read_b128 v[198:201], v162 offset:37888
	ds_read_b128 v[202:205], v162 offset:38912
	ds_read_b128 v[206:209], v162 offset:39936
	global_load_lds_dwordx4 v132, s[46:47]
	s_mov_b32 m0, s59
	s_nop 0
	global_load_lds_dwordx4 v136, s[46:47]
	s_waitcnt vmcnt(8)
	s_waitcnt lgkmcnt(0)
	s_barrier
	v_mfma_f32_16x16x32_bf16 v[128:131], v[140:143], v[178:181], v[128:131]
	v_mfma_f32_16x16x32_bf16 v[128:131], v[144:147], v[182:185], v[128:131]
	v_mfma_f32_16x16x32_bf16 v[124:127], v[148:151], v[178:181], v[124:127]
	v_mfma_f32_16x16x32_bf16 v[124:127], v[152:155], v[182:185], v[124:127]
	v_mfma_f32_16x16x32_bf16 v[120:123], v[140:143], v[186:189], v[120:123]
	v_mfma_f32_16x16x32_bf16 v[120:123], v[144:147], v[190:193], v[120:123]
	v_mfma_f32_16x16x32_bf16 v[116:119], v[148:151], v[186:189], v[116:119]
	v_mfma_f32_16x16x32_bf16 v[116:119], v[152:155], v[190:193], v[116:119]
	v_mfma_f32_16x16x32_bf16 v[112:115], v[140:143], v[194:197], v[112:115]
	v_mfma_f32_16x16x32_bf16 v[112:115], v[144:147], v[198:201], v[112:115]
	v_mfma_f32_16x16x32_bf16 v[108:111], v[148:151], v[194:197], v[108:111]
	v_mfma_f32_16x16x32_bf16 v[108:111], v[152:155], v[198:201], v[108:111]
	v_mfma_f32_16x16x32_bf16 v[104:107], v[140:143], v[202:205], v[104:107]
	v_mfma_f32_16x16x32_bf16 v[104:107], v[144:147], v[206:209], v[104:107]
	v_mfma_f32_16x16x32_bf16 v[100:103], v[148:151], v[202:205], v[100:103]
	v_mfma_f32_16x16x32_bf16 v[100:103], v[152:155], v[206:209], v[100:103]
	v_mfma_f32_16x16x32_bf16 v[96:99], v[156:159], v[178:181], v[96:99]
	v_mfma_f32_16x16x32_bf16 v[96:99], v[166:169], v[182:185], v[96:99]
	v_mfma_f32_16x16x32_bf16 v[92:95], v[170:173], v[178:181], v[92:95]
	v_mfma_f32_16x16x32_bf16 v[92:95], v[174:177], v[182:185], v[92:95]
	v_mfma_f32_16x16x32_bf16 v[88:91], v[156:159], v[186:189], v[88:91]
	v_mfma_f32_16x16x32_bf16 v[88:91], v[166:169], v[190:193], v[88:91]
	v_mfma_f32_16x16x32_bf16 v[84:87], v[170:173], v[186:189], v[84:87]
	v_mfma_f32_16x16x32_bf16 v[84:87], v[174:177], v[190:193], v[84:87]
	v_mfma_f32_16x16x32_bf16 v[80:83], v[156:159], v[194:197], v[80:83]
	v_mfma_f32_16x16x32_bf16 v[80:83], v[166:169], v[198:201], v[80:83]
	v_mfma_f32_16x16x32_bf16 v[76:79], v[170:173], v[194:197], v[76:79]
	v_mfma_f32_16x16x32_bf16 v[76:79], v[174:177], v[198:201], v[76:79]
	v_mfma_f32_16x16x32_bf16 v[72:75], v[156:159], v[202:205], v[72:75]
	v_mfma_f32_16x16x32_bf16 v[72:75], v[166:169], v[206:209], v[72:75]
	v_mfma_f32_16x16x32_bf16 v[68:71], v[170:173], v[202:205], v[68:71]
	v_mfma_f32_16x16x32_bf16 v[68:71], v[174:177], v[206:209], v[68:71]
	s_barrier
; #define PG8_STAGE(bufoff, gbase, voff) do { _Pragma("unroll") for (int _i = 0; _i < 2; ++_i) \
;         __builtin_amdgcn_global_load_lds((const unsigned*)((const char*)(gbase) + (voff)[_i]), (LAS unsigned*)(lds + (bufoff) + ldsw + _i * 8192), 16, 0, 0); } while (0)
; #define PG8_LDA(dst, b, h) do { _Pragma("unroll") for (int m = 0; m < 4; ++m) _Pragma("unroll") for (int k = 0; k < 2; ++k) dst[m][k] = *(const LAS bf16x8*)(pA + PG8_SA(b, h) + m * 2048 + k * 1024); } while (0)
; #define PG8_MMA(ai, bj, At, Bt) do { __builtin_amdgcn_s_setprio(1); _Pragma("unroll") for (int m = 0; m < 4; ++m) _Pragma("unroll") for (int n = 0; n < 2; ++n) _Pragma("unroll") for (int k = 0; k < 2; ++k) \
;         acc[ai][bj][m][n] = __builtin_amdgcn_mfma_f32_16x16x32_bf16(Bt[n][k], At[m][k], acc[ai][bj][m][n], 0, 0, 0); __builtin_amdgcn_s_setprio(0); } while (0)
; #define PG8_WAIT_V(n) asm volatile("s_waitcnt vmcnt(" #n ")" ::: "memory")
; #define PG8_WAIT_L(n) asm volatile("s_waitcnt lgkmcnt(" #n ")" ::: "memory")
; #define PG8_BAR __builtin_amdgcn_s_barrier()
; #define PG8_SCHED __builtin_amdgcn_sched_barrier(0)
; template <class Desc, class Epi, bool ALIGN_EPI>
; __device__ __forceinline__ void gemm_phase(LAS unsigned char* lds, const Desc& D, const Epi& E, int G, int c) {
;     ...
;             PG8_LDA(At, 1, 1); PG8_STAGE(PG8_SB(1, 0), b3, voffB); PG8_STAGE(PG8_SB(1, 1), b3 + hstepB, voffB); PG8_STAGE(PG8_SA(1, 0), a3, voffA);
;             PG8_WAIT_V(8); PG8_WAIT_L(0); PG8_BAR; PG8_MMA(1, 0, At, B0); PG8_MMA(1, 1, At, B1); PG8_BAR; PG8_SCHED;
;         }
	s_mov_b32 m0, s61
	s_add_u32 s74, s34, 0x80
	s_addc_u32 s75, s35, 0
	s_add_u32 s34, s34, 0x100080
	s_addc_u32 s35, s35, 0
	ds_read_b128 v[178:181], v162 offset:49152
	ds_read_b128 v[182:185], v162 offset:50176
	ds_read_b128 v[186:189], v162 offset:51200
	ds_read_b128 v[190:193], v162 offset:52224
	ds_read_b128 v[194:197], v162 offset:53248
	ds_read_b128 v[198:201], v162 offset:54272
	ds_read_b128 v[202:205], v162 offset:55296
	ds_read_b128 v[206:209], v162 offset:56320
	global_load_lds_dwordx4 v134, s[74:75]
	s_mov_b32 m0, s62
	s_nop 0
	global_load_lds_dwordx4 v138, s[74:75]
	s_mov_b32 m0, s65
	s_nop 0
	global_load_lds_dwordx4 v134, s[34:35]
	s_mov_b32 m0, s67
	s_nop 0
	global_load_lds_dwordx4 v138, s[34:35]
	s_sub_u32 s74, s46, 0xfff80
	s_subb_u32 s75, s47, 0
	s_mov_b32 m0, s63
	s_nop 0
	global_load_lds_dwordx4 v132, s[74:75]
	s_mov_b32 m0, s64
	s_nop 0
	global_load_lds_dwordx4 v136, s[74:75]
	s_waitcnt vmcnt(8)
	s_waitcnt lgkmcnt(0)
	s_barrier
	v_mfma_f32_16x16x32_bf16 v[64:67], v[140:143], v[178:181], v[64:67]
	v_mfma_f32_16x16x32_bf16 v[64:67], v[144:147], v[182:185], v[64:67]
	v_mfma_f32_16x16x32_bf16 v[52:55], v[148:151], v[178:181], v[52:55]
	v_mfma_f32_16x16x32_bf16 v[52:55], v[152:155], v[182:185], v[52:55]
	v_mfma_f32_16x16x32_bf16 v[32:35], v[140:143], v[186:189], v[32:35]
	v_mfma_f32_16x16x32_bf16 v[32:35], v[144:147], v[190:193], v[32:35]
	v_mfma_f32_16x16x32_bf16 v[20:23], v[148:151], v[186:189], v[20:23]
	v_mfma_f32_16x16x32_bf16 v[20:23], v[152:155], v[190:193], v[20:23]
	v_mfma_f32_16x16x32_bf16 v[16:19], v[140:143], v[194:197], v[16:19]
	v_mfma_f32_16x16x32_bf16 v[16:19], v[144:147], v[198:201], v[16:19]
	v_mfma_f32_16x16x32_bf16 v[12:15], v[148:151], v[194:197], v[12:15]
	v_mfma_f32_16x16x32_bf16 v[12:15], v[152:155], v[198:201], v[12:15]
	v_mfma_f32_16x16x32_bf16 v[8:11], v[140:143], v[202:205], v[8:11]
	v_mfma_f32_16x16x32_bf16 v[8:11], v[144:147], v[206:209], v[8:11]
	v_mfma_f32_16x16x32_bf16 v[4:7], v[148:151], v[202:205], v[4:7]
	v_mfma_f32_16x16x32_bf16 v[4:7], v[152:155], v[206:209], v[4:7]
	v_mfma_f32_16x16x32_bf16 v[60:63], v[156:159], v[178:181], v[60:63]
	v_mfma_f32_16x16x32_bf16 v[60:63], v[166:169], v[182:185], v[60:63]
	v_mfma_f32_16x16x32_bf16 v[56:59], v[170:173], v[178:181], v[56:59]
	v_mfma_f32_16x16x32_bf16 v[56:59], v[174:177], v[182:185], v[56:59]
	v_mfma_f32_16x16x32_bf16 v[48:51], v[156:159], v[186:189], v[48:51]
	v_mfma_f32_16x16x32_bf16 v[48:51], v[166:169], v[190:193], v[48:51]
	v_mfma_f32_16x16x32_bf16 v[44:47], v[170:173], v[186:189], v[44:47]
	v_mfma_f32_16x16x32_bf16 v[44:47], v[174:177], v[190:193], v[44:47]
	v_mfma_f32_16x16x32_bf16 v[40:43], v[156:159], v[194:197], v[40:43]
	v_mfma_f32_16x16x32_bf16 v[40:43], v[166:169], v[198:201], v[40:43]
	v_mfma_f32_16x16x32_bf16 v[36:39], v[170:173], v[194:197], v[36:39]
	v_mfma_f32_16x16x32_bf16 v[36:39], v[174:177], v[198:201], v[36:39]
	v_mfma_f32_16x16x32_bf16 v[28:31], v[156:159], v[202:205], v[28:31]
	v_mfma_f32_16x16x32_bf16 v[28:31], v[166:169], v[206:209], v[28:31]
	v_mfma_f32_16x16x32_bf16 v[24:27], v[170:173], v[202:205], v[24:27]
	v_mfma_f32_16x16x32_bf16 v[24:27], v[174:177], v[206:209], v[24:27]
	s_barrier
	s_cmp_ge_u32 s30, s2
	s_cbranch_scc1 .LBB0_1591

;     __device__ __forceinline__ int nt(const Unit& u) const { return (u.pn >> 1) < 2 ? 22 : 20; }
; #define PG8_STAGE(bufoff, gbase, voff) do { _Pragma("unroll") for (int _i = 0; _i < 2; ++_i) \
;         __builtin_amdgcn_global_load_lds((const unsigned*)((const char*)(gbase) + (voff)[_i]), (LAS unsigned*)(lds + (bufoff) + ldsw + _i * 8192), 16, 0, 0); } while (0)
; #define PG8_LDA(dst, b, h) do { _Pragma("unroll") for (int m = 0; m < 4; ++m) _Pragma("unroll") for (int k = 0; k < 2; ++k) dst[m][k] = *(const LAS bf16x8*)(pA + PG8_SA(b, h) + m * 2048 + k * 1024); } while (0)
; #define PG8_LDB(dst, b, h) do { _Pragma("unroll") for (int n = 0; n < 2; ++n) _Pragma("unroll") for (int k = 0; k < 2; ++k) dst[n][k] = *(const LAS bf16x8*)(pB + (PG8_SB(b, h) - 4 * HTB) + n * 2048 + k * 1024); } while (0)
; #define PG8_MMA(ai, bj, At, Bt) do { __builtin_amdgcn_s_setprio(1); _Pragma("unroll") for (int m = 0; m < 4; ++m) _Pragma("unroll") for (int n = 0; n < 2; ++n) _Pragma("unroll") for (int k = 0; k < 2; ++k) \
;         acc[ai][bj][m][n] = __builtin_amdgcn_mfma_f32_16x16x32_bf16(Bt[n][k], At[m][k], acc[ai][bj][m][n], 0, 0, 0); __builtin_amdgcn_s_setprio(0); } while (0)
; #define PG8_WAIT_V(n) asm volatile("s_waitcnt vmcnt(" #n ")" ::: "memory")
; #define PG8_BAR __builtin_amdgcn_s_barrier()
; template <class Desc, class Epi, bool ALIGN_EPI>
; __device__ __forceinline__ void gemm_phase(LAS unsigned char* lds, const Desc& D, const Epi& E, int G, int c) {
;     ...
;         for (int t = 0; t < nt; t += 2) {
;             const bool last = (t == nt - 2);
;             if (last && has_next) PG8_AWAIT(nxt);
;             const char* a1 = cA + (size_t)(t + 1) * kstep;
;             const char* a2 = last ? nA : cA + (size_t)(t + 2) * kstep; const char* b2 = last ? nB : cB + (size_t)(t + 2) * kstep;
;             const char* a3 = a2 + kstep; const char* b3 = b2 + kstep;
;             PG8_LDB(B0, 0, 0); PG8_LDB(B1, 0, 1); PG8_SCHED; PG8_LDA(At, 0, 0); PG8_STAGE(PG8_SA(1, 1), a1 + hstepA, voffA);
;             PG8_WAIT_V(8); PG8_WAIT_L(0); PG8_BAR; PG8_MMA(0, 0, At, B0); PG8_MMA(0, 1, At, B1); PG8_BAR; PG8_SCHED;
;             PG8_LDA(At, 0, 1); PG8_STAGE(PG8_SB(0, 0), b2, voffB); PG8_STAGE(PG8_SB(0, 1), b2 + hstepB, voffB); PG8_STAGE(PG8_SA(0, 0), a2, voffA);
;             PG8_WAIT_V(8); PG8_WAIT_L(0); PG8_BAR; PG8_MMA(1, 0, At, B0); PG8_MMA(1, 1, At, B1); PG8_BAR; PG8_SCHED;
.LBB0_1765:
	s_or_b32 s14, s39, 1
	s_lshl_b64 s[40:41], s[14:15], 7
	s_add_i32 s14, s39, 2
	s_lshl_b64 s[42:43], s[14:15], 7
	s_add_u32 s39, s12, s42
	s_waitcnt lgkmcnt(0)
	ds_read_b128 v[132:135], v248
	ds_read_b128 v[136:139], v248 offset:1024
	ds_read_b128 v[140:143], v248 offset:2048
	ds_read_b128 v[144:147], v248 offset:3072
	ds_read_b128 v[148:151], v248 offset:16384
	ds_read_b128 v[152:155], v248 offset:17408
	ds_read_b128 v[156:159], v248 offset:18432
	ds_read_b128 v[160:163], v248 offset:19456
	s_addc_u32 s78, s13, s43
	s_and_b64 s[30:31], s[20:21], exec
	s_cselect_b32 s31, s49, s78
	s_cselect_b32 s30, s48, s39
	s_add_u32 s39, s16, s42
	s_addc_u32 s42, s17, s43
	s_and_b64 s[20:21], s[20:21], exec
	s_cselect_b32 s21, s51, s42
	s_cselect_b32 s20, s50, s39
	s_add_u32 s39, s12, s40
	s_addc_u32 s41, s13, s41
	s_add_u32 s40, s39, 0x2b0000
	s_addc_u32 s41, s41, 0
	v_lshl_add_u64 v[196:197], s[40:41], 0, v[200:201]
	s_add_i32 m0, s56, 0xc000
	ds_read_b128 v[164:167], v247
	ds_read_b128 v[168:171], v247 offset:1024
	ds_read_b128 v[172:175], v247 offset:2048
	ds_read_b128 v[176:179], v247 offset:3072
	ds_read_b128 v[180:183], v247 offset:4096
	ds_read_b128 v[184:187], v247 offset:5120
	ds_read_b128 v[188:191], v247 offset:6144
	ds_read_b128 v[192:195], v247 offset:7168
	global_load_lds_dwordx4 v[196:197], off
	v_lshl_add_u64 v[196:197], s[40:41], 0, v[204:205]
	s_add_i32 m0, s56, 0xe000
	s_nop 0
	global_load_lds_dwordx4 v[196:197], off
	s_waitcnt vmcnt(8)
	s_waitcnt lgkmcnt(0)
	s_barrier
	v_mfma_f32_16x16x32_bf16 v[128:131], v[132:135], v[164:167], v[128:131]
	v_mfma_f32_16x16x32_bf16 v[128:131], v[136:139], v[168:171], v[128:131]
	v_mfma_f32_16x16x32_bf16 v[124:127], v[140:143], v[164:167], v[124:127]
	v_mfma_f32_16x16x32_bf16 v[124:127], v[144:147], v[168:171], v[124:127]
	v_mfma_f32_16x16x32_bf16 v[120:123], v[132:135], v[172:175], v[120:123]
	v_mfma_f32_16x16x32_bf16 v[120:123], v[136:139], v[176:179], v[120:123]
	v_mfma_f32_16x16x32_bf16 v[116:119], v[140:143], v[172:175], v[116:119]
	v_mfma_f32_16x16x32_bf16 v[116:119], v[144:147], v[176:179], v[116:119]
	v_mfma_f32_16x16x32_bf16 v[112:115], v[132:135], v[180:183], v[112:115]
	v_mfma_f32_16x16x32_bf16 v[112:115], v[136:139], v[184:187], v[112:115]
	v_mfma_f32_16x16x32_bf16 v[108:111], v[140:143], v[180:183], v[108:111]
	v_mfma_f32_16x16x32_bf16 v[108:111], v[144:147], v[184:187], v[108:111]
	v_mfma_f32_16x16x32_bf16 v[104:107], v[132:135], v[188:191], v[104:107]
	v_mfma_f32_16x16x32_bf16 v[104:107], v[136:139], v[192:195], v[104:107]
	v_mfma_f32_16x16x32_bf16 v[100:103], v[140:143], v[188:191], v[100:103]
	v_mfma_f32_16x16x32_bf16 v[100:103], v[144:147], v[192:195], v[100:103]
	v_mfma_f32_16x16x32_bf16 v[96:99], v[148:151], v[164:167], v[96:99]
	v_mfma_f32_16x16x32_bf16 v[96:99], v[152:155], v[168:171], v[96:99]
	v_mfma_f32_16x16x32_bf16 v[92:95], v[156:159], v[164:167], v[92:95]
	v_mfma_f32_16x16x32_bf16 v[92:95], v[160:163], v[168:171], v[92:95]
	v_mfma_f32_16x16x32_bf16 v[88:91], v[148:151], v[172:175], v[88:91]
	v_mfma_f32_16x16x32_bf16 v[88:91], v[152:155], v[176:179], v[88:91]
	v_mfma_f32_16x16x32_bf16 v[80:83], v[156:159], v[172:175], v[80:83]
	v_mfma_f32_16x16x32_bf16 v[80:83], v[160:163], v[176:179], v[80:83]
	v_mfma_f32_16x16x32_bf16 v[64:67], v[148:151], v[180:183], v[64:67]
	v_mfma_f32_16x16x32_bf16 v[64:67], v[152:155], v[184:187], v[64:67]
	v_mfma_f32_16x16x32_bf16 v[52:55], v[156:159], v[180:183], v[52:55]
	v_mfma_f32_16x16x32_bf16 v[52:55], v[160:163], v[184:187], v[52:55]
	v_mfma_f32_16x16x32_bf16 v[32:35], v[148:151], v[188:191], v[32:35]
	v_mfma_f32_16x16x32_bf16 v[32:35], v[152:155], v[192:195], v[32:35]
	v_mfma_f32_16x16x32_bf16 v[20:23], v[156:159], v[188:191], v[20:23]
	v_mfma_f32_16x16x32_bf16 v[20:23], v[160:163], v[192:195], v[20:23]
	s_barrier
	s_mov_b32 m0, s57
	v_lshl_add_u64 v[196:197], s[20:21], 0, v[202:203]
	s_add_u32 s40, s20, 0x2b0000
	ds_read_b128 v[164:167], v247 offset:16384
	ds_read_b128 v[168:171], v247 offset:17408
	ds_read_b128 v[172:175], v247 offset:18432
	ds_read_b128 v[176:179], v247 offset:19456
	ds_read_b128 v[180:183], v247 offset:20480
	ds_read_b128 v[184:187], v247 offset:21504
	ds_read_b128 v[188:191], v247 offset:22528
	ds_read_b128 v[192:195], v247 offset:23552
	global_load_lds_dwordx4 v[196:197], off
	v_lshl_add_u64 v[198:199], s[20:21], 0, v[206:207]
	s_mov_b32 m0, s58
	s_addc_u32 s41, s21, 0
	global_load_lds_dwordx4 v[198:199], off
	v_lshl_add_u64 v[208:209], s[40:41], 0, v[202:203]
	s_mov_b32 m0, s59
	v_lshl_add_u64 v[210:211], s[30:31], 0, v[204:205]
	global_load_lds_dwordx4 v[208:209], off
	v_lshl_add_u64 v[208:209], s[40:41], 0, v[206:207]
	s_mov_b32 m0, s60
	s_nop 0
	global_load_lds_dwordx4 v[208:209], off
	v_lshl_add_u64 v[208:209], s[30:31], 0, v[200:201]
	s_mov_b32 m0, s56
	s_nop 0
	global_load_lds_dwordx4 v[208:209], off
	s_mov_b32 m0, s61
	s_nop 0
	global_load_lds_dwordx4 v[210:211], off
	s_waitcnt vmcnt(8)
	s_waitcnt lgkmcnt(0)
	s_barrier
; #define PG8_STAGE(bufoff, gbase, voff) do { _Pragma("unroll") for (int _i = 0; _i < 2; ++_i) \
;         __builtin_amdgcn_global_load_lds((const unsigned*)((const char*)(gbase) + (voff)[_i]), (LAS unsigned*)(lds + (bufoff) + ldsw + _i * 8192), 16, 0, 0); } while (0)
; #define PG8_LDA(dst, b, h) do { _Pragma("unroll") for (int m = 0; m < 4; ++m) _Pragma("unroll") for (int k = 0; k < 2; ++k) dst[m][k] = *(const LAS bf16x8*)(pA + PG8_SA(b, h) + m * 2048 + k * 1024); } while (0)
; #define PG8_LDB(dst, b, h) do { _Pragma("unroll") for (int n = 0; n < 2; ++n) _Pragma("unroll") for (int k = 0; k < 2; ++k) dst[n][k] = *(const LAS bf16x8*)(pB + (PG8_SB(b, h) - 4 * HTB) + n * 2048 + k * 1024); } while (0)
; #define PG8_MMA(ai, bj, At, Bt) do { __builtin_amdgcn_s_setprio(1); _Pragma("unroll") for (int m = 0; m < 4; ++m) _Pragma("unroll") for (int n = 0; n < 2; ++n) _Pragma("unroll") for (int k = 0; k < 2; ++k) \
;         acc[ai][bj][m][n] = __builtin_amdgcn_mfma_f32_16x16x32_bf16(Bt[n][k], At[m][k], acc[ai][bj][m][n], 0, 0, 0); __builtin_amdgcn_s_setprio(0); } while (0)
; #define PG8_WAIT_V(n) asm volatile("s_waitcnt vmcnt(" #n ")" ::: "memory")
; #define PG8_WAIT_L(n) asm volatile("s_waitcnt lgkmcnt(" #n ")" ::: "memory")
; #define PG8_BAR __builtin_amdgcn_s_barrier()
; #define PG8_SCHED __builtin_amdgcn_sched_barrier(0)
; template <class Desc, class Epi, bool ALIGN_EPI>
; __device__ __forceinline__ void gemm_phase(LAS unsigned char* lds, const Desc& D, const Epi& E, int G, int c) {
;     ...
;             PG8_WAIT_V(8); PG8_WAIT_L(0); PG8_BAR; PG8_MMA(1, 0, At, B0); PG8_MMA(1, 1, At, B1); PG8_BAR; PG8_SCHED;
;             PG8_LDB(B0, 1, 0); PG8_LDB(B1, 1, 1); PG8_SCHED; PG8_LDA(At, 1, 0); PG8_STAGE(PG8_SA(0, 1), a2 + hstepA, voffA);
;             PG8_WAIT_V(8); PG8_WAIT_L(0); PG8_BAR; PG8_MMA(0, 0, At, B0); PG8_MMA(0, 1, At, B1); PG8_BAR; PG8_SCHED;
	v_mfma_f32_16x16x32_bf16 v[84:87], v[132:135], v[164:167], v[84:87]
	v_mfma_f32_16x16x32_bf16 v[84:87], v[136:139], v[168:171], v[84:87]
	v_mfma_f32_16x16x32_bf16 v[76:79], v[140:143], v[164:167], v[76:79]
	v_mfma_f32_16x16x32_bf16 v[76:79], v[144:147], v[168:171], v[76:79]
	v_mfma_f32_16x16x32_bf16 v[72:75], v[132:135], v[172:175], v[72:75]
	v_mfma_f32_16x16x32_bf16 v[72:75], v[136:139], v[176:179], v[72:75]
	v_mfma_f32_16x16x32_bf16 v[68:71], v[140:143], v[172:175], v[68:71]
	v_mfma_f32_16x16x32_bf16 v[68:71], v[144:147], v[176:179], v[68:71]
	v_mfma_f32_16x16x32_bf16 v[60:63], v[132:135], v[180:183], v[60:63]
	v_mfma_f32_16x16x32_bf16 v[60:63], v[136:139], v[184:187], v[60:63]
	v_mfma_f32_16x16x32_bf16 v[56:59], v[140:143], v[180:183], v[56:59]
	v_mfma_f32_16x16x32_bf16 v[56:59], v[144:147], v[184:187], v[56:59]
	v_mfma_f32_16x16x32_bf16 v[48:51], v[132:135], v[188:191], v[48:51]
	v_mfma_f32_16x16x32_bf16 v[48:51], v[136:139], v[192:195], v[48:51]
	v_mfma_f32_16x16x32_bf16 v[44:47], v[140:143], v[188:191], v[44:47]
	v_mfma_f32_16x16x32_bf16 v[44:47], v[144:147], v[192:195], v[44:47]
	v_mfma_f32_16x16x32_bf16 v[40:43], v[148:151], v[164:167], v[40:43]
	v_mfma_f32_16x16x32_bf16 v[40:43], v[152:155], v[168:171], v[40:43]
	v_mfma_f32_16x16x32_bf16 v[36:39], v[156:159], v[164:167], v[36:39]
	v_mfma_f32_16x16x32_bf16 v[36:39], v[160:163], v[168:171], v[36:39]
	v_mfma_f32_16x16x32_bf16 v[28:31], v[148:151], v[172:175], v[28:31]
	v_mfma_f32_16x16x32_bf16 v[28:31], v[152:155], v[176:179], v[28:31]
	v_mfma_f32_16x16x32_bf16 v[24:27], v[156:159], v[172:175], v[24:27]
	v_mfma_f32_16x16x32_bf16 v[24:27], v[160:163], v[176:179], v[24:27]
	v_mfma_f32_16x16x32_bf16 v[16:19], v[148:151], v[180:183], v[16:19]
	v_mfma_f32_16x16x32_bf16 v[16:19], v[152:155], v[184:187], v[16:19]
	v_mfma_f32_16x16x32_bf16 v[12:15], v[156:159], v[180:183], v[12:15]
	v_mfma_f32_16x16x32_bf16 v[12:15], v[160:163], v[184:187], v[12:15]
	v_mfma_f32_16x16x32_bf16 v[8:11], v[148:151], v[188:191], v[8:11]
	v_mfma_f32_16x16x32_bf16 v[8:11], v[152:155], v[192:195], v[8:11]
	v_mfma_f32_16x16x32_bf16 v[4:7], v[156:159], v[188:191], v[4:7]
	v_mfma_f32_16x16x32_bf16 v[4:7], v[160:163], v[192:195], v[4:7]
	s_barrier
	ds_read_b128 v[132:135], v248 offset:32768
	ds_read_b128 v[136:139], v248 offset:33792
	ds_read_b128 v[140:143], v248 offset:34816
	ds_read_b128 v[144:147], v248 offset:35840
	ds_read_b128 v[148:151], v248 offset:49152
	ds_read_b128 v[152:155], v248 offset:50176
	ds_read_b128 v[156:159], v248 offset:51200
	ds_read_b128 v[160:163], v248 offset:52224
	s_add_u32 s30, s30, 0x2b0000
	s_addc_u32 s31, s31, 0
	s_mov_b32 m0, s62
	v_lshl_add_u64 v[212:213], s[30:31], 0, v[200:201]
	ds_read_b128 v[164:167], v247 offset:32768
	ds_read_b128 v[168:171], v247 offset:33792
	ds_read_b128 v[172:175], v247 offset:34816
	ds_read_b128 v[176:179], v247 offset:35840
	ds_read_b128 v[180:183], v247 offset:36864
	ds_read_b128 v[184:187], v247 offset:37888
	ds_read_b128 v[188:191], v247 offset:38912
	ds_read_b128 v[192:195], v247 offset:39936
	global_load_lds_dwordx4 v[212:213], off
	v_lshl_add_u64 v[212:213], s[30:31], 0, v[204:205]
	s_mov_b32 m0, s63
	s_nop 0
	global_load_lds_dwordx4 v[212:213], off
	s_waitcnt vmcnt(8)
	s_waitcnt lgkmcnt(0)
	s_barrier
	v_mfma_f32_16x16x32_bf16 v[128:131], v[132:135], v[164:167], v[128:131]
	v_mfma_f32_16x16x32_bf16 v[128:131], v[136:139], v[168:171], v[128:131]
	v_mfma_f32_16x16x32_bf16 v[124:127], v[140:143], v[164:167], v[124:127]
	v_mfma_f32_16x16x32_bf16 v[124:127], v[144:147], v[168:171], v[124:127]
	v_mfma_f32_16x16x32_bf16 v[120:123], v[132:135], v[172:175], v[120:123]
	v_mfma_f32_16x16x32_bf16 v[120:123], v[136:139], v[176:179], v[120:123]
	v_mfma_f32_16x16x32_bf16 v[116:119], v[140:143], v[172:175], v[116:119]
	v_mfma_f32_16x16x32_bf16 v[116:119], v[144:147], v[176:179], v[116:119]
	v_mfma_f32_16x16x32_bf16 v[112:115], v[132:135], v[180:183], v[112:115]
	v_mfma_f32_16x16x32_bf16 v[112:115], v[136:139], v[184:187], v[112:115]
	v_mfma_f32_16x16x32_bf16 v[108:111], v[140:143], v[180:183], v[108:111]
	v_mfma_f32_16x16x32_bf16 v[108:111], v[144:147], v[184:187], v[108:111]
	v_mfma_f32_16x16x32_bf16 v[104:107], v[132:135], v[188:191], v[104:107]
	v_mfma_f32_16x16x32_bf16 v[104:107], v[136:139], v[192:195], v[104:107]
	v_mfma_f32_16x16x32_bf16 v[100:103], v[140:143], v[188:191], v[100:103]
	v_mfma_f32_16x16x32_bf16 v[100:103], v[144:147], v[192:195], v[100:103]
	v_mfma_f32_16x16x32_bf16 v[96:99], v[148:151], v[164:167], v[96:99]
	v_mfma_f32_16x16x32_bf16 v[96:99], v[152:155], v[168:171], v[96:99]
	v_mfma_f32_16x16x32_bf16 v[92:95], v[156:159], v[164:167], v[92:95]
	v_mfma_f32_16x16x32_bf16 v[92:95], v[160:163], v[168:171], v[92:95]
	v_mfma_f32_16x16x32_bf16 v[88:91], v[148:151], v[172:175], v[88:91]
	v_mfma_f32_16x16x32_bf16 v[88:91], v[152:155], v[176:179], v[88:91]
	v_mfma_f32_16x16x32_bf16 v[80:83], v[156:159], v[172:175], v[80:83]
	v_mfma_f32_16x16x32_bf16 v[80:83], v[160:163], v[176:179], v[80:83]
	v_mfma_f32_16x16x32_bf16 v[64:67], v[148:151], v[180:183], v[64:67]
	v_mfma_f32_16x16x32_bf16 v[64:67], v[152:155], v[184:187], v[64:67]
	v_mfma_f32_16x16x32_bf16 v[52:55], v[156:159], v[180:183], v[52:55]
	v_mfma_f32_16x16x32_bf16 v[52:55], v[160:163], v[184:187], v[52:55]
	v_mfma_f32_16x16x32_bf16 v[32:35], v[148:151], v[188:191], v[32:35]
	v_mfma_f32_16x16x32_bf16 v[32:35], v[152:155], v[192:195], v[32:35]
	v_mfma_f32_16x16x32_bf16 v[20:23], v[156:159], v[188:191], v[20:23]
	v_mfma_f32_16x16x32_bf16 v[20:23], v[160:163], v[192:195], v[20:23]
	s_barrier
; #define PG8_STAGE(bufoff, gbase, voff) do { _Pragma("unroll") for (int _i = 0; _i < 2; ++_i) \
;         __builtin_amdgcn_global_load_lds((const unsigned*)((const char*)(gbase) + (voff)[_i]), (LAS unsigned*)(lds + (bufoff) + ldsw + _i * 8192), 16, 0, 0); } while (0)
; #define PG8_LDA(dst, b, h) do { _Pragma("unroll") for (int m = 0; m < 4; ++m) _Pragma("unroll") for (int k = 0; k < 2; ++k) dst[m][k] = *(const LAS bf16x8*)(pA + PG8_SA(b, h) + m * 2048 + k * 1024); } while (0)
; #define PG8_MMA(ai, bj, At, Bt) do { __builtin_amdgcn_s_setprio(1); _Pragma("unroll") for (int m = 0; m < 4; ++m) _Pragma("unroll") for (int n = 0; n < 2; ++n) _Pragma("unroll") for (int k = 0; k < 2; ++k) \
;         acc[ai][bj][m][n] = __builtin_amdgcn_mfma_f32_16x16x32_bf16(Bt[n][k], At[m][k], acc[ai][bj][m][n], 0, 0, 0); __builtin_amdgcn_s_setprio(0); } while (0)
; #define PG8_WAIT_V(n) asm volatile("s_waitcnt vmcnt(" #n ")" ::: "memory")
; #define PG8_WAIT_L(n) asm volatile("s_waitcnt lgkmcnt(" #n ")" ::: "memory")
; #define PG8_BAR __builtin_amdgcn_s_barrier()
; #define PG8_SCHED __builtin_amdgcn_sched_barrier(0)
; template <class Desc, class Epi, bool ALIGN_EPI>
; __device__ __forceinline__ void gemm_phase(LAS unsigned char* lds, const Desc& D, const Epi& E, int G, int c) {
;     ...
;             PG8_LDA(At, 1, 1); PG8_STAGE(PG8_SB(1, 0), b3, voffB); PG8_STAGE(PG8_SB(1, 1), b3 + hstepB, voffB); PG8_STAGE(PG8_SA(1, 0), a3, voffA);
;             PG8_WAIT_V(8); PG8_WAIT_L(0); PG8_BAR; PG8_MMA(1, 0, At, B0); PG8_MMA(1, 1, At, B1); PG8_BAR; PG8_SCHED;
;         }
	s_mov_b32 m0, s64
	v_lshl_add_u64 v[196:197], v[196:197], 0, s[76:77]
	s_add_u32 s20, s20, 0x2b0080
	ds_read_b128 v[164:167], v247 offset:49152
	ds_read_b128 v[168:171], v247 offset:50176
	ds_read_b128 v[172:175], v247 offset:51200
	ds_read_b128 v[176:179], v247 offset:52224
	ds_read_b128 v[180:183], v247 offset:53248
	ds_read_b128 v[184:187], v247 offset:54272
	ds_read_b128 v[188:191], v247 offset:55296
	ds_read_b128 v[192:195], v247 offset:56320
	global_load_lds_dwordx4 v[196:197], off
	v_lshl_add_u64 v[196:197], v[198:199], 0, s[76:77]
	s_mov_b32 m0, s65
	s_addc_u32 s21, s21, 0
	global_load_lds_dwordx4 v[196:197], off
	v_lshl_add_u64 v[196:197], s[20:21], 0, v[202:203]
	s_mov_b32 m0, s69
	s_nop 0
	global_load_lds_dwordx4 v[196:197], off
	v_lshl_add_u64 v[196:197], s[20:21], 0, v[206:207]
	s_mov_b32 m0, s70
	s_nop 0
	global_load_lds_dwordx4 v[196:197], off
	v_lshl_add_u64 v[196:197], v[208:209], 0, s[76:77]
	s_mov_b32 m0, s66
	s_nop 0
	global_load_lds_dwordx4 v[196:197], off
	v_lshl_add_u64 v[196:197], v[210:211], 0, s[76:77]
	s_mov_b32 m0, s67
	s_nop 0
	global_load_lds_dwordx4 v[196:197], off
	s_waitcnt vmcnt(8)
	s_waitcnt lgkmcnt(0)
	s_barrier
	v_mfma_f32_16x16x32_bf16 v[84:87], v[132:135], v[164:167], v[84:87]
	v_mfma_f32_16x16x32_bf16 v[84:87], v[136:139], v[168:171], v[84:87]
	v_mfma_f32_16x16x32_bf16 v[76:79], v[140:143], v[164:167], v[76:79]
	v_mfma_f32_16x16x32_bf16 v[76:79], v[144:147], v[168:171], v[76:79]
	v_mfma_f32_16x16x32_bf16 v[72:75], v[132:135], v[172:175], v[72:75]
	v_mfma_f32_16x16x32_bf16 v[72:75], v[136:139], v[176:179], v[72:75]
	v_mfma_f32_16x16x32_bf16 v[68:71], v[140:143], v[172:175], v[68:71]
	v_mfma_f32_16x16x32_bf16 v[68:71], v[144:147], v[176:179], v[68:71]
	v_mfma_f32_16x16x32_bf16 v[60:63], v[132:135], v[180:183], v[60:63]
	v_mfma_f32_16x16x32_bf16 v[60:63], v[136:139], v[184:187], v[60:63]
	v_mfma_f32_16x16x32_bf16 v[56:59], v[140:143], v[180:183], v[56:59]
	v_mfma_f32_16x16x32_bf16 v[56:59], v[144:147], v[184:187], v[56:59]
	v_mfma_f32_16x16x32_bf16 v[48:51], v[132:135], v[188:191], v[48:51]
	v_mfma_f32_16x16x32_bf16 v[48:51], v[136:139], v[192:195], v[48:51]
	v_mfma_f32_16x16x32_bf16 v[44:47], v[140:143], v[188:191], v[44:47]
	v_mfma_f32_16x16x32_bf16 v[44:47], v[144:147], v[192:195], v[44:47]
	v_mfma_f32_16x16x32_bf16 v[40:43], v[148:151], v[164:167], v[40:43]
	v_mfma_f32_16x16x32_bf16 v[40:43], v[152:155], v[168:171], v[40:43]
	v_mfma_f32_16x16x32_bf16 v[36:39], v[156:159], v[164:167], v[36:39]
	v_mfma_f32_16x16x32_bf16 v[36:39], v[160:163], v[168:171], v[36:39]
	v_mfma_f32_16x16x32_bf16 v[28:31], v[148:151], v[172:175], v[28:31]
	v_mfma_f32_16x16x32_bf16 v[28:31], v[152:155], v[176:179], v[28:31]
	v_mfma_f32_16x16x32_bf16 v[24:27], v[156:159], v[172:175], v[24:27]
	v_mfma_f32_16x16x32_bf16 v[24:27], v[160:163], v[176:179], v[24:27]
	v_mfma_f32_16x16x32_bf16 v[16:19], v[148:151], v[180:183], v[16:19]
	v_mfma_f32_16x16x32_bf16 v[16:19], v[152:155], v[184:187], v[16:19]
	v_mfma_f32_16x16x32_bf16 v[12:15], v[156:159], v[180:183], v[12:15]
	v_mfma_f32_16x16x32_bf16 v[12:15], v[160:163], v[184:187], v[12:15]
	v_mfma_f32_16x16x32_bf16 v[8:11], v[148:151], v[188:191], v[8:11]
	v_mfma_f32_16x16x32_bf16 v[8:11], v[152:155], v[192:195], v[8:11]
	v_mfma_f32_16x16x32_bf16 v[4:7], v[156:159], v[188:191], v[4:7]
	v_mfma_f32_16x16x32_bf16 v[4:7], v[160:163], v[192:195], v[4:7]
	s_barrier
	s_cmp_ge_u32 s14, s24
	s_mov_b32 s39, s14
	s_cbranch_scc1 .LBB0_1776
